# baseline (speedup 1.0000x reference)
; #define STA(b, h, half, kt) STAGE(((b) * 2 + (h)) * G_HT * 2, pA, ((size_t)(half) * G_HALF * lda + (size_t)(kt) * G_BK) * 2, lda)
; #define STB(b, h, half, kt) STAGE((4 + (b) * 2 + (h)) * G_HT * 2, pB, ((size_t)(half) * G_HALF * K + (size_t)(kt) * G_BK) * 2, K)
; #define LDA(dst, b, h) for (int m = 0; m < 4; ++m) for (int k = 0; k < 2; ++k) \
;     dst[m][k] = *reinterpret_cast<const bf16x8*>(aRd + (((b) * 2 + (h)) * G_HT * 2 + m * 2048 + k * 1024))
; #define LDB(dst, b, h) for (int n = 0; n < 2; ++n) for (int k = 0; k < 2; ++k) \
;     dst[n][k] = *reinterpret_cast<const bf16x8*>(bRd + (((b) * 2 + (h)) * G_HT * 2 + n * 2048 + k * 1024))
; #define MMA(ai, bj, At, Bx) do { __builtin_amdgcn_s_setprio(1); \
;     for (int m = 0; m < 4; ++m) for (int n = 0; n < 2; ++n) for (int k = 0; k < 2; ++k) \
;       acc[ai][bj][m][n] = __builtin_amdgcn_mfma_f32_16x16x32_bf16(Bx[n][k], At[m][k], acc[ai][bj][m][n], 0, 0, 0);     \
;     __builtin_amdgcn_s_setprio(0); } while (0)
; #define WAIT_V(n) asm volatile("s_waitcnt vmcnt(" #n ")" ::: "memory")
; #define WAIT_L(n) asm volatile("s_waitcnt lgkmcnt(" #n ")" ::: "memory")
; #define BAR __builtin_amdgcn_s_barrier()
; #define SCHED __builtin_amdgcn_sched_barrier(0)
; template <int EPI>
; __device__ __forceinline__ void gemm_tile(const bf16* __restrict__ A, int lda, const bf16* __restrict__ Bt, int K,
;                                           int brow, int bcol, const EpiArgs& ea, char* shmc, bool has_next, int nbrow, int nbcol, bool first_tile) {
;     ...
;   for (int t = 0; t < nt - 2; t += 2) {
;     LDB(B0, 0, 0); SCHED; LDA(At, 0, 0); STA(1, 1, 1, t + 1);
;     WAIT_L(8); BAR; WAIT_L(0); MMA(0, 0, At, B0); BAR; SCHED;
;     LDB(B1, 0, 1); STB(0, 0, 0, t + 2);
;     BAR; WAIT_L(0); MMA(0, 1, At, B1); BAR;
;     LDA(At, 0, 1); STA(0, 0, 0, t + 2);
;     BAR; WAIT_L(0); MMA(1, 0, At, B0); BAR; SCHED;
;     STB(0, 1, 1, t + 2);
;     WAIT_V(6); BAR; MMA(1, 1, At, B1); BAR;
.LBB0_96:
	ds_read_b128 v[162:165], v141
	ds_read_b128 v[166:169], v142
	ds_read_b128 v[170:173], v143
	ds_read_b128 v[174:177], v144
	s_add_u32 s82, s34, 0xffffff00
	s_addc_u32 s83, s35, -1
	s_mov_b32 m0, s77
	ds_read_b128 v[178:181], v160
	ds_read_b128 v[182:185], v160 offset:1024
	ds_read_b128 v[186:189], v160 offset:2048
	ds_read_b128 v[190:193], v160 offset:3072
	ds_read_b128 v[194:197], v160 offset:4096
	ds_read_b128 v[198:201], v160 offset:5120
	ds_read_b128 v[202:205], v160 offset:6144
	ds_read_b128 v[206:209], v160 offset:7168
	v_lshl_add_u64 v[210:211], v[134:135], 0, s[82:83]
	global_load_lds_dwordx4 v[210:211], off
	s_mov_b32 m0, s68
	v_lshl_add_u64 v[210:211], v[210:211], 0, s[0:1]
	global_load_lds_dwordx4 v[210:211], off
	s_waitcnt lgkmcnt(8)
	s_barrier
	s_waitcnt lgkmcnt(0)
	s_setprio 1
	v_mfma_f32_16x16x32_bf16 v[124:127], v[162:165], v[178:181], v[124:127]
	v_mfma_f32_16x16x32_bf16 v[120:123], v[170:173], v[178:181], v[120:123]
	v_mfma_f32_16x16x32_bf16 v[116:119], v[162:165], v[186:189], v[116:119]
	v_mfma_f32_16x16x32_bf16 v[112:115], v[170:173], v[186:189], v[112:115]
	v_mfma_f32_16x16x32_bf16 v[108:111], v[162:165], v[194:197], v[108:111]
	v_mfma_f32_16x16x32_bf16 v[104:107], v[170:173], v[194:197], v[104:107]
	v_mfma_f32_16x16x32_bf16 v[100:103], v[162:165], v[202:205], v[100:103]
	v_mfma_f32_16x16x32_bf16 v[96:99], v[170:173], v[202:205], v[96:99]
	v_mfma_f32_16x16x32_bf16 v[124:127], v[166:169], v[182:185], v[124:127]
	v_mfma_f32_16x16x32_bf16 v[120:123], v[174:177], v[182:185], v[120:123]
	v_mfma_f32_16x16x32_bf16 v[116:119], v[166:169], v[190:193], v[116:119]
	v_mfma_f32_16x16x32_bf16 v[112:115], v[174:177], v[190:193], v[112:115]
	v_mfma_f32_16x16x32_bf16 v[108:111], v[166:169], v[198:201], v[108:111]
	v_mfma_f32_16x16x32_bf16 v[104:107], v[174:177], v[198:201], v[104:107]
	v_mfma_f32_16x16x32_bf16 v[100:103], v[166:169], v[206:209], v[100:103]
	v_mfma_f32_16x16x32_bf16 v[96:99], v[174:177], v[206:209], v[96:99]
	s_setprio 0
	s_barrier
	s_add_u32 s82, s34, 0xffefff80
	s_addc_u32 s83, s35, -1
	s_mov_b32 m0, s71
	ds_read_b128 v[210:213], v145
	ds_read_b128 v[214:217], v146
	ds_read_b128 v[218:221], v147
	ds_read_b128 v[222:225], v148
	v_lshl_add_u64 v[226:227], v[136:137], 0, s[82:83]
	global_load_lds_dwordx4 v[226:227], off
	s_mov_b32 m0, s72
	v_lshl_add_u64 v[226:227], v[226:227], 0, s[0:1]
	global_load_lds_dwordx4 v[226:227], off
	s_barrier
	s_waitcnt lgkmcnt(0)
	s_setprio 1
	v_mfma_f32_16x16x32_bf16 v[92:95], v[210:213], v[178:181], v[92:95]
	v_mfma_f32_16x16x32_bf16 v[88:91], v[218:221], v[178:181], v[88:91]
	v_mfma_f32_16x16x32_bf16 v[84:87], v[210:213], v[186:189], v[84:87]
	v_mfma_f32_16x16x32_bf16 v[80:83], v[218:221], v[186:189], v[80:83]
	v_mfma_f32_16x16x32_bf16 v[76:79], v[210:213], v[194:197], v[76:79]
	v_mfma_f32_16x16x32_bf16 v[72:75], v[218:221], v[194:197], v[72:75]
	v_mfma_f32_16x16x32_bf16 v[68:71], v[210:213], v[202:205], v[68:71]
	v_mfma_f32_16x16x32_bf16 v[64:67], v[218:221], v[202:205], v[64:67]
	v_mfma_f32_16x16x32_bf16 v[92:95], v[214:217], v[182:185], v[92:95]
	v_mfma_f32_16x16x32_bf16 v[88:91], v[222:225], v[182:185], v[88:91]
	v_mfma_f32_16x16x32_bf16 v[84:87], v[214:217], v[190:193], v[84:87]
	v_mfma_f32_16x16x32_bf16 v[80:83], v[222:225], v[190:193], v[80:83]
	v_mfma_f32_16x16x32_bf16 v[76:79], v[214:217], v[198:201], v[76:79]
	v_mfma_f32_16x16x32_bf16 v[72:75], v[222:225], v[198:201], v[72:75]
	v_mfma_f32_16x16x32_bf16 v[68:71], v[214:217], v[206:209], v[68:71]
	v_mfma_f32_16x16x32_bf16 v[64:67], v[222:225], v[206:209], v[64:67]
	s_setprio 0
	s_mov_b32 m0, s7
	s_barrier
	ds_read_b128 v[178:181], v160 offset:16384
	ds_read_b128 v[182:185], v160 offset:17408
	ds_read_b128 v[186:189], v160 offset:18432
	ds_read_b128 v[190:193], v160 offset:19456
	ds_read_b128 v[194:197], v160 offset:20480
	ds_read_b128 v[198:201], v160 offset:21504
	ds_read_b128 v[202:205], v160 offset:22528
	ds_read_b128 v[206:209], v160 offset:23552
	v_lshl_add_u64 v[226:227], v[134:135], 0, s[82:83]
	global_load_lds_dwordx4 v[226:227], off
	s_mov_b32 m0, s79
	v_lshl_add_u64 v[226:227], v[226:227], 0, s[0:1]
	global_load_lds_dwordx4 v[226:227], off
	s_barrier
	s_waitcnt lgkmcnt(0)
	s_setprio 1
	v_mfma_f32_16x16x32_bf16 v[60:63], v[162:165], v[178:181], v[60:63]
	v_mfma_f32_16x16x32_bf16 v[56:59], v[170:173], v[178:181], v[56:59]
	v_mfma_f32_16x16x32_bf16 v[52:55], v[162:165], v[186:189], v[52:55]
	v_mfma_f32_16x16x32_bf16 v[48:51], v[170:173], v[186:189], v[48:51]
	v_mfma_f32_16x16x32_bf16 v[44:47], v[162:165], v[194:197], v[44:47]
	v_mfma_f32_16x16x32_bf16 v[40:43], v[170:173], v[194:197], v[40:43]
	v_mfma_f32_16x16x32_bf16 v[36:39], v[162:165], v[202:205], v[36:39]
	v_mfma_f32_16x16x32_bf16 v[32:35], v[170:173], v[202:205], v[32:35]
	v_mfma_f32_16x16x32_bf16 v[60:63], v[166:169], v[182:185], v[60:63]
	v_mfma_f32_16x16x32_bf16 v[56:59], v[174:177], v[182:185], v[56:59]
	v_mfma_f32_16x16x32_bf16 v[52:55], v[166:169], v[190:193], v[52:55]
	v_mfma_f32_16x16x32_bf16 v[48:51], v[174:177], v[190:193], v[48:51]
	v_mfma_f32_16x16x32_bf16 v[44:47], v[166:169], v[198:201], v[44:47]
	v_mfma_f32_16x16x32_bf16 v[40:43], v[174:177], v[198:201], v[40:43]
	v_mfma_f32_16x16x32_bf16 v[36:39], v[166:169], v[206:209], v[36:39]
	v_mfma_f32_16x16x32_bf16 v[32:35], v[174:177], v[206:209], v[32:35]
	s_setprio 0
	s_barrier
	s_add_u32 s82, s34, 0xffffff80
	s_addc_u32 s83, s35, -1
	s_mov_b32 m0, s73
	v_lshl_add_u64 v[162:163], v[136:137], 0, s[82:83]
	global_load_lds_dwordx4 v[162:163], off
	s_mov_b32 m0, s74
	v_lshl_add_u64 v[162:163], v[162:163], 0, s[0:1]
	global_load_lds_dwordx4 v[162:163], off
	s_waitcnt vmcnt(6)
	s_barrier
; #define STA(b, h, half, kt) STAGE(((b) * 2 + (h)) * G_HT * 2, pA, ((size_t)(half) * G_HALF * lda + (size_t)(kt) * G_BK) * 2, lda)
; #define STB(b, h, half, kt) STAGE((4 + (b) * 2 + (h)) * G_HT * 2, pB, ((size_t)(half) * G_HALF * K + (size_t)(kt) * G_BK) * 2, K)
; #define LDA(dst, b, h) for (int m = 0; m < 4; ++m) for (int k = 0; k < 2; ++k) \
;     dst[m][k] = *reinterpret_cast<const bf16x8*>(aRd + (((b) * 2 + (h)) * G_HT * 2 + m * 2048 + k * 1024))
; #define LDB(dst, b, h) for (int n = 0; n < 2; ++n) for (int k = 0; k < 2; ++k) \
;     dst[n][k] = *reinterpret_cast<const bf16x8*>(bRd + (((b) * 2 + (h)) * G_HT * 2 + n * 2048 + k * 1024))
; #define MMA(ai, bj, At, Bx) do { __builtin_amdgcn_s_setprio(1); \
;     for (int m = 0; m < 4; ++m) for (int n = 0; n < 2; ++n) for (int k = 0; k < 2; ++k) \
;       acc[ai][bj][m][n] = __builtin_amdgcn_mfma_f32_16x16x32_bf16(Bx[n][k], At[m][k], acc[ai][bj][m][n], 0, 0, 0);     \
;     __builtin_amdgcn_s_setprio(0); } while (0)
; #define WAIT_V(n) asm volatile("s_waitcnt vmcnt(" #n ")" ::: "memory")
; #define WAIT_L(n) asm volatile("s_waitcnt lgkmcnt(" #n ")" ::: "memory")
; #define BAR __builtin_amdgcn_s_barrier()
; #define SCHED __builtin_amdgcn_sched_barrier(0)
; template <int EPI>
; __device__ __forceinline__ void gemm_tile(const bf16* __restrict__ A, int lda, const bf16* __restrict__ Bt, int K,
;                                           int brow, int bcol, const EpiArgs& ea, char* shmc, bool has_next, int nbrow, int nbcol, bool first_tile) {
;     ...
;     WAIT_V(6); BAR; MMA(1, 1, At, B1); BAR;
;     LDB(B0, 1, 0); SCHED; LDA(At, 1, 0); STA(0, 1, 1, t + 2);
;     WAIT_L(8); BAR; WAIT_L(0); MMA(0, 0, At, B0); BAR; SCHED;
;     LDB(B1, 1, 1); STB(1, 0, 0, t + 3);
;     BAR; WAIT_L(0); MMA(0, 1, At, B1); BAR;
;     LDA(At, 1, 1); STA(1, 0, 0, t + 3);
;     BAR; WAIT_L(0); MMA(1, 0, At, B0); BAR; SCHED;
	s_setprio 1
	v_mfma_f32_16x16x32_bf16 v[28:31], v[210:213], v[178:181], v[28:31]
	v_mfma_f32_16x16x32_bf16 v[24:27], v[218:221], v[178:181], v[24:27]
	v_mfma_f32_16x16x32_bf16 v[20:23], v[210:213], v[186:189], v[20:23]
	v_mfma_f32_16x16x32_bf16 v[16:19], v[218:221], v[186:189], v[16:19]
	v_mfma_f32_16x16x32_bf16 v[12:15], v[210:213], v[194:197], v[12:15]
	v_mfma_f32_16x16x32_bf16 v[8:11], v[218:221], v[194:197], v[8:11]
	v_mfma_f32_16x16x32_bf16 v[4:7], v[210:213], v[202:205], v[4:7]
	v_mfma_f32_16x16x32_bf16 v[0:3], v[218:221], v[202:205], v[0:3]
	v_mfma_f32_16x16x32_bf16 v[28:31], v[214:217], v[182:185], v[28:31]
	v_mfma_f32_16x16x32_bf16 v[24:27], v[222:225], v[182:185], v[24:27]
	v_mfma_f32_16x16x32_bf16 v[20:23], v[214:217], v[190:193], v[20:23]
	v_mfma_f32_16x16x32_bf16 v[16:19], v[222:225], v[190:193], v[16:19]
	v_mfma_f32_16x16x32_bf16 v[12:15], v[214:217], v[198:201], v[12:15]
	v_mfma_f32_16x16x32_bf16 v[8:11], v[222:225], v[198:201], v[8:11]
	v_mfma_f32_16x16x32_bf16 v[4:7], v[214:217], v[206:209], v[4:7]
	v_mfma_f32_16x16x32_bf16 v[0:3], v[222:225], v[206:209], v[0:3]
	s_setprio 0
	s_barrier
	ds_read_b128 v[162:165], v149
	ds_read_b128 v[166:169], v150
	ds_read_b128 v[170:173], v151
	ds_read_b128 v[174:177], v152
	s_mov_b32 m0, s80
	ds_read_b128 v[178:181], v160 offset:32768
	ds_read_b128 v[182:185], v160 offset:33792
	ds_read_b128 v[186:189], v160 offset:34816
	ds_read_b128 v[190:193], v160 offset:35840
	ds_read_b128 v[194:197], v160 offset:36864
	ds_read_b128 v[198:201], v160 offset:37888
	ds_read_b128 v[202:205], v160 offset:38912
	ds_read_b128 v[206:209], v160 offset:39936
	v_lshl_add_u64 v[210:211], v[134:135], 0, s[82:83]
	global_load_lds_dwordx4 v[210:211], off
	s_mov_b32 m0, s81
	v_lshl_add_u64 v[210:211], v[210:211], 0, s[0:1]
	global_load_lds_dwordx4 v[210:211], off
	s_waitcnt lgkmcnt(8)
	s_barrier
	s_waitcnt lgkmcnt(0)
	s_setprio 1
	v_mfma_f32_16x16x32_bf16 v[124:127], v[162:165], v[178:181], v[124:127]
	v_mfma_f32_16x16x32_bf16 v[120:123], v[170:173], v[178:181], v[120:123]
	v_mfma_f32_16x16x32_bf16 v[116:119], v[162:165], v[186:189], v[116:119]
	v_mfma_f32_16x16x32_bf16 v[112:115], v[170:173], v[186:189], v[112:115]
	v_mfma_f32_16x16x32_bf16 v[108:111], v[162:165], v[194:197], v[108:111]
	v_mfma_f32_16x16x32_bf16 v[104:107], v[170:173], v[194:197], v[104:107]
	v_mfma_f32_16x16x32_bf16 v[100:103], v[162:165], v[202:205], v[100:103]
	v_mfma_f32_16x16x32_bf16 v[96:99], v[170:173], v[202:205], v[96:99]
	v_mfma_f32_16x16x32_bf16 v[124:127], v[166:169], v[182:185], v[124:127]
	v_mfma_f32_16x16x32_bf16 v[120:123], v[174:177], v[182:185], v[120:123]
	v_mfma_f32_16x16x32_bf16 v[116:119], v[166:169], v[190:193], v[116:119]
	v_mfma_f32_16x16x32_bf16 v[112:115], v[174:177], v[190:193], v[112:115]
	v_mfma_f32_16x16x32_bf16 v[108:111], v[166:169], v[198:201], v[108:111]
	v_mfma_f32_16x16x32_bf16 v[104:107], v[174:177], v[198:201], v[104:107]
	v_mfma_f32_16x16x32_bf16 v[100:103], v[166:169], v[206:209], v[100:103]
	v_mfma_f32_16x16x32_bf16 v[96:99], v[174:177], v[206:209], v[96:99]
	s_setprio 0
	s_barrier
	s_add_u32 s82, s34, 0xfff00000
	s_addc_u32 s83, s35, -1
	s_mov_b32 m0, s11
	ds_read_b128 v[210:213], v153
	ds_read_b128 v[214:217], v154
	ds_read_b128 v[218:221], v155
	ds_read_b128 v[222:225], v156
	v_lshl_add_u64 v[226:227], v[136:137], 0, s[82:83]
	global_load_lds_dwordx4 v[226:227], off
	s_mov_b32 m0, s63
	v_lshl_add_u64 v[226:227], v[226:227], 0, s[0:1]
	global_load_lds_dwordx4 v[226:227], off
	s_barrier
	s_waitcnt lgkmcnt(0)
	s_setprio 1
	v_mfma_f32_16x16x32_bf16 v[92:95], v[210:213], v[178:181], v[92:95]
	v_mfma_f32_16x16x32_bf16 v[88:91], v[218:221], v[178:181], v[88:91]
	v_mfma_f32_16x16x32_bf16 v[84:87], v[210:213], v[186:189], v[84:87]
	v_mfma_f32_16x16x32_bf16 v[80:83], v[218:221], v[186:189], v[80:83]
	v_mfma_f32_16x16x32_bf16 v[76:79], v[210:213], v[194:197], v[76:79]
	v_mfma_f32_16x16x32_bf16 v[72:75], v[218:221], v[194:197], v[72:75]
	v_mfma_f32_16x16x32_bf16 v[68:71], v[210:213], v[202:205], v[68:71]
	v_mfma_f32_16x16x32_bf16 v[64:67], v[218:221], v[202:205], v[64:67]
	v_mfma_f32_16x16x32_bf16 v[92:95], v[214:217], v[182:185], v[92:95]
	v_mfma_f32_16x16x32_bf16 v[88:91], v[222:225], v[182:185], v[88:91]
	v_mfma_f32_16x16x32_bf16 v[84:87], v[214:217], v[190:193], v[84:87]
	v_mfma_f32_16x16x32_bf16 v[80:83], v[222:225], v[190:193], v[80:83]
	v_mfma_f32_16x16x32_bf16 v[76:79], v[214:217], v[198:201], v[76:79]
	v_mfma_f32_16x16x32_bf16 v[72:75], v[222:225], v[198:201], v[72:75]
	v_mfma_f32_16x16x32_bf16 v[68:71], v[214:217], v[206:209], v[68:71]
	v_mfma_f32_16x16x32_bf16 v[64:67], v[222:225], v[206:209], v[64:67]
	s_setprio 0
	s_mov_b32 m0, s66
	s_barrier
	ds_read_b128 v[178:181], v160 offset:49152
	ds_read_b128 v[182:185], v160 offset:50176
	ds_read_b128 v[186:189], v160 offset:51200
	ds_read_b128 v[190:193], v160 offset:52224
	ds_read_b128 v[194:197], v160 offset:53248
	ds_read_b128 v[198:201], v160 offset:54272
	ds_read_b128 v[202:205], v160 offset:55296
	ds_read_b128 v[206:209], v160 offset:56320
	v_lshl_add_u64 v[226:227], v[134:135], 0, s[82:83]
	global_load_lds_dwordx4 v[226:227], off
	s_mov_b32 m0, s67
	v_lshl_add_u64 v[226:227], v[226:227], 0, s[0:1]
	global_load_lds_dwordx4 v[226:227], off
	s_barrier
; #define STA(b, h, half, kt) STAGE(((b) * 2 + (h)) * G_HT * 2, pA, ((size_t)(half) * G_HALF * lda + (size_t)(kt) * G_BK) * 2, lda)
; #define STB(b, h, half, kt) STAGE((4 + (b) * 2 + (h)) * G_HT * 2, pB, ((size_t)(half) * G_HALF * K + (size_t)(kt) * G_BK) * 2, K)
; #define LDA(dst, b, h) for (int m = 0; m < 4; ++m) for (int k = 0; k < 2; ++k) \
;     dst[m][k] = *reinterpret_cast<const bf16x8*>(aRd + (((b) * 2 + (h)) * G_HT * 2 + m * 2048 + k * 1024))
; #define LDB(dst, b, h) for (int n = 0; n < 2; ++n) for (int k = 0; k < 2; ++k) \
;     dst[n][k] = *reinterpret_cast<const bf16x8*>(bRd + (((b) * 2 + (h)) * G_HT * 2 + n * 2048 + k * 1024))
; #define MMA(ai, bj, At, Bx) do { __builtin_amdgcn_s_setprio(1); \
;     for (int m = 0; m < 4; ++m) for (int n = 0; n < 2; ++n) for (int k = 0; k < 2; ++k) \
;       acc[ai][bj][m][n] = __builtin_amdgcn_mfma_f32_16x16x32_bf16(Bx[n][k], At[m][k], acc[ai][bj][m][n], 0, 0, 0);     \
;     __builtin_amdgcn_s_setprio(0); } while (0)
; #define WAIT_V(n) asm volatile("s_waitcnt vmcnt(" #n ")" ::: "memory")
; #define WAIT_L(n) asm volatile("s_waitcnt lgkmcnt(" #n ")" ::: "memory")
; #define BAR __builtin_amdgcn_s_barrier()
; #define SCHED __builtin_amdgcn_sched_barrier(0)
; template <int EPI>
; __device__ __forceinline__ void gemm_tile(const bf16* __restrict__ A, int lda, const bf16* __restrict__ Bt, int K,
;                                           int brow, int bcol, const EpiArgs& ea, char* shmc, bool has_next, int nbrow, int nbcol, bool first_tile) {
;     ...
;     BAR; WAIT_L(0); MMA(1, 0, At, B0); BAR; SCHED;
;     STB(1, 1, 1, t + 3);
;     WAIT_V(6); BAR; MMA(1, 1, At, B1); BAR;
;   }
;   { LDB(B0, 0, 0); LDA(At, 0, 0); STA(1, 1, 1, nt - 1);
;     BAR; WAIT_L(0); MMA(0, 0, At, B0); BAR;
;     LDB(B1, 0, 1); BAR; WAIT_L(0); MMA(0, 1, At, B1); BAR;
;     LDA(At, 0, 1); WAIT_V(4); BAR; WAIT_L(0); MMA(1, 0, At, B0); MMA(1, 1, At, B1); BAR; }
	s_waitcnt lgkmcnt(0)
	s_setprio 1
	v_mfma_f32_16x16x32_bf16 v[60:63], v[162:165], v[178:181], v[60:63]
	v_mfma_f32_16x16x32_bf16 v[56:59], v[170:173], v[178:181], v[56:59]
	v_mfma_f32_16x16x32_bf16 v[52:55], v[162:165], v[186:189], v[52:55]
	v_mfma_f32_16x16x32_bf16 v[48:51], v[170:173], v[186:189], v[48:51]
	v_mfma_f32_16x16x32_bf16 v[44:47], v[162:165], v[194:197], v[44:47]
	v_mfma_f32_16x16x32_bf16 v[40:43], v[170:173], v[194:197], v[40:43]
	v_mfma_f32_16x16x32_bf16 v[36:39], v[162:165], v[202:205], v[36:39]
	v_mfma_f32_16x16x32_bf16 v[32:35], v[170:173], v[202:205], v[32:35]
	v_mfma_f32_16x16x32_bf16 v[60:63], v[166:169], v[182:185], v[60:63]
	v_mfma_f32_16x16x32_bf16 v[56:59], v[174:177], v[182:185], v[56:59]
	v_mfma_f32_16x16x32_bf16 v[52:55], v[166:169], v[190:193], v[52:55]
	v_mfma_f32_16x16x32_bf16 v[48:51], v[174:177], v[190:193], v[48:51]
	v_mfma_f32_16x16x32_bf16 v[44:47], v[166:169], v[198:201], v[44:47]
	v_mfma_f32_16x16x32_bf16 v[40:43], v[174:177], v[198:201], v[40:43]
	v_mfma_f32_16x16x32_bf16 v[36:39], v[166:169], v[206:209], v[36:39]
	v_mfma_f32_16x16x32_bf16 v[32:35], v[174:177], v[206:209], v[32:35]
	s_setprio 0
	s_barrier
	s_mov_b32 m0, s69
	v_lshl_add_u64 v[162:163], v[136:137], 0, s[34:35]
	global_load_lds_dwordx4 v[162:163], off
	s_mov_b32 m0, s70
	v_lshl_add_u64 v[162:163], v[162:163], 0, s[0:1]
	global_load_lds_dwordx4 v[162:163], off
	s_waitcnt vmcnt(6)
	s_barrier
	s_setprio 1
	v_mfma_f32_16x16x32_bf16 v[28:31], v[210:213], v[178:181], v[28:31]
	v_mfma_f32_16x16x32_bf16 v[24:27], v[218:221], v[178:181], v[24:27]
	v_mfma_f32_16x16x32_bf16 v[20:23], v[210:213], v[186:189], v[20:23]
	v_mfma_f32_16x16x32_bf16 v[16:19], v[218:221], v[186:189], v[16:19]
	v_mfma_f32_16x16x32_bf16 v[12:15], v[210:213], v[194:197], v[12:15]
	v_mfma_f32_16x16x32_bf16 v[8:11], v[218:221], v[194:197], v[8:11]
	v_mfma_f32_16x16x32_bf16 v[4:7], v[210:213], v[202:205], v[4:7]
	v_mfma_f32_16x16x32_bf16 v[0:3], v[218:221], v[202:205], v[0:3]
	v_mfma_f32_16x16x32_bf16 v[28:31], v[214:217], v[182:185], v[28:31]
	v_mfma_f32_16x16x32_bf16 v[24:27], v[222:225], v[182:185], v[24:27]
	v_mfma_f32_16x16x32_bf16 v[20:23], v[214:217], v[190:193], v[20:23]
	v_mfma_f32_16x16x32_bf16 v[16:19], v[222:225], v[190:193], v[16:19]
	v_mfma_f32_16x16x32_bf16 v[12:15], v[214:217], v[198:201], v[12:15]
	v_mfma_f32_16x16x32_bf16 v[8:11], v[222:225], v[198:201], v[8:11]
	v_mfma_f32_16x16x32_bf16 v[4:7], v[214:217], v[206:209], v[4:7]
	v_mfma_f32_16x16x32_bf16 v[0:3], v[222:225], v[206:209], v[0:3]
	s_setprio 0
	s_add_i32 s75, s75, 2
	s_add_u32 s34, s34, 0x100
	s_addc_u32 s35, s35, 0
	s_cmp_lt_u32 s75, 60
	s_barrier
	s_cbranch_scc1 .LBB0_96
	s_mov_b64 s[34:35], 0x101f80
	s_mov_b32 m0, s77
	ds_read_b128 v[162:165], v141
	ds_read_b128 v[166:169], v142
	ds_read_b128 v[170:173], v143
	ds_read_b128 v[174:177], v144
	ds_read_b128 v[178:181], v160
	ds_read_b128 v[182:185], v160 offset:1024
	ds_read_b128 v[186:189], v160 offset:2048
	ds_read_b128 v[190:193], v160 offset:3072
	ds_read_b128 v[194:197], v160 offset:4096
	ds_read_b128 v[198:201], v160 offset:5120
	ds_read_b128 v[202:205], v160 offset:6144
	ds_read_b128 v[206:209], v160 offset:7168
	s_nop 0
	v_lshl_add_u64 v[134:135], v[134:135], 0, s[34:35]
	global_load_lds_dwordx4 v[134:135], off
	v_lshl_add_u64 v[134:135], v[134:135], 0, s[0:1]
	s_mov_b32 m0, s68
	s_nop 0
	global_load_lds_dwordx4 v[134:135], off
	s_barrier
	s_waitcnt lgkmcnt(0)
	s_setprio 1
	s_waitcnt lgkmcnt(0)
	v_mfma_f32_16x16x32_bf16 v[124:127], v[162:165], v[178:181], v[124:127]
	v_mfma_f32_16x16x32_bf16 v[116:119], v[162:165], v[186:189], v[116:119]
	v_mfma_f32_16x16x32_bf16 v[112:115], v[170:173], v[186:189], v[112:115]
	v_mfma_f32_16x16x32_bf16 v[100:103], v[162:165], v[202:205], v[100:103]
	v_mfma_f32_16x16x32_bf16 v[96:99], v[170:173], v[202:205], v[96:99]
	v_mfma_f32_16x16x32_bf16 v[124:127], v[166:169], v[182:185], v[124:127]
	v_mfma_f32_16x16x32_bf16 v[120:123], v[170:173], v[178:181], v[120:123]
	v_mfma_f32_16x16x32_bf16 v[116:119], v[166:169], v[190:193], v[116:119]
	v_mfma_f32_16x16x32_bf16 v[112:115], v[174:177], v[190:193], v[112:115]
	v_mfma_f32_16x16x32_bf16 v[108:111], v[162:165], v[194:197], v[108:111]
	v_mfma_f32_16x16x32_bf16 v[104:107], v[170:173], v[194:197], v[104:107]
	v_mfma_f32_16x16x32_bf16 v[100:103], v[166:169], v[206:209], v[100:103]
	v_mfma_f32_16x16x32_bf16 v[96:99], v[174:177], v[206:209], v[96:99]
	v_mfma_f32_16x16x32_bf16 v[134:137], v[174:177], v[182:185], v[120:123]
	v_mfma_f32_16x16x32_bf16 v[210:213], v[166:169], v[198:201], v[108:111]
	v_mfma_f32_16x16x32_bf16 v[214:217], v[174:177], v[198:201], v[104:107]
	s_setprio 0
	s_barrier
	s_nop 0
	ds_read_b128 v[104:107], v145
	ds_read_b128 v[108:111], v146
	ds_read_b128 v[120:123], v147
	ds_read_b128 v[218:221], v148
	s_barrier
	s_waitcnt lgkmcnt(0)
	s_setprio 1
	s_waitcnt lgkmcnt(0)
	v_mfma_f32_16x16x32_bf16 v[84:87], v[104:107], v[186:189], v[84:87]
	v_mfma_f32_16x16x32_bf16 v[80:83], v[120:123], v[186:189], v[80:83]
	v_mfma_f32_16x16x32_bf16 v[68:71], v[104:107], v[202:205], v[68:71]
	v_mfma_f32_16x16x32_bf16 v[92:95], v[104:107], v[178:181], v[92:95]
	v_mfma_f32_16x16x32_bf16 v[88:91], v[120:123], v[178:181], v[88:91]
	v_mfma_f32_16x16x32_bf16 v[84:87], v[108:111], v[190:193], v[84:87]
	v_mfma_f32_16x16x32_bf16 v[80:83], v[218:221], v[190:193], v[80:83]
	v_mfma_f32_16x16x32_bf16 v[76:79], v[104:107], v[194:197], v[76:79]
	v_mfma_f32_16x16x32_bf16 v[72:75], v[120:123], v[194:197], v[72:75]
	v_mfma_f32_16x16x32_bf16 v[68:71], v[108:111], v[206:209], v[68:71]
	v_mfma_f32_16x16x32_bf16 v[64:67], v[120:123], v[202:205], v[64:67]
	v_mfma_f32_16x16x32_bf16 v[222:225], v[108:111], v[182:185], v[92:95]
	v_mfma_f32_16x16x32_bf16 v[178:181], v[218:221], v[182:185], v[88:91]
	v_mfma_f32_16x16x32_bf16 v[182:185], v[108:111], v[198:201], v[76:79]
	v_mfma_f32_16x16x32_bf16 v[186:189], v[218:221], v[198:201], v[72:75]
	v_mfma_f32_16x16x32_bf16 v[190:193], v[218:221], v[206:209], v[64:67]
	s_setprio 0
	s_barrier
; #define LDA(dst, b, h) for (int m = 0; m < 4; ++m) for (int k = 0; k < 2; ++k) \
;     dst[m][k] = *reinterpret_cast<const bf16x8*>(aRd + (((b) * 2 + (h)) * G_HT * 2 + m * 2048 + k * 1024))
; #define LDB(dst, b, h) for (int n = 0; n < 2; ++n) for (int k = 0; k < 2; ++k) \
;     dst[n][k] = *reinterpret_cast<const bf16x8*>(bRd + (((b) * 2 + (h)) * G_HT * 2 + n * 2048 + k * 1024))
; #define MMA(ai, bj, At, Bx) do { __builtin_amdgcn_s_setprio(1); \
;     for (int m = 0; m < 4; ++m) for (int n = 0; n < 2; ++n) for (int k = 0; k < 2; ++k) \
;       acc[ai][bj][m][n] = __builtin_amdgcn_mfma_f32_16x16x32_bf16(Bx[n][k], At[m][k], acc[ai][bj][m][n], 0, 0, 0);     \
;     __builtin_amdgcn_s_setprio(0); } while (0)
; #define WAIT_V(n) asm volatile("s_waitcnt vmcnt(" #n ")" ::: "memory")
; #define WAIT_L(n) asm volatile("s_waitcnt lgkmcnt(" #n ")" ::: "memory")
; #define BAR __builtin_amdgcn_s_barrier()
; template <int EPI>
; __device__ __forceinline__ void gemm_tile(const bf16* __restrict__ A, int lda, const bf16* __restrict__ Bt, int K,
;                                           int brow, int bcol, const EpiArgs& ea, char* shmc, bool has_next, int nbrow, int nbcol, bool first_tile) {
;     ...
;     LDA(At, 0, 1); WAIT_V(4); BAR; WAIT_L(0); MMA(1, 0, At, B0); MMA(1, 1, At, B1); BAR; }
;   { LDB(B0, 1, 0); LDA(At, 1, 0); WAIT_V(2); BAR; WAIT_L(0); MMA(0, 0, At, B0); BAR;
;     LDB(B1, 1, 1); WAIT_V(0); BAR; WAIT_L(0); MMA(0, 1, At, B1); BAR;
;     LDA(At, 1, 1); BAR; WAIT_L(0); MMA(1, 0, At, B0); MMA(1, 1, At, B1); BAR; }
	s_nop 0
	ds_read_b128 v[64:67], v160 offset:16384
	ds_read_b128 v[72:75], v160 offset:17408
	ds_read_b128 v[76:79], v160 offset:18432
	ds_read_b128 v[88:91], v160 offset:19456
	ds_read_b128 v[92:95], v160 offset:20480
	ds_read_b128 v[194:197], v160 offset:21504
	ds_read_b128 v[198:201], v160 offset:22528
	ds_read_b128 v[202:205], v160 offset:23552
	s_waitcnt vmcnt(4)
	s_barrier
	s_waitcnt lgkmcnt(0)
	s_setprio 1
	s_waitcnt lgkmcnt(0)
	v_mfma_f32_16x16x32_bf16 v[60:63], v[162:165], v[64:67], v[60:63]
	v_mfma_f32_16x16x32_bf16 v[52:55], v[162:165], v[76:79], v[52:55]
	v_mfma_f32_16x16x32_bf16 v[48:51], v[170:173], v[76:79], v[48:51]
	v_mfma_f32_16x16x32_bf16 v[36:39], v[162:165], v[198:201], v[36:39]
	v_mfma_f32_16x16x32_bf16 v[32:35], v[170:173], v[198:201], v[32:35]
	v_mfma_f32_16x16x32_bf16 v[60:63], v[166:169], v[72:75], v[60:63]
	v_mfma_f32_16x16x32_bf16 v[56:59], v[170:173], v[64:67], v[56:59]
	v_mfma_f32_16x16x32_bf16 v[52:55], v[166:169], v[88:91], v[52:55]
	v_mfma_f32_16x16x32_bf16 v[48:51], v[174:177], v[88:91], v[48:51]
	v_mfma_f32_16x16x32_bf16 v[44:47], v[162:165], v[92:95], v[44:47]
	v_mfma_f32_16x16x32_bf16 v[40:43], v[170:173], v[92:95], v[40:43]
	v_mfma_f32_16x16x32_bf16 v[36:39], v[166:169], v[202:205], v[36:39]
	v_mfma_f32_16x16x32_bf16 v[32:35], v[174:177], v[202:205], v[32:35]
	v_mfma_f32_16x16x32_bf16 v[206:209], v[174:177], v[72:75], v[56:59]
	v_mfma_f32_16x16x32_bf16 v[226:229], v[166:169], v[194:197], v[44:47]
	v_mfma_f32_16x16x32_bf16 v[230:233], v[174:177], v[194:197], v[40:43]
	s_setprio 0
	s_setprio 1
	v_mfma_f32_16x16x32_bf16 v[20:23], v[104:107], v[76:79], v[20:23]
	v_mfma_f32_16x16x32_bf16 v[16:19], v[120:123], v[76:79], v[16:19]
	v_mfma_f32_16x16x32_bf16 v[4:7], v[104:107], v[198:201], v[4:7]
	v_mfma_f32_16x16x32_bf16 v[28:31], v[104:107], v[64:67], v[28:31]
	v_mfma_f32_16x16x32_bf16 v[24:27], v[120:123], v[64:67], v[24:27]
	v_mfma_f32_16x16x32_bf16 v[20:23], v[108:111], v[88:91], v[20:23]
	v_mfma_f32_16x16x32_bf16 v[16:19], v[218:221], v[88:91], v[16:19]
	v_mfma_f32_16x16x32_bf16 v[12:15], v[104:107], v[92:95], v[12:15]
	v_mfma_f32_16x16x32_bf16 v[8:11], v[120:123], v[92:95], v[8:11]
	v_mfma_f32_16x16x32_bf16 v[4:7], v[108:111], v[202:205], v[4:7]
	v_mfma_f32_16x16x32_bf16 v[0:3], v[120:123], v[198:201], v[0:3]
	v_mfma_f32_16x16x32_bf16 v[162:165], v[108:111], v[72:75], v[28:31]
	v_mfma_f32_16x16x32_bf16 v[166:169], v[218:221], v[72:75], v[24:27]
	v_mfma_f32_16x16x32_bf16 v[170:173], v[108:111], v[194:197], v[12:15]
	v_mfma_f32_16x16x32_bf16 v[174:177], v[218:221], v[194:197], v[8:11]
	v_mfma_f32_16x16x32_bf16 v[194:197], v[218:221], v[202:205], v[0:3]
	s_setprio 0
	s_barrier
	s_nop 0
	ds_read_b128 v[0:3], v149
	ds_read_b128 v[8:11], v150
	ds_read_b128 v[12:15], v151
	ds_read_b128 v[198:201], v152
	ds_read_b128 v[24:27], v160 offset:32768
	ds_read_b128 v[28:31], v160 offset:33792
	ds_read_b128 v[40:43], v160 offset:34816
	ds_read_b128 v[44:47], v160 offset:35840
	ds_read_b128 v[56:59], v160 offset:36864
	ds_read_b128 v[64:67], v160 offset:37888
	ds_read_b128 v[202:205], v160 offset:38912
	ds_read_b128 v[218:221], v160 offset:39936
	s_waitcnt vmcnt(2)
	s_barrier
	s_waitcnt lgkmcnt(0)
	s_setprio 1
	s_waitcnt lgkmcnt(0)
	v_mfma_f32_16x16x32_bf16 v[72:75], v[0:3], v[24:27], v[124:127]
	v_mfma_f32_16x16x32_bf16 v[120:123], v[8:11], v[28:31], v[72:75]
	v_mfma_f32_16x16x32_bf16 v[72:75], v[12:15], v[24:27], v[134:137]
	v_mfma_f32_16x16x32_bf16 v[124:127], v[198:201], v[28:31], v[72:75]
	v_mfma_f32_16x16x32_bf16 v[72:75], v[0:3], v[40:43], v[116:119]
	v_mfma_f32_16x16x32_bf16 v[104:107], v[8:11], v[44:47], v[72:75]
	v_mfma_f32_16x16x32_bf16 v[72:75], v[12:15], v[40:43], v[112:115]
	v_mfma_f32_16x16x32_bf16 v[108:111], v[198:201], v[44:47], v[72:75]
	v_mfma_f32_16x16x32_bf16 v[72:75], v[0:3], v[56:59], v[210:213]
	v_mfma_f32_16x16x32_bf16 v[88:91], v[8:11], v[64:67], v[72:75]
	v_mfma_f32_16x16x32_bf16 v[72:75], v[12:15], v[56:59], v[214:217]
	v_mfma_f32_16x16x32_bf16 v[92:95], v[198:201], v[64:67], v[72:75]
	v_mfma_f32_16x16x32_bf16 v[72:75], v[0:3], v[202:205], v[100:103]
	v_mfma_f32_16x16x32_bf16 v[76:79], v[12:15], v[202:205], v[96:99]
	v_mfma_f32_16x16x32_bf16 v[72:75], v[8:11], v[218:221], v[72:75]
	v_mfma_f32_16x16x32_bf16 v[76:79], v[198:201], v[218:221], v[76:79]
	s_setprio 0
	s_barrier
; #define LDA(dst, b, h) for (int m = 0; m < 4; ++m) for (int k = 0; k < 2; ++k) \
;     dst[m][k] = *reinterpret_cast<const bf16x8*>(aRd + (((b) * 2 + (h)) * G_HT * 2 + m * 2048 + k * 1024))
; #define LDB(dst, b, h) for (int n = 0; n < 2; ++n) for (int k = 0; k < 2; ++k) \
;     dst[n][k] = *reinterpret_cast<const bf16x8*>(bRd + (((b) * 2 + (h)) * G_HT * 2 + n * 2048 + k * 1024))
; #define MMA(ai, bj, At, Bx) do { __builtin_amdgcn_s_setprio(1); \
;     for (int m = 0; m < 4; ++m) for (int n = 0; n < 2; ++n) for (int k = 0; k < 2; ++k) \
;       acc[ai][bj][m][n] = __builtin_amdgcn_mfma_f32_16x16x32_bf16(Bx[n][k], At[m][k], acc[ai][bj][m][n], 0, 0, 0);     \
;     __builtin_amdgcn_s_setprio(0); } while (0)
; #define WAIT_V(n) asm volatile("s_waitcnt vmcnt(" #n ")" ::: "memory")
; #define WAIT_L(n) asm volatile("s_waitcnt lgkmcnt(" #n ")" ::: "memory")
; #define BAR __builtin_amdgcn_s_barrier()
; template <int EPI>
; __device__ __forceinline__ void gemm_tile(const bf16* __restrict__ A, int lda, const bf16* __restrict__ Bt, int K,
;                                           int brow, int bcol, const EpiArgs& ea, char* shmc, bool has_next, int nbrow, int nbcol, bool first_tile) {
;     ...
;   { LDB(B0, 1, 0); LDA(At, 1, 0); WAIT_V(2); BAR; WAIT_L(0); MMA(0, 0, At, B0); BAR;
;     LDB(B1, 1, 1); WAIT_V(0); BAR; WAIT_L(0); MMA(0, 1, At, B1); BAR;
;     LDA(At, 1, 1); BAR; WAIT_L(0); MMA(1, 0, At, B0); MMA(1, 1, At, B1); BAR; }
;   if (wr == 0) BAR;
;   if (has_next) gemm_prefetch(A, lda, Bt, K, nbrow, nbcol, shmc);
	ds_read_b128 v[134:137], v153
	ds_read_b128 v[210:213], v154
	ds_read_b128 v[214:217], v155
	ds_read_b128 v[234:237], v156
	s_waitcnt vmcnt(0)
	s_barrier
	s_waitcnt lgkmcnt(0)
	s_setprio 1
	s_waitcnt lgkmcnt(0)
	v_mfma_f32_16x16x32_bf16 v[96:99], v[134:137], v[24:27], v[222:225]
	v_mfma_f32_16x16x32_bf16 v[24:27], v[214:217], v[24:27], v[178:181]
	v_mfma_f32_16x16x32_bf16 v[116:119], v[234:237], v[28:31], v[24:27]
	v_mfma_f32_16x16x32_bf16 v[24:27], v[134:137], v[40:43], v[84:87]
	v_mfma_f32_16x16x32_bf16 v[112:115], v[210:213], v[28:31], v[96:99]
	v_mfma_f32_16x16x32_bf16 v[96:99], v[210:213], v[44:47], v[24:27]
	v_mfma_f32_16x16x32_bf16 v[24:27], v[214:217], v[40:43], v[80:83]
	v_mfma_f32_16x16x32_bf16 v[100:103], v[234:237], v[44:47], v[24:27]
	v_mfma_f32_16x16x32_bf16 v[24:27], v[134:137], v[56:59], v[182:185]
	v_mfma_f32_16x16x32_bf16 v[80:83], v[210:213], v[64:67], v[24:27]
	v_mfma_f32_16x16x32_bf16 v[24:27], v[214:217], v[56:59], v[186:189]
	v_mfma_f32_16x16x32_bf16 v[84:87], v[234:237], v[64:67], v[24:27]
	v_mfma_f32_16x16x32_bf16 v[24:27], v[134:137], v[202:205], v[68:71]
	v_mfma_f32_16x16x32_bf16 v[64:67], v[210:213], v[218:221], v[24:27]
	v_mfma_f32_16x16x32_bf16 v[24:27], v[214:217], v[202:205], v[190:193]
	v_mfma_f32_16x16x32_bf16 v[68:71], v[234:237], v[218:221], v[24:27]
	s_setprio 0
	s_barrier
	ds_read_b128 v[178:181], v160 offset:49152
	ds_read_b128 v[182:185], v160 offset:50176
	ds_read_b128 v[186:189], v160 offset:51200
	ds_read_b128 v[190:193], v160 offset:52224
	ds_read_b128 v[202:205], v160 offset:53248
	ds_read_b128 v[218:221], v160 offset:54272
	ds_read_b128 v[222:225], v160 offset:55296
	ds_read_b128 v[238:241], v160 offset:56320
	s_barrier
	s_waitcnt lgkmcnt(0)
	s_setprio 1
	s_waitcnt lgkmcnt(0)
	v_mfma_f32_16x16x32_bf16 v[24:27], v[0:3], v[178:181], v[60:63]
	v_mfma_f32_16x16x32_bf16 v[56:59], v[8:11], v[182:185], v[24:27]
	v_mfma_f32_16x16x32_bf16 v[24:27], v[12:15], v[178:181], v[206:209]
	v_mfma_f32_16x16x32_bf16 v[60:63], v[198:201], v[182:185], v[24:27]
	v_mfma_f32_16x16x32_bf16 v[24:27], v[0:3], v[186:189], v[52:55]
	v_mfma_f32_16x16x32_bf16 v[40:43], v[8:11], v[190:193], v[24:27]
	v_mfma_f32_16x16x32_bf16 v[24:27], v[12:15], v[186:189], v[48:51]
	v_mfma_f32_16x16x32_bf16 v[44:47], v[198:201], v[190:193], v[24:27]
	v_mfma_f32_16x16x32_bf16 v[24:27], v[0:3], v[202:205], v[226:229]
	v_mfma_f32_16x16x32_bf16 v[0:3], v[0:3], v[222:225], v[36:39]
	v_mfma_f32_16x16x32_bf16 v[24:27], v[8:11], v[218:221], v[24:27]
	v_mfma_f32_16x16x32_bf16 v[28:31], v[12:15], v[202:205], v[230:233]
	v_mfma_f32_16x16x32_bf16 v[8:11], v[8:11], v[238:241], v[0:3]
	v_mfma_f32_16x16x32_bf16 v[0:3], v[12:15], v[222:225], v[32:35]
	v_mfma_f32_16x16x32_bf16 v[28:31], v[198:201], v[218:221], v[28:31]
	v_mfma_f32_16x16x32_bf16 v[12:15], v[198:201], v[238:241], v[0:3]
	s_setprio 0
	s_setprio 1
	v_mfma_f32_16x16x32_bf16 v[0:3], v[134:137], v[178:181], v[162:165]
	v_mfma_f32_16x16x32_bf16 v[48:51], v[210:213], v[182:185], v[0:3]
	v_mfma_f32_16x16x32_bf16 v[0:3], v[214:217], v[178:181], v[166:169]
	v_mfma_f32_16x16x32_bf16 v[52:55], v[234:237], v[182:185], v[0:3]
	v_mfma_f32_16x16x32_bf16 v[0:3], v[134:137], v[186:189], v[20:23]
	v_mfma_f32_16x16x32_bf16 v[32:35], v[210:213], v[190:193], v[0:3]
	v_mfma_f32_16x16x32_bf16 v[0:3], v[214:217], v[186:189], v[16:19]
	v_mfma_f32_16x16x32_bf16 v[36:39], v[234:237], v[190:193], v[0:3]
	v_mfma_f32_16x16x32_bf16 v[0:3], v[134:137], v[202:205], v[170:173]
	v_mfma_f32_16x16x32_bf16 v[16:19], v[210:213], v[218:221], v[0:3]
	v_mfma_f32_16x16x32_bf16 v[0:3], v[214:217], v[202:205], v[174:177]
	v_mfma_f32_16x16x32_bf16 v[20:23], v[234:237], v[218:221], v[0:3]
	v_mfma_f32_16x16x32_bf16 v[0:3], v[134:137], v[222:225], v[4:7]
	v_mfma_f32_16x16x32_bf16 v[4:7], v[214:217], v[222:225], v[194:197]
	v_mfma_f32_16x16x32_bf16 v[0:3], v[210:213], v[238:241], v[0:3]
	v_mfma_f32_16x16x32_bf16 v[4:7], v[234:237], v[238:241], v[4:7]
	s_setprio 0
	s_barrier
	s_and_saveexec_b64 s[34:35], s[4:5]
	s_cbranch_execz .LBB0_99
	s_barrier

; #define STA(b, h, half, kt) STAGE(((b) * 2 + (h)) * G_HT * 2, pA, ((size_t)(half) * G_HALF * lda + (size_t)(kt) * G_BK) * 2, lda)
; #define STB(b, h, half, kt) STAGE((4 + (b) * 2 + (h)) * G_HT * 2, pB, ((size_t)(half) * G_HALF * K + (size_t)(kt) * G_BK) * 2, K)
; #define LDA(dst, b, h) for (int m = 0; m < 4; ++m) for (int k = 0; k < 2; ++k) \
;     dst[m][k] = *reinterpret_cast<const bf16x8*>(aRd + (((b) * 2 + (h)) * G_HT * 2 + m * 2048 + k * 1024))
; #define LDB(dst, b, h) for (int n = 0; n < 2; ++n) for (int k = 0; k < 2; ++k) \
;     dst[n][k] = *reinterpret_cast<const bf16x8*>(bRd + (((b) * 2 + (h)) * G_HT * 2 + n * 2048 + k * 1024))
; #define MMA(ai, bj, At, Bx) do { __builtin_amdgcn_s_setprio(1); \
;     for (int m = 0; m < 4; ++m) for (int n = 0; n < 2; ++n) for (int k = 0; k < 2; ++k) \
;       acc[ai][bj][m][n] = __builtin_amdgcn_mfma_f32_16x16x32_bf16(Bx[n][k], At[m][k], acc[ai][bj][m][n], 0, 0, 0);     \
;     __builtin_amdgcn_s_setprio(0); } while (0)
; #define WAIT_V(n) asm volatile("s_waitcnt vmcnt(" #n ")" ::: "memory")
; #define WAIT_L(n) asm volatile("s_waitcnt lgkmcnt(" #n ")" ::: "memory")
; #define BAR __builtin_amdgcn_s_barrier()
; #define SCHED __builtin_amdgcn_sched_barrier(0)
; template <int EPI>
; __device__ __forceinline__ void gemm_tile(const bf16* __restrict__ A, int lda, const bf16* __restrict__ Bt, int K,
;                                           int brow, int bcol, const EpiArgs& ea, char* shmc, bool has_next, int nbrow, int nbcol, bool first_tile) {
;     ...
;   for (int t = 0; t < nt - 2; t += 2) {
;     LDB(B0, 0, 0); SCHED; LDA(At, 0, 0); STA(1, 1, 1, t + 1);
;     WAIT_L(8); BAR; WAIT_L(0); MMA(0, 0, At, B0); BAR; SCHED;
;     LDB(B1, 0, 1); STB(0, 0, 0, t + 2);
;     BAR; WAIT_L(0); MMA(0, 1, At, B1); BAR;
;     LDA(At, 0, 1); STA(0, 0, 0, t + 2);
;     BAR; WAIT_L(0); MMA(1, 0, At, B0); BAR; SCHED;
;     STB(0, 1, 1, t + 2);
;     WAIT_V(6); BAR; MMA(1, 1, At, B1); BAR;
.LBB0_291:
	ds_read_b128 v[160:163], v137
	ds_read_b128 v[164:167], v138
	ds_read_b128 v[168:171], v139
	ds_read_b128 v[172:175], v140
	s_add_u32 s80, s18, 0xffffff80
	s_addc_u32 s81, s19, -1
	s_mov_b32 m0, s72
	ds_read_b128 v[176:179], v158
	ds_read_b128 v[180:183], v158 offset:1024
	ds_read_b128 v[184:187], v158 offset:2048
	ds_read_b128 v[188:191], v158 offset:3072
	ds_read_b128 v[192:195], v158 offset:4096
	ds_read_b128 v[196:199], v158 offset:5120
	ds_read_b128 v[200:203], v158 offset:6144
	ds_read_b128 v[204:207], v158 offset:7168
	v_lshl_add_u64 v[208:209], v[132:133], 0, s[80:81]
	global_load_lds_dwordx4 v[208:209], off
	s_mov_b32 m0, s62
	v_lshl_add_u64 v[208:209], v[208:209], 0, s[10:11]
	global_load_lds_dwordx4 v[208:209], off
	s_waitcnt lgkmcnt(8)
	s_barrier
	s_waitcnt lgkmcnt(0)
	s_setprio 1
	v_mfma_f32_16x16x32_bf16 v[124:127], v[160:163], v[176:179], v[124:127]
	v_mfma_f32_16x16x32_bf16 v[120:123], v[168:171], v[176:179], v[120:123]
	v_mfma_f32_16x16x32_bf16 v[116:119], v[160:163], v[184:187], v[116:119]
	v_mfma_f32_16x16x32_bf16 v[112:115], v[168:171], v[184:187], v[112:115]
	v_mfma_f32_16x16x32_bf16 v[108:111], v[160:163], v[192:195], v[108:111]
	v_mfma_f32_16x16x32_bf16 v[104:107], v[168:171], v[192:195], v[104:107]
	v_mfma_f32_16x16x32_bf16 v[100:103], v[160:163], v[200:203], v[100:103]
	v_mfma_f32_16x16x32_bf16 v[96:99], v[168:171], v[200:203], v[96:99]
	v_mfma_f32_16x16x32_bf16 v[124:127], v[164:167], v[180:183], v[124:127]
	v_mfma_f32_16x16x32_bf16 v[120:123], v[172:175], v[180:183], v[120:123]
	v_mfma_f32_16x16x32_bf16 v[116:119], v[164:167], v[188:191], v[116:119]
	v_mfma_f32_16x16x32_bf16 v[112:115], v[172:175], v[188:191], v[112:115]
	v_mfma_f32_16x16x32_bf16 v[108:111], v[164:167], v[196:199], v[108:111]
	v_mfma_f32_16x16x32_bf16 v[104:107], v[172:175], v[196:199], v[104:107]
	v_mfma_f32_16x16x32_bf16 v[100:103], v[164:167], v[204:207], v[100:103]
	v_mfma_f32_16x16x32_bf16 v[96:99], v[172:175], v[204:207], v[96:99]
	s_setprio 0
	s_barrier
	s_add_u32 s80, s18, 0xfffa0000
	s_addc_u32 s81, s19, -1
	s_mov_b32 m0, s67
	ds_read_b128 v[208:211], v141
	ds_read_b128 v[212:215], v142
	ds_read_b128 v[216:219], v143
	ds_read_b128 v[220:223], v144
	v_lshl_add_u64 v[224:225], v[134:135], 0, s[80:81]
	global_load_lds_dwordx4 v[224:225], off
	s_mov_b32 m0, s68
	v_lshl_add_u64 v[224:225], v[224:225], 0, s[8:9]
	global_load_lds_dwordx4 v[224:225], off
	s_barrier
	s_waitcnt lgkmcnt(0)
	s_setprio 1
	v_mfma_f32_16x16x32_bf16 v[92:95], v[208:211], v[176:179], v[92:95]
	v_mfma_f32_16x16x32_bf16 v[88:91], v[216:219], v[176:179], v[88:91]
	v_mfma_f32_16x16x32_bf16 v[84:87], v[208:211], v[184:187], v[84:87]
	v_mfma_f32_16x16x32_bf16 v[80:83], v[216:219], v[184:187], v[80:83]
	v_mfma_f32_16x16x32_bf16 v[76:79], v[208:211], v[192:195], v[76:79]
	v_mfma_f32_16x16x32_bf16 v[72:75], v[216:219], v[192:195], v[72:75]
	v_mfma_f32_16x16x32_bf16 v[68:71], v[208:211], v[200:203], v[68:71]
	v_mfma_f32_16x16x32_bf16 v[64:67], v[216:219], v[200:203], v[64:67]
	v_mfma_f32_16x16x32_bf16 v[92:95], v[212:215], v[180:183], v[92:95]
	v_mfma_f32_16x16x32_bf16 v[88:91], v[220:223], v[180:183], v[88:91]
	v_mfma_f32_16x16x32_bf16 v[84:87], v[212:215], v[188:191], v[84:87]
	v_mfma_f32_16x16x32_bf16 v[80:83], v[220:223], v[188:191], v[80:83]
	v_mfma_f32_16x16x32_bf16 v[76:79], v[212:215], v[196:199], v[76:79]
	v_mfma_f32_16x16x32_bf16 v[72:75], v[220:223], v[196:199], v[72:75]
	v_mfma_f32_16x16x32_bf16 v[68:71], v[212:215], v[204:207], v[68:71]
	v_mfma_f32_16x16x32_bf16 v[64:67], v[220:223], v[204:207], v[64:67]
	s_setprio 0
	s_mov_b32 m0, s31
	s_barrier
	ds_read_b128 v[176:179], v158 offset:16384
	ds_read_b128 v[180:183], v158 offset:17408
	ds_read_b128 v[184:187], v158 offset:18432
	ds_read_b128 v[188:191], v158 offset:19456
	ds_read_b128 v[192:195], v158 offset:20480
	ds_read_b128 v[196:199], v158 offset:21504
	ds_read_b128 v[200:203], v158 offset:22528
	ds_read_b128 v[204:207], v158 offset:23552
	v_lshl_add_u64 v[224:225], v[132:133], 0, s[80:81]
	global_load_lds_dwordx4 v[224:225], off
	s_mov_b32 m0, s73
	v_lshl_add_u64 v[224:225], v[224:225], 0, s[10:11]
	global_load_lds_dwordx4 v[224:225], off
	s_barrier
	s_waitcnt lgkmcnt(0)
	s_setprio 1
	v_mfma_f32_16x16x32_bf16 v[60:63], v[160:163], v[176:179], v[60:63]
	v_mfma_f32_16x16x32_bf16 v[56:59], v[168:171], v[176:179], v[56:59]
	v_mfma_f32_16x16x32_bf16 v[52:55], v[160:163], v[184:187], v[52:55]
	v_mfma_f32_16x16x32_bf16 v[48:51], v[168:171], v[184:187], v[48:51]
	v_mfma_f32_16x16x32_bf16 v[44:47], v[160:163], v[192:195], v[44:47]
	v_mfma_f32_16x16x32_bf16 v[40:43], v[168:171], v[192:195], v[40:43]
	v_mfma_f32_16x16x32_bf16 v[36:39], v[160:163], v[200:203], v[36:39]
	v_mfma_f32_16x16x32_bf16 v[32:35], v[168:171], v[200:203], v[32:35]
	v_mfma_f32_16x16x32_bf16 v[60:63], v[164:167], v[180:183], v[60:63]
	v_mfma_f32_16x16x32_bf16 v[56:59], v[172:175], v[180:183], v[56:59]
	v_mfma_f32_16x16x32_bf16 v[52:55], v[164:167], v[188:191], v[52:55]
	v_mfma_f32_16x16x32_bf16 v[48:51], v[172:175], v[188:191], v[48:51]
	v_mfma_f32_16x16x32_bf16 v[44:47], v[164:167], v[196:199], v[44:47]
	v_mfma_f32_16x16x32_bf16 v[40:43], v[172:175], v[196:199], v[40:43]
	v_mfma_f32_16x16x32_bf16 v[36:39], v[164:167], v[204:207], v[36:39]
	v_mfma_f32_16x16x32_bf16 v[32:35], v[172:175], v[204:207], v[32:35]
	s_setprio 0
	s_barrier
	s_add_u32 s80, s18, 0xfffd0000
	s_addc_u32 s81, s19, -1
	s_mov_b32 m0, s69
	v_lshl_add_u64 v[160:161], v[134:135], 0, s[80:81]
	global_load_lds_dwordx4 v[160:161], off
	s_mov_b32 m0, s70
	v_lshl_add_u64 v[160:161], v[160:161], 0, s[8:9]
	global_load_lds_dwordx4 v[160:161], off
	s_waitcnt vmcnt(6)
	s_barrier
; #define STA(b, h, half, kt) STAGE(((b) * 2 + (h)) * G_HT * 2, pA, ((size_t)(half) * G_HALF * lda + (size_t)(kt) * G_BK) * 2, lda)
; #define STB(b, h, half, kt) STAGE((4 + (b) * 2 + (h)) * G_HT * 2, pB, ((size_t)(half) * G_HALF * K + (size_t)(kt) * G_BK) * 2, K)
; #define LDA(dst, b, h) for (int m = 0; m < 4; ++m) for (int k = 0; k < 2; ++k) \
;     dst[m][k] = *reinterpret_cast<const bf16x8*>(aRd + (((b) * 2 + (h)) * G_HT * 2 + m * 2048 + k * 1024))
; #define LDB(dst, b, h) for (int n = 0; n < 2; ++n) for (int k = 0; k < 2; ++k) \
;     dst[n][k] = *reinterpret_cast<const bf16x8*>(bRd + (((b) * 2 + (h)) * G_HT * 2 + n * 2048 + k * 1024))
; #define MMA(ai, bj, At, Bx) do { __builtin_amdgcn_s_setprio(1); \
;     for (int m = 0; m < 4; ++m) for (int n = 0; n < 2; ++n) for (int k = 0; k < 2; ++k) \
;       acc[ai][bj][m][n] = __builtin_amdgcn_mfma_f32_16x16x32_bf16(Bx[n][k], At[m][k], acc[ai][bj][m][n], 0, 0, 0);     \
;     __builtin_amdgcn_s_setprio(0); } while (0)
; #define WAIT_V(n) asm volatile("s_waitcnt vmcnt(" #n ")" ::: "memory")
; #define WAIT_L(n) asm volatile("s_waitcnt lgkmcnt(" #n ")" ::: "memory")
; #define BAR __builtin_amdgcn_s_barrier()
; #define SCHED __builtin_amdgcn_sched_barrier(0)
; template <int EPI>
; __device__ __forceinline__ void gemm_tile(const bf16* __restrict__ A, int lda, const bf16* __restrict__ Bt, int K,
;                                           int brow, int bcol, const EpiArgs& ea, char* shmc, bool has_next, int nbrow, int nbcol, bool first_tile) {
;     ...
;     WAIT_V(6); BAR; MMA(1, 1, At, B1); BAR;
;     LDB(B0, 1, 0); SCHED; LDA(At, 1, 0); STA(0, 1, 1, t + 2);
;     WAIT_L(8); BAR; WAIT_L(0); MMA(0, 0, At, B0); BAR; SCHED;
;     LDB(B1, 1, 1); STB(1, 0, 0, t + 3);
;     BAR; WAIT_L(0); MMA(0, 1, At, B1); BAR;
;     LDA(At, 1, 1); STA(1, 0, 0, t + 3);
;     BAR; WAIT_L(0); MMA(1, 0, At, B0); BAR; SCHED;
	s_setprio 1
	v_mfma_f32_16x16x32_bf16 v[28:31], v[208:211], v[176:179], v[28:31]
	v_mfma_f32_16x16x32_bf16 v[24:27], v[216:219], v[176:179], v[24:27]
	v_mfma_f32_16x16x32_bf16 v[20:23], v[208:211], v[184:187], v[20:23]
	v_mfma_f32_16x16x32_bf16 v[16:19], v[216:219], v[184:187], v[16:19]
	v_mfma_f32_16x16x32_bf16 v[12:15], v[208:211], v[192:195], v[12:15]
	v_mfma_f32_16x16x32_bf16 v[8:11], v[216:219], v[192:195], v[8:11]
	v_mfma_f32_16x16x32_bf16 v[4:7], v[208:211], v[200:203], v[4:7]
	v_mfma_f32_16x16x32_bf16 v[0:3], v[216:219], v[200:203], v[0:3]
	v_mfma_f32_16x16x32_bf16 v[28:31], v[212:215], v[180:183], v[28:31]
	v_mfma_f32_16x16x32_bf16 v[24:27], v[220:223], v[180:183], v[24:27]
	v_mfma_f32_16x16x32_bf16 v[20:23], v[212:215], v[188:191], v[20:23]
	v_mfma_f32_16x16x32_bf16 v[16:19], v[220:223], v[188:191], v[16:19]
	v_mfma_f32_16x16x32_bf16 v[12:15], v[212:215], v[196:199], v[12:15]
	v_mfma_f32_16x16x32_bf16 v[8:11], v[220:223], v[196:199], v[8:11]
	v_mfma_f32_16x16x32_bf16 v[4:7], v[212:215], v[204:207], v[4:7]
	v_mfma_f32_16x16x32_bf16 v[0:3], v[220:223], v[204:207], v[0:3]
	s_setprio 0
	s_barrier
	ds_read_b128 v[160:163], v145
	ds_read_b128 v[164:167], v146
	ds_read_b128 v[168:171], v147
	ds_read_b128 v[172:175], v148
	s_mov_b32 m0, s74
	ds_read_b128 v[176:179], v158 offset:32768
	ds_read_b128 v[180:183], v158 offset:33792
	ds_read_b128 v[184:187], v158 offset:34816
	ds_read_b128 v[188:191], v158 offset:35840
	ds_read_b128 v[192:195], v158 offset:36864
	ds_read_b128 v[196:199], v158 offset:37888
	ds_read_b128 v[200:203], v158 offset:38912
	ds_read_b128 v[204:207], v158 offset:39936
	v_lshl_add_u64 v[208:209], v[132:133], 0, s[18:19]
	global_load_lds_dwordx4 v[208:209], off
	s_mov_b32 m0, s75
	v_lshl_add_u64 v[208:209], v[208:209], 0, s[10:11]
	global_load_lds_dwordx4 v[208:209], off
	s_waitcnt lgkmcnt(8)
	s_barrier
	s_waitcnt lgkmcnt(0)
	s_setprio 1
	v_mfma_f32_16x16x32_bf16 v[124:127], v[160:163], v[176:179], v[124:127]
	v_mfma_f32_16x16x32_bf16 v[120:123], v[168:171], v[176:179], v[120:123]
	v_mfma_f32_16x16x32_bf16 v[116:119], v[160:163], v[184:187], v[116:119]
	v_mfma_f32_16x16x32_bf16 v[112:115], v[168:171], v[184:187], v[112:115]
	v_mfma_f32_16x16x32_bf16 v[108:111], v[160:163], v[192:195], v[108:111]
	v_mfma_f32_16x16x32_bf16 v[104:107], v[168:171], v[192:195], v[104:107]
	v_mfma_f32_16x16x32_bf16 v[100:103], v[160:163], v[200:203], v[100:103]
	v_mfma_f32_16x16x32_bf16 v[96:99], v[168:171], v[200:203], v[96:99]
	v_mfma_f32_16x16x32_bf16 v[124:127], v[164:167], v[180:183], v[124:127]
	v_mfma_f32_16x16x32_bf16 v[120:123], v[172:175], v[180:183], v[120:123]
	v_mfma_f32_16x16x32_bf16 v[116:119], v[164:167], v[188:191], v[116:119]
	v_mfma_f32_16x16x32_bf16 v[112:115], v[172:175], v[188:191], v[112:115]
	v_mfma_f32_16x16x32_bf16 v[108:111], v[164:167], v[196:199], v[108:111]
	v_mfma_f32_16x16x32_bf16 v[104:107], v[172:175], v[196:199], v[104:107]
	v_mfma_f32_16x16x32_bf16 v[100:103], v[164:167], v[204:207], v[100:103]
	v_mfma_f32_16x16x32_bf16 v[96:99], v[172:175], v[204:207], v[96:99]
	s_setprio 0
	s_barrier
	s_add_u32 s80, s18, 0xfffa0080
	s_addc_u32 s81, s19, -1
	s_mov_b32 m0, s34
	ds_read_b128 v[208:211], v149
	ds_read_b128 v[212:215], v150
	ds_read_b128 v[216:219], v151
	ds_read_b128 v[220:223], v152
	v_lshl_add_u64 v[224:225], v[134:135], 0, s[80:81]
	global_load_lds_dwordx4 v[224:225], off
	s_mov_b32 m0, s35
	v_lshl_add_u64 v[224:225], v[224:225], 0, s[8:9]
	global_load_lds_dwordx4 v[224:225], off
	s_barrier
	s_waitcnt lgkmcnt(0)
	s_setprio 1
	v_mfma_f32_16x16x32_bf16 v[92:95], v[208:211], v[176:179], v[92:95]
	v_mfma_f32_16x16x32_bf16 v[88:91], v[216:219], v[176:179], v[88:91]
	v_mfma_f32_16x16x32_bf16 v[84:87], v[208:211], v[184:187], v[84:87]
	v_mfma_f32_16x16x32_bf16 v[80:83], v[216:219], v[184:187], v[80:83]
	v_mfma_f32_16x16x32_bf16 v[76:79], v[208:211], v[192:195], v[76:79]
	v_mfma_f32_16x16x32_bf16 v[72:75], v[216:219], v[192:195], v[72:75]
	v_mfma_f32_16x16x32_bf16 v[68:71], v[208:211], v[200:203], v[68:71]
	v_mfma_f32_16x16x32_bf16 v[64:67], v[216:219], v[200:203], v[64:67]
	v_mfma_f32_16x16x32_bf16 v[92:95], v[212:215], v[180:183], v[92:95]
	v_mfma_f32_16x16x32_bf16 v[88:91], v[220:223], v[180:183], v[88:91]
	v_mfma_f32_16x16x32_bf16 v[84:87], v[212:215], v[188:191], v[84:87]
	v_mfma_f32_16x16x32_bf16 v[80:83], v[220:223], v[188:191], v[80:83]
	v_mfma_f32_16x16x32_bf16 v[76:79], v[212:215], v[196:199], v[76:79]
	v_mfma_f32_16x16x32_bf16 v[72:75], v[220:223], v[196:199], v[72:75]
	v_mfma_f32_16x16x32_bf16 v[68:71], v[212:215], v[204:207], v[68:71]
	v_mfma_f32_16x16x32_bf16 v[64:67], v[220:223], v[204:207], v[64:67]
	s_setprio 0
	s_mov_b32 m0, s54
	s_barrier
	ds_read_b128 v[176:179], v158 offset:49152
	ds_read_b128 v[180:183], v158 offset:50176
	ds_read_b128 v[184:187], v158 offset:51200
	ds_read_b128 v[188:191], v158 offset:52224
	ds_read_b128 v[192:195], v158 offset:53248
	ds_read_b128 v[196:199], v158 offset:54272
	ds_read_b128 v[200:203], v158 offset:55296
	ds_read_b128 v[204:207], v158 offset:56320
	v_lshl_add_u64 v[224:225], v[132:133], 0, s[80:81]
	global_load_lds_dwordx4 v[224:225], off
	s_mov_b32 m0, s55
	v_lshl_add_u64 v[224:225], v[224:225], 0, s[10:11]
	global_load_lds_dwordx4 v[224:225], off
	s_barrier
; #define STA(b, h, half, kt) STAGE(((b) * 2 + (h)) * G_HT * 2, pA, ((size_t)(half) * G_HALF * lda + (size_t)(kt) * G_BK) * 2, lda)
; #define STB(b, h, half, kt) STAGE((4 + (b) * 2 + (h)) * G_HT * 2, pB, ((size_t)(half) * G_HALF * K + (size_t)(kt) * G_BK) * 2, K)
; #define LDA(dst, b, h) for (int m = 0; m < 4; ++m) for (int k = 0; k < 2; ++k) \
;     dst[m][k] = *reinterpret_cast<const bf16x8*>(aRd + (((b) * 2 + (h)) * G_HT * 2 + m * 2048 + k * 1024))
; #define LDB(dst, b, h) for (int n = 0; n < 2; ++n) for (int k = 0; k < 2; ++k) \
;     dst[n][k] = *reinterpret_cast<const bf16x8*>(bRd + (((b) * 2 + (h)) * G_HT * 2 + n * 2048 + k * 1024))
; #define MMA(ai, bj, At, Bx) do { __builtin_amdgcn_s_setprio(1); \
;     for (int m = 0; m < 4; ++m) for (int n = 0; n < 2; ++n) for (int k = 0; k < 2; ++k) \
;       acc[ai][bj][m][n] = __builtin_amdgcn_mfma_f32_16x16x32_bf16(Bx[n][k], At[m][k], acc[ai][bj][m][n], 0, 0, 0);     \
;     __builtin_amdgcn_s_setprio(0); } while (0)
; #define WAIT_V(n) asm volatile("s_waitcnt vmcnt(" #n ")" ::: "memory")
; #define WAIT_L(n) asm volatile("s_waitcnt lgkmcnt(" #n ")" ::: "memory")
; #define BAR __builtin_amdgcn_s_barrier()
; #define SCHED __builtin_amdgcn_sched_barrier(0)
; template <int EPI>
; __device__ __forceinline__ void gemm_tile(const bf16* __restrict__ A, int lda, const bf16* __restrict__ Bt, int K,
;                                           int brow, int bcol, const EpiArgs& ea, char* shmc, bool has_next, int nbrow, int nbcol, bool first_tile) {
;     ...
;     BAR; WAIT_L(0); MMA(1, 0, At, B0); BAR; SCHED;
;     STB(1, 1, 1, t + 3);
;     WAIT_V(6); BAR; MMA(1, 1, At, B1); BAR;
;   }
;   { LDB(B0, 0, 0); LDA(At, 0, 0); STA(1, 1, 1, nt - 1);
;     BAR; WAIT_L(0); MMA(0, 0, At, B0); BAR;
;     LDB(B1, 0, 1); BAR; WAIT_L(0); MMA(0, 1, At, B1); BAR;
;     LDA(At, 0, 1); WAIT_V(4); BAR; WAIT_L(0); MMA(1, 0, At, B0); MMA(1, 1, At, B1); BAR; }
	s_waitcnt lgkmcnt(0)
	s_setprio 1
	v_mfma_f32_16x16x32_bf16 v[60:63], v[160:163], v[176:179], v[60:63]
	v_mfma_f32_16x16x32_bf16 v[56:59], v[168:171], v[176:179], v[56:59]
	v_mfma_f32_16x16x32_bf16 v[52:55], v[160:163], v[184:187], v[52:55]
	v_mfma_f32_16x16x32_bf16 v[48:51], v[168:171], v[184:187], v[48:51]
	v_mfma_f32_16x16x32_bf16 v[44:47], v[160:163], v[192:195], v[44:47]
	v_mfma_f32_16x16x32_bf16 v[40:43], v[168:171], v[192:195], v[40:43]
	v_mfma_f32_16x16x32_bf16 v[36:39], v[160:163], v[200:203], v[36:39]
	v_mfma_f32_16x16x32_bf16 v[32:35], v[168:171], v[200:203], v[32:35]
	v_mfma_f32_16x16x32_bf16 v[60:63], v[164:167], v[180:183], v[60:63]
	v_mfma_f32_16x16x32_bf16 v[56:59], v[172:175], v[180:183], v[56:59]
	v_mfma_f32_16x16x32_bf16 v[52:55], v[164:167], v[188:191], v[52:55]
	v_mfma_f32_16x16x32_bf16 v[48:51], v[172:175], v[188:191], v[48:51]
	v_mfma_f32_16x16x32_bf16 v[44:47], v[164:167], v[196:199], v[44:47]
	v_mfma_f32_16x16x32_bf16 v[40:43], v[172:175], v[196:199], v[40:43]
	v_mfma_f32_16x16x32_bf16 v[36:39], v[164:167], v[204:207], v[36:39]
	v_mfma_f32_16x16x32_bf16 v[32:35], v[172:175], v[204:207], v[32:35]
	s_setprio 0
	s_barrier
	s_add_u32 s80, s18, 0xfffd0080
	s_addc_u32 s81, s19, -1
	s_mov_b32 m0, s63
	v_lshl_add_u64 v[160:161], v[134:135], 0, s[80:81]
	global_load_lds_dwordx4 v[160:161], off
	s_mov_b32 m0, s66
	v_lshl_add_u64 v[160:161], v[160:161], 0, s[8:9]
	global_load_lds_dwordx4 v[160:161], off
	s_waitcnt vmcnt(6)
	s_barrier
	s_setprio 1
	v_mfma_f32_16x16x32_bf16 v[28:31], v[208:211], v[176:179], v[28:31]
	v_mfma_f32_16x16x32_bf16 v[24:27], v[216:219], v[176:179], v[24:27]
	v_mfma_f32_16x16x32_bf16 v[20:23], v[208:211], v[184:187], v[20:23]
	v_mfma_f32_16x16x32_bf16 v[16:19], v[216:219], v[184:187], v[16:19]
	v_mfma_f32_16x16x32_bf16 v[12:15], v[208:211], v[192:195], v[12:15]
	v_mfma_f32_16x16x32_bf16 v[8:11], v[216:219], v[192:195], v[8:11]
	v_mfma_f32_16x16x32_bf16 v[4:7], v[208:211], v[200:203], v[4:7]
	v_mfma_f32_16x16x32_bf16 v[0:3], v[216:219], v[200:203], v[0:3]
	v_mfma_f32_16x16x32_bf16 v[28:31], v[212:215], v[180:183], v[28:31]
	v_mfma_f32_16x16x32_bf16 v[24:27], v[220:223], v[180:183], v[24:27]
	v_mfma_f32_16x16x32_bf16 v[20:23], v[212:215], v[188:191], v[20:23]
	v_mfma_f32_16x16x32_bf16 v[16:19], v[220:223], v[188:191], v[16:19]
	v_mfma_f32_16x16x32_bf16 v[12:15], v[212:215], v[196:199], v[12:15]
	v_mfma_f32_16x16x32_bf16 v[8:11], v[220:223], v[196:199], v[8:11]
	v_mfma_f32_16x16x32_bf16 v[4:7], v[212:215], v[204:207], v[4:7]
	v_mfma_f32_16x16x32_bf16 v[0:3], v[220:223], v[204:207], v[0:3]
	s_setprio 0
	s_add_i32 s71, s71, 2
	s_add_u32 s18, s18, 0x100
	s_addc_u32 s19, s19, 0
	s_cmp_lt_u32 s71, 8
	s_barrier
	s_cbranch_scc1 .LBB0_291
	s_mov_b64 s[18:19], 0x60580
	s_mov_b32 m0, s72
	ds_read_b128 v[160:163], v137
	ds_read_b128 v[164:167], v138
	ds_read_b128 v[168:171], v139
	ds_read_b128 v[172:175], v140
	ds_read_b128 v[176:179], v158
	ds_read_b128 v[180:183], v158 offset:1024
	ds_read_b128 v[184:187], v158 offset:2048
	ds_read_b128 v[188:191], v158 offset:3072
	ds_read_b128 v[192:195], v158 offset:4096
	ds_read_b128 v[196:199], v158 offset:5120
	ds_read_b128 v[200:203], v158 offset:6144
	ds_read_b128 v[204:207], v158 offset:7168
	s_nop 0
	v_lshl_add_u64 v[132:133], v[132:133], 0, s[18:19]
	global_load_lds_dwordx4 v[132:133], off
	v_lshl_add_u64 v[132:133], v[132:133], 0, s[10:11]
	s_mov_b32 m0, s62
	s_nop 0
	global_load_lds_dwordx4 v[132:133], off
	s_barrier
	s_waitcnt lgkmcnt(0)
	s_setprio 1
	s_waitcnt lgkmcnt(0)
	v_mfma_f32_16x16x32_bf16 v[124:127], v[160:163], v[176:179], v[124:127]
	v_mfma_f32_16x16x32_bf16 v[120:123], v[168:171], v[176:179], v[120:123]
	v_mfma_f32_16x16x32_bf16 v[108:111], v[160:163], v[192:195], v[108:111]
	v_mfma_f32_16x16x32_bf16 v[104:107], v[168:171], v[192:195], v[104:107]
	v_mfma_f32_16x16x32_bf16 v[124:127], v[164:167], v[180:183], v[124:127]
	v_mfma_f32_16x16x32_bf16 v[120:123], v[172:175], v[180:183], v[120:123]
	v_mfma_f32_16x16x32_bf16 v[116:119], v[160:163], v[184:187], v[116:119]
	v_mfma_f32_16x16x32_bf16 v[112:115], v[168:171], v[184:187], v[112:115]
	v_mfma_f32_16x16x32_bf16 v[108:111], v[164:167], v[196:199], v[108:111]
	v_mfma_f32_16x16x32_bf16 v[104:107], v[172:175], v[196:199], v[104:107]
	v_mfma_f32_16x16x32_bf16 v[100:103], v[160:163], v[200:203], v[100:103]
	v_mfma_f32_16x16x32_bf16 v[96:99], v[168:171], v[200:203], v[96:99]
	v_mfma_f32_16x16x32_bf16 v[132:135], v[164:167], v[188:191], v[116:119]
	v_mfma_f32_16x16x32_bf16 v[208:211], v[172:175], v[188:191], v[112:115]
	v_mfma_f32_16x16x32_bf16 v[212:215], v[164:167], v[204:207], v[100:103]
	v_mfma_f32_16x16x32_bf16 v[216:219], v[172:175], v[204:207], v[96:99]
	s_setprio 0
	s_barrier
	s_nop 1
	ds_read_b128 v[96:99], v141
	ds_read_b128 v[100:103], v142
	ds_read_b128 v[112:115], v143
	ds_read_b128 v[116:119], v144
	s_barrier
	s_waitcnt lgkmcnt(0)
	s_setprio 1
	s_waitcnt lgkmcnt(0)
	v_mfma_f32_16x16x32_bf16 v[92:95], v[96:99], v[176:179], v[92:95]
	v_mfma_f32_16x16x32_bf16 v[88:91], v[112:115], v[176:179], v[88:91]
	v_mfma_f32_16x16x32_bf16 v[76:79], v[96:99], v[192:195], v[76:79]
	v_mfma_f32_16x16x32_bf16 v[72:75], v[112:115], v[192:195], v[72:75]
	v_mfma_f32_16x16x32_bf16 v[68:71], v[96:99], v[200:203], v[68:71]
	v_mfma_f32_16x16x32_bf16 v[64:67], v[112:115], v[200:203], v[64:67]
	v_mfma_f32_16x16x32_bf16 v[92:95], v[100:103], v[180:183], v[92:95]
	v_mfma_f32_16x16x32_bf16 v[88:91], v[116:119], v[180:183], v[88:91]
	v_mfma_f32_16x16x32_bf16 v[84:87], v[96:99], v[184:187], v[84:87]
	v_mfma_f32_16x16x32_bf16 v[80:83], v[112:115], v[184:187], v[80:83]
	v_mfma_f32_16x16x32_bf16 v[76:79], v[100:103], v[196:199], v[76:79]
	v_mfma_f32_16x16x32_bf16 v[72:75], v[116:119], v[196:199], v[72:75]
	v_mfma_f32_16x16x32_bf16 v[68:71], v[100:103], v[204:207], v[68:71]
	v_mfma_f32_16x16x32_bf16 v[64:67], v[116:119], v[204:207], v[64:67]
	v_mfma_f32_16x16x32_bf16 v[176:179], v[100:103], v[188:191], v[84:87]
	v_mfma_f32_16x16x32_bf16 v[180:183], v[116:119], v[188:191], v[80:83]
	s_setprio 0
	s_barrier
; #define LDA(dst, b, h) for (int m = 0; m < 4; ++m) for (int k = 0; k < 2; ++k) \
;     dst[m][k] = *reinterpret_cast<const bf16x8*>(aRd + (((b) * 2 + (h)) * G_HT * 2 + m * 2048 + k * 1024))
; #define LDB(dst, b, h) for (int n = 0; n < 2; ++n) for (int k = 0; k < 2; ++k) \
;     dst[n][k] = *reinterpret_cast<const bf16x8*>(bRd + (((b) * 2 + (h)) * G_HT * 2 + n * 2048 + k * 1024))
; #define MMA(ai, bj, At, Bx) do { __builtin_amdgcn_s_setprio(1); \
;     for (int m = 0; m < 4; ++m) for (int n = 0; n < 2; ++n) for (int k = 0; k < 2; ++k) \
;       acc[ai][bj][m][n] = __builtin_amdgcn_mfma_f32_16x16x32_bf16(Bx[n][k], At[m][k], acc[ai][bj][m][n], 0, 0, 0);     \
;     __builtin_amdgcn_s_setprio(0); } while (0)
; #define WAIT_V(n) asm volatile("s_waitcnt vmcnt(" #n ")" ::: "memory")
; #define WAIT_L(n) asm volatile("s_waitcnt lgkmcnt(" #n ")" ::: "memory")
; #define BAR __builtin_amdgcn_s_barrier()
; template <int EPI>
; __device__ __forceinline__ void gemm_tile(const bf16* __restrict__ A, int lda, const bf16* __restrict__ Bt, int K,
;                                           int brow, int bcol, const EpiArgs& ea, char* shmc, bool has_next, int nbrow, int nbcol, bool first_tile) {
;     ...
;     LDA(At, 0, 1); WAIT_V(4); BAR; WAIT_L(0); MMA(1, 0, At, B0); MMA(1, 1, At, B1); BAR; }
;   { LDB(B0, 1, 0); LDA(At, 1, 0); WAIT_V(2); BAR; WAIT_L(0); MMA(0, 0, At, B0); BAR;
;     LDB(B1, 1, 1); WAIT_V(0); BAR; WAIT_L(0); MMA(0, 1, At, B1); BAR;
;     LDA(At, 1, 1); BAR; WAIT_L(0); MMA(1, 0, At, B0); MMA(1, 1, At, B1); BAR; }
	s_nop 0
	ds_read_b128 v[80:83], v158 offset:16384
	ds_read_b128 v[84:87], v158 offset:17408
	ds_read_b128 v[184:187], v158 offset:18432
	ds_read_b128 v[188:191], v158 offset:19456
	ds_read_b128 v[192:195], v158 offset:20480
	ds_read_b128 v[196:199], v158 offset:21504
	ds_read_b128 v[200:203], v158 offset:22528
	ds_read_b128 v[204:207], v158 offset:23552
	s_waitcnt vmcnt(4)
	s_barrier
	s_waitcnt lgkmcnt(0)
	s_setprio 1
	s_waitcnt lgkmcnt(0)
	v_mfma_f32_16x16x32_bf16 v[44:47], v[160:163], v[192:195], v[44:47]
	v_mfma_f32_16x16x32_bf16 v[40:43], v[168:171], v[192:195], v[40:43]
	v_mfma_f32_16x16x32_bf16 v[60:63], v[160:163], v[80:83], v[60:63]
	v_mfma_f32_16x16x32_bf16 v[56:59], v[168:171], v[80:83], v[56:59]
	v_mfma_f32_16x16x32_bf16 v[52:55], v[160:163], v[184:187], v[52:55]
	v_mfma_f32_16x16x32_bf16 v[48:51], v[168:171], v[184:187], v[48:51]
	v_mfma_f32_16x16x32_bf16 v[44:47], v[164:167], v[196:199], v[44:47]
	v_mfma_f32_16x16x32_bf16 v[40:43], v[172:175], v[196:199], v[40:43]
	v_mfma_f32_16x16x32_bf16 v[36:39], v[160:163], v[200:203], v[36:39]
	v_mfma_f32_16x16x32_bf16 v[32:35], v[168:171], v[200:203], v[32:35]
	v_mfma_f32_16x16x32_bf16 v[220:223], v[164:167], v[84:87], v[60:63]
	v_mfma_f32_16x16x32_bf16 v[224:227], v[172:175], v[84:87], v[56:59]
	v_mfma_f32_16x16x32_bf16 v[228:231], v[164:167], v[188:191], v[52:55]
	v_mfma_f32_16x16x32_bf16 v[232:235], v[172:175], v[188:191], v[48:51]
	v_mfma_f32_16x16x32_bf16 v[160:163], v[164:167], v[204:207], v[36:39]
	v_mfma_f32_16x16x32_bf16 v[164:167], v[172:175], v[204:207], v[32:35]
	s_setprio 0
	s_setprio 1
	v_mfma_f32_16x16x32_bf16 v[28:31], v[96:99], v[80:83], v[28:31]
	v_mfma_f32_16x16x32_bf16 v[24:27], v[112:115], v[80:83], v[24:27]
	v_mfma_f32_16x16x32_bf16 v[12:15], v[96:99], v[192:195], v[12:15]
	v_mfma_f32_16x16x32_bf16 v[8:11], v[112:115], v[192:195], v[8:11]
	v_mfma_f32_16x16x32_bf16 v[28:31], v[100:103], v[84:87], v[28:31]
	v_mfma_f32_16x16x32_bf16 v[24:27], v[116:119], v[84:87], v[24:27]
	v_mfma_f32_16x16x32_bf16 v[20:23], v[96:99], v[184:187], v[20:23]
	v_mfma_f32_16x16x32_bf16 v[16:19], v[112:115], v[184:187], v[16:19]
	v_mfma_f32_16x16x32_bf16 v[12:15], v[100:103], v[196:199], v[12:15]
	v_mfma_f32_16x16x32_bf16 v[8:11], v[116:119], v[196:199], v[8:11]
	v_mfma_f32_16x16x32_bf16 v[4:7], v[96:99], v[200:203], v[4:7]
	v_mfma_f32_16x16x32_bf16 v[0:3], v[112:115], v[200:203], v[0:3]
	v_mfma_f32_16x16x32_bf16 v[168:171], v[100:103], v[188:191], v[20:23]
	v_mfma_f32_16x16x32_bf16 v[172:175], v[116:119], v[188:191], v[16:19]
	v_mfma_f32_16x16x32_bf16 v[184:187], v[100:103], v[204:207], v[4:7]
	v_mfma_f32_16x16x32_bf16 v[188:191], v[116:119], v[204:207], v[0:3]
	s_setprio 0
	s_barrier
	s_nop 1
	ds_read_b128 v[0:3], v145
	ds_read_b128 v[4:7], v146
	ds_read_b128 v[192:195], v147
	ds_read_b128 v[196:199], v148
	ds_read_b128 v[16:19], v158 offset:32768
	ds_read_b128 v[20:23], v158 offset:33792
	ds_read_b128 v[32:35], v158 offset:34816
	ds_read_b128 v[36:39], v158 offset:35840
	ds_read_b128 v[56:59], v158 offset:36864
	ds_read_b128 v[60:63], v158 offset:37888
	ds_read_b128 v[200:203], v158 offset:38912
	ds_read_b128 v[204:207], v158 offset:39936
	s_waitcnt vmcnt(2)
	s_barrier
	s_waitcnt lgkmcnt(0)
	s_setprio 1
	s_waitcnt lgkmcnt(0)
	v_mfma_f32_16x16x32_bf16 v[48:51], v[0:3], v[16:19], v[124:127]
	v_mfma_f32_16x16x32_bf16 v[112:115], v[4:7], v[20:23], v[48:51]
	v_mfma_f32_16x16x32_bf16 v[48:51], v[192:195], v[16:19], v[120:123]
	v_mfma_f32_16x16x32_bf16 v[116:119], v[196:199], v[20:23], v[48:51]
	v_mfma_f32_16x16x32_bf16 v[48:51], v[0:3], v[32:35], v[132:135]
	v_mfma_f32_16x16x32_bf16 v[96:99], v[4:7], v[36:39], v[48:51]
	v_mfma_f32_16x16x32_bf16 v[48:51], v[192:195], v[32:35], v[208:211]
	v_mfma_f32_16x16x32_bf16 v[100:103], v[196:199], v[36:39], v[48:51]
	v_mfma_f32_16x16x32_bf16 v[48:51], v[0:3], v[56:59], v[108:111]
	v_mfma_f32_16x16x32_bf16 v[80:83], v[4:7], v[60:63], v[48:51]
	v_mfma_f32_16x16x32_bf16 v[48:51], v[192:195], v[56:59], v[104:107]
	v_mfma_f32_16x16x32_bf16 v[84:87], v[196:199], v[60:63], v[48:51]
	v_mfma_f32_16x16x32_bf16 v[48:51], v[0:3], v[200:203], v[212:215]
	v_mfma_f32_16x16x32_bf16 v[52:55], v[192:195], v[200:203], v[216:219]
	v_mfma_f32_16x16x32_bf16 v[48:51], v[4:7], v[204:207], v[48:51]
	v_mfma_f32_16x16x32_bf16 v[52:55], v[196:199], v[204:207], v[52:55]
	s_setprio 0
	s_barrier
; #define LDA(dst, b, h) for (int m = 0; m < 4; ++m) for (int k = 0; k < 2; ++k) \
;     dst[m][k] = *reinterpret_cast<const bf16x8*>(aRd + (((b) * 2 + (h)) * G_HT * 2 + m * 2048 + k * 1024))
; #define LDB(dst, b, h) for (int n = 0; n < 2; ++n) for (int k = 0; k < 2; ++k) \
;     dst[n][k] = *reinterpret_cast<const bf16x8*>(bRd + (((b) * 2 + (h)) * G_HT * 2 + n * 2048 + k * 1024))
; #define MMA(ai, bj, At, Bx) do { __builtin_amdgcn_s_setprio(1); \
;     for (int m = 0; m < 4; ++m) for (int n = 0; n < 2; ++n) for (int k = 0; k < 2; ++k) \
;       acc[ai][bj][m][n] = __builtin_amdgcn_mfma_f32_16x16x32_bf16(Bx[n][k], At[m][k], acc[ai][bj][m][n], 0, 0, 0);     \
;     __builtin_amdgcn_s_setprio(0); } while (0)
; #define WAIT_V(n) asm volatile("s_waitcnt vmcnt(" #n ")" ::: "memory")
; #define WAIT_L(n) asm volatile("s_waitcnt lgkmcnt(" #n ")" ::: "memory")
; #define BAR __builtin_amdgcn_s_barrier()
; template <int EPI>
; __device__ __forceinline__ void gemm_tile(const bf16* __restrict__ A, int lda, const bf16* __restrict__ Bt, int K,
;                                           int brow, int bcol, const EpiArgs& ea, char* shmc, bool has_next, int nbrow, int nbcol, bool first_tile) {
;     ...
;   { LDB(B0, 1, 0); LDA(At, 1, 0); WAIT_V(2); BAR; WAIT_L(0); MMA(0, 0, At, B0); BAR;
;     LDB(B1, 1, 1); WAIT_V(0); BAR; WAIT_L(0); MMA(0, 1, At, B1); BAR;
;     LDA(At, 1, 1); BAR; WAIT_L(0); MMA(1, 0, At, B0); MMA(1, 1, At, B1); BAR; }
;   if (wr == 0) BAR;
;   if (has_next) gemm_prefetch(A, lda, Bt, K, nbrow, nbcol, shmc);
	ds_read_b128 v[132:135], v149
	ds_read_b128 v[208:211], v150
	ds_read_b128 v[212:215], v151
	ds_read_b128 v[216:219], v152
	s_waitcnt vmcnt(0)
	s_barrier
	s_waitcnt lgkmcnt(0)
	s_setprio 1
	s_waitcnt lgkmcnt(0)
	v_mfma_f32_16x16x32_bf16 v[92:95], v[132:135], v[16:19], v[92:95]
	v_mfma_f32_16x16x32_bf16 v[16:19], v[212:215], v[16:19], v[88:91]
	v_mfma_f32_16x16x32_bf16 v[124:127], v[216:219], v[20:23], v[16:19]
	v_mfma_f32_16x16x32_bf16 v[16:19], v[132:135], v[32:35], v[176:179]
	v_mfma_f32_16x16x32_bf16 v[104:107], v[208:211], v[36:39], v[16:19]
	v_mfma_f32_16x16x32_bf16 v[16:19], v[212:215], v[32:35], v[180:183]
	v_mfma_f32_16x16x32_bf16 v[108:111], v[216:219], v[36:39], v[16:19]
	v_mfma_f32_16x16x32_bf16 v[16:19], v[132:135], v[56:59], v[76:79]
	v_mfma_f32_16x16x32_bf16 v[88:91], v[208:211], v[60:63], v[16:19]
	v_mfma_f32_16x16x32_bf16 v[16:19], v[212:215], v[56:59], v[72:75]
	v_mfma_f32_16x16x32_bf16 v[120:123], v[208:211], v[20:23], v[92:95]
	v_mfma_f32_16x16x32_bf16 v[92:95], v[216:219], v[60:63], v[16:19]
	v_mfma_f32_16x16x32_bf16 v[16:19], v[132:135], v[200:203], v[68:71]
	v_mfma_f32_16x16x32_bf16 v[56:59], v[208:211], v[204:207], v[16:19]
	v_mfma_f32_16x16x32_bf16 v[16:19], v[212:215], v[200:203], v[64:67]
	v_mfma_f32_16x16x32_bf16 v[60:63], v[216:219], v[204:207], v[16:19]
	s_setprio 0
	s_barrier
	ds_read_b128 v[76:79], v158 offset:49152
	ds_read_b128 v[176:179], v158 offset:50176
	ds_read_b128 v[180:183], v158 offset:51200
	ds_read_b128 v[200:203], v158 offset:52224
	ds_read_b128 v[204:207], v158 offset:53248
	ds_read_b128 v[236:239], v158 offset:54272
	ds_read_b128 v[240:243], v158 offset:55296
	ds_read_b128 v[244:247], v158 offset:56320
	s_barrier
	s_waitcnt lgkmcnt(0)
	s_setprio 1
	s_waitcnt lgkmcnt(0)
	v_mfma_f32_16x16x32_bf16 v[16:19], v[0:3], v[76:79], v[220:223]
	v_mfma_f32_16x16x32_bf16 v[64:67], v[4:7], v[176:179], v[16:19]
	v_mfma_f32_16x16x32_bf16 v[16:19], v[192:195], v[76:79], v[224:227]
	v_mfma_f32_16x16x32_bf16 v[68:71], v[196:199], v[176:179], v[16:19]
	v_mfma_f32_16x16x32_bf16 v[16:19], v[0:3], v[180:183], v[228:231]
	v_mfma_f32_16x16x32_bf16 v[32:35], v[4:7], v[200:203], v[16:19]
	v_mfma_f32_16x16x32_bf16 v[16:19], v[192:195], v[180:183], v[232:235]
	v_mfma_f32_16x16x32_bf16 v[36:39], v[196:199], v[200:203], v[16:19]
	v_mfma_f32_16x16x32_bf16 v[16:19], v[0:3], v[204:207], v[44:47]
	v_mfma_f32_16x16x32_bf16 v[0:3], v[0:3], v[240:243], v[160:163]
	v_mfma_f32_16x16x32_bf16 v[16:19], v[4:7], v[236:239], v[16:19]
	v_mfma_f32_16x16x32_bf16 v[20:23], v[192:195], v[204:207], v[40:43]
	v_mfma_f32_16x16x32_bf16 v[0:3], v[4:7], v[244:247], v[0:3]
	v_mfma_f32_16x16x32_bf16 v[4:7], v[192:195], v[240:243], v[164:167]
	v_mfma_f32_16x16x32_bf16 v[20:23], v[196:199], v[236:239], v[20:23]
	v_mfma_f32_16x16x32_bf16 v[4:7], v[196:199], v[244:247], v[4:7]
	s_setprio 0
	s_setprio 1
	v_mfma_f32_16x16x32_bf16 v[24:27], v[212:215], v[76:79], v[24:27]
	v_mfma_f32_16x16x32_bf16 v[28:31], v[132:135], v[76:79], v[28:31]
	v_mfma_f32_16x16x32_bf16 v[76:79], v[216:219], v[176:179], v[24:27]
	v_mfma_f32_16x16x32_bf16 v[24:27], v[132:135], v[180:183], v[168:171]
	v_mfma_f32_16x16x32_bf16 v[40:43], v[208:211], v[200:203], v[24:27]
	v_mfma_f32_16x16x32_bf16 v[24:27], v[212:215], v[180:183], v[172:175]
	v_mfma_f32_16x16x32_bf16 v[12:15], v[132:135], v[204:207], v[12:15]
	v_mfma_f32_16x16x32_bf16 v[8:11], v[212:215], v[204:207], v[8:11]
	v_mfma_f32_16x16x32_bf16 v[72:75], v[208:211], v[176:179], v[28:31]
	v_mfma_f32_16x16x32_bf16 v[44:47], v[216:219], v[200:203], v[24:27]
	v_mfma_f32_16x16x32_bf16 v[24:27], v[208:211], v[236:239], v[12:15]
	v_mfma_f32_16x16x32_bf16 v[28:31], v[216:219], v[236:239], v[8:11]
	v_mfma_f32_16x16x32_bf16 v[8:11], v[132:135], v[240:243], v[184:187]
	v_mfma_f32_16x16x32_bf16 v[12:15], v[212:215], v[240:243], v[188:191]
	v_mfma_f32_16x16x32_bf16 v[8:11], v[208:211], v[244:247], v[8:11]
	v_mfma_f32_16x16x32_bf16 v[12:15], v[216:219], v[244:247], v[12:15]
	s_setprio 0
	s_barrier
	s_and_saveexec_b64 s[18:19], s[4:5]
	s_cbranch_execz .LBB0_294
	s_barrier

; #define STA(b, h, half, kt) STAGE(((b) * 2 + (h)) * G_HT * 2, pA, ((size_t)(half) * G_HALF * lda + (size_t)(kt) * G_BK) * 2, lda)
; #define STB(b, h, half, kt) STAGE((4 + (b) * 2 + (h)) * G_HT * 2, pB, ((size_t)(half) * G_HALF * K + (size_t)(kt) * G_BK) * 2, K)
; #define LDA(dst, b, h) for (int m = 0; m < 4; ++m) for (int k = 0; k < 2; ++k) \
;     dst[m][k] = *reinterpret_cast<const bf16x8*>(aRd + (((b) * 2 + (h)) * G_HT * 2 + m * 2048 + k * 1024))
; #define LDB(dst, b, h) for (int n = 0; n < 2; ++n) for (int k = 0; k < 2; ++k) \
;     dst[n][k] = *reinterpret_cast<const bf16x8*>(bRd + (((b) * 2 + (h)) * G_HT * 2 + n * 2048 + k * 1024))
; #define MMA(ai, bj, At, Bx) do { __builtin_amdgcn_s_setprio(1); \
;     for (int m = 0; m < 4; ++m) for (int n = 0; n < 2; ++n) for (int k = 0; k < 2; ++k) \
;       acc[ai][bj][m][n] = __builtin_amdgcn_mfma_f32_16x16x32_bf16(Bx[n][k], At[m][k], acc[ai][bj][m][n], 0, 0, 0);     \
;     __builtin_amdgcn_s_setprio(0); } while (0)
; #define WAIT_V(n) asm volatile("s_waitcnt vmcnt(" #n ")" ::: "memory")
; #define WAIT_L(n) asm volatile("s_waitcnt lgkmcnt(" #n ")" ::: "memory")
; #define BAR __builtin_amdgcn_s_barrier()
; #define SCHED __builtin_amdgcn_sched_barrier(0)
; template <int EPI>
; __device__ __forceinline__ void gemm_tile(const bf16* __restrict__ A, int lda, const bf16* __restrict__ Bt, int K,
;                                           int brow, int bcol, const EpiArgs& ea, char* shmc, bool has_next, int nbrow, int nbcol, bool first_tile) {
;     ...
;   for (int t = 0; t < nt - 2; t += 2) {
;     LDB(B0, 0, 0); SCHED; LDA(At, 0, 0); STA(1, 1, 1, t + 1);
;     WAIT_L(8); BAR; WAIT_L(0); MMA(0, 0, At, B0); BAR; SCHED;
;     LDB(B1, 0, 1); STB(0, 0, 0, t + 2);
;     BAR; WAIT_L(0); MMA(0, 1, At, B1); BAR;
;     LDA(At, 0, 1); STA(0, 0, 0, t + 2);
;     BAR; WAIT_L(0); MMA(1, 0, At, B0); BAR; SCHED;
;     STB(0, 1, 1, t + 2);
;     WAIT_V(6); BAR; MMA(1, 1, At, B1); BAR;
.LBB0_310:
	ds_read_b128 v[160:163], v138
	ds_read_b128 v[164:167], v139
	ds_read_b128 v[168:171], v140
	ds_read_b128 v[172:175], v141
	s_add_u32 s84, s30, 0xffffff80
	s_addc_u32 s85, s31, -1
	s_mov_b32 m0, s81
	ds_read_b128 v[176:179], v158
	ds_read_b128 v[180:183], v158 offset:1024
	ds_read_b128 v[184:187], v158 offset:2048
	ds_read_b128 v[188:191], v158 offset:3072
	ds_read_b128 v[192:195], v158 offset:4096
	ds_read_b128 v[196:199], v158 offset:5120
	ds_read_b128 v[200:203], v158 offset:6144
	ds_read_b128 v[204:207], v158 offset:7168
	v_lshl_add_u64 v[208:209], v[134:135], 0, s[84:85]
	global_load_lds_dwordx4 v[208:209], off
	s_mov_b32 m0, s71
	v_lshl_add_u64 v[208:209], v[208:209], 0, s[8:9]
	global_load_lds_dwordx4 v[208:209], off
	s_waitcnt lgkmcnt(8)
	s_barrier
	s_waitcnt lgkmcnt(0)
	s_setprio 1
	v_mfma_f32_16x16x32_bf16 v[124:127], v[160:163], v[176:179], v[124:127]
	v_mfma_f32_16x16x32_bf16 v[120:123], v[168:171], v[176:179], v[120:123]
	v_mfma_f32_16x16x32_bf16 v[116:119], v[160:163], v[184:187], v[116:119]
	v_mfma_f32_16x16x32_bf16 v[112:115], v[168:171], v[184:187], v[112:115]
	v_mfma_f32_16x16x32_bf16 v[108:111], v[160:163], v[192:195], v[108:111]
	v_mfma_f32_16x16x32_bf16 v[104:107], v[168:171], v[192:195], v[104:107]
	v_mfma_f32_16x16x32_bf16 v[100:103], v[160:163], v[200:203], v[100:103]
	v_mfma_f32_16x16x32_bf16 v[96:99], v[168:171], v[200:203], v[96:99]
	v_mfma_f32_16x16x32_bf16 v[124:127], v[164:167], v[180:183], v[124:127]
	v_mfma_f32_16x16x32_bf16 v[120:123], v[172:175], v[180:183], v[120:123]
	v_mfma_f32_16x16x32_bf16 v[116:119], v[164:167], v[188:191], v[116:119]
	v_mfma_f32_16x16x32_bf16 v[112:115], v[172:175], v[188:191], v[112:115]
	v_mfma_f32_16x16x32_bf16 v[108:111], v[164:167], v[196:199], v[108:111]
	v_mfma_f32_16x16x32_bf16 v[104:107], v[172:175], v[196:199], v[104:107]
	v_mfma_f32_16x16x32_bf16 v[100:103], v[164:167], v[204:207], v[100:103]
	v_mfma_f32_16x16x32_bf16 v[96:99], v[172:175], v[204:207], v[96:99]
	s_setprio 0
	s_barrier
	s_add_u32 s84, s30, 0xfffa0000
	s_addc_u32 s85, s31, -1
	s_mov_b32 m0, s74
	ds_read_b128 v[208:211], v142
	ds_read_b128 v[212:215], v143
	ds_read_b128 v[216:219], v144
	ds_read_b128 v[220:223], v145
	v_lshl_add_u64 v[224:225], v[136:137], 0, s[84:85]
	global_load_lds_dwordx4 v[224:225], off
	s_mov_b32 m0, s75
	v_lshl_add_u64 v[224:225], v[224:225], 0, s[6:7]
	global_load_lds_dwordx4 v[224:225], off
	s_barrier
	s_waitcnt lgkmcnt(0)
	s_setprio 1
	v_mfma_f32_16x16x32_bf16 v[92:95], v[208:211], v[176:179], v[92:95]
	v_mfma_f32_16x16x32_bf16 v[88:91], v[216:219], v[176:179], v[88:91]
	v_mfma_f32_16x16x32_bf16 v[84:87], v[208:211], v[184:187], v[84:87]
	v_mfma_f32_16x16x32_bf16 v[80:83], v[216:219], v[184:187], v[80:83]
	v_mfma_f32_16x16x32_bf16 v[76:79], v[208:211], v[192:195], v[76:79]
	v_mfma_f32_16x16x32_bf16 v[72:75], v[216:219], v[192:195], v[72:75]
	v_mfma_f32_16x16x32_bf16 v[68:71], v[208:211], v[200:203], v[68:71]
	v_mfma_f32_16x16x32_bf16 v[64:67], v[216:219], v[200:203], v[64:67]
	v_mfma_f32_16x16x32_bf16 v[92:95], v[212:215], v[180:183], v[92:95]
	v_mfma_f32_16x16x32_bf16 v[88:91], v[220:223], v[180:183], v[88:91]
	v_mfma_f32_16x16x32_bf16 v[84:87], v[212:215], v[188:191], v[84:87]
	v_mfma_f32_16x16x32_bf16 v[80:83], v[220:223], v[188:191], v[80:83]
	v_mfma_f32_16x16x32_bf16 v[76:79], v[212:215], v[196:199], v[76:79]
	v_mfma_f32_16x16x32_bf16 v[72:75], v[220:223], v[196:199], v[72:75]
	v_mfma_f32_16x16x32_bf16 v[68:71], v[212:215], v[204:207], v[68:71]
	v_mfma_f32_16x16x32_bf16 v[64:67], v[220:223], v[204:207], v[64:67]
	s_setprio 0
	s_mov_b32 m0, s29
	s_barrier
	ds_read_b128 v[176:179], v158 offset:16384
	ds_read_b128 v[180:183], v158 offset:17408
	ds_read_b128 v[184:187], v158 offset:18432
	ds_read_b128 v[188:191], v158 offset:19456
	ds_read_b128 v[192:195], v158 offset:20480
	ds_read_b128 v[196:199], v158 offset:21504
	ds_read_b128 v[200:203], v158 offset:22528
	ds_read_b128 v[204:207], v158 offset:23552
	v_lshl_add_u64 v[224:225], v[134:135], 0, s[84:85]
	global_load_lds_dwordx4 v[224:225], off
	s_mov_b32 m0, s82
	v_lshl_add_u64 v[224:225], v[224:225], 0, s[8:9]
	global_load_lds_dwordx4 v[224:225], off
	s_barrier
	s_waitcnt lgkmcnt(0)
	s_setprio 1
	v_mfma_f32_16x16x32_bf16 v[60:63], v[160:163], v[176:179], v[60:63]
	v_mfma_f32_16x16x32_bf16 v[56:59], v[168:171], v[176:179], v[56:59]
	v_mfma_f32_16x16x32_bf16 v[52:55], v[160:163], v[184:187], v[52:55]
	v_mfma_f32_16x16x32_bf16 v[48:51], v[168:171], v[184:187], v[48:51]
	v_mfma_f32_16x16x32_bf16 v[44:47], v[160:163], v[192:195], v[44:47]
	v_mfma_f32_16x16x32_bf16 v[40:43], v[168:171], v[192:195], v[40:43]
	v_mfma_f32_16x16x32_bf16 v[36:39], v[160:163], v[200:203], v[36:39]
	v_mfma_f32_16x16x32_bf16 v[32:35], v[168:171], v[200:203], v[32:35]
	v_mfma_f32_16x16x32_bf16 v[60:63], v[164:167], v[180:183], v[60:63]
	v_mfma_f32_16x16x32_bf16 v[56:59], v[172:175], v[180:183], v[56:59]
	v_mfma_f32_16x16x32_bf16 v[52:55], v[164:167], v[188:191], v[52:55]
	v_mfma_f32_16x16x32_bf16 v[48:51], v[172:175], v[188:191], v[48:51]
	v_mfma_f32_16x16x32_bf16 v[44:47], v[164:167], v[196:199], v[44:47]
	v_mfma_f32_16x16x32_bf16 v[40:43], v[172:175], v[196:199], v[40:43]
	v_mfma_f32_16x16x32_bf16 v[36:39], v[164:167], v[204:207], v[36:39]
	v_mfma_f32_16x16x32_bf16 v[32:35], v[172:175], v[204:207], v[32:35]
	s_setprio 0
	s_barrier
	s_add_u32 s84, s30, 0xfffc0000
	s_addc_u32 s85, s31, -1
	s_mov_b32 m0, s77
	v_lshl_add_u64 v[160:161], v[136:137], 0, s[84:85]
	global_load_lds_dwordx4 v[160:161], off
	s_mov_b32 m0, s79
	v_lshl_add_u64 v[160:161], v[160:161], 0, s[6:7]
	global_load_lds_dwordx4 v[160:161], off
	s_waitcnt vmcnt(6)
	s_barrier
; #define STA(b, h, half, kt) STAGE(((b) * 2 + (h)) * G_HT * 2, pA, ((size_t)(half) * G_HALF * lda + (size_t)(kt) * G_BK) * 2, lda)
; #define STB(b, h, half, kt) STAGE((4 + (b) * 2 + (h)) * G_HT * 2, pB, ((size_t)(half) * G_HALF * K + (size_t)(kt) * G_BK) * 2, K)
; #define LDA(dst, b, h) for (int m = 0; m < 4; ++m) for (int k = 0; k < 2; ++k) \
;     dst[m][k] = *reinterpret_cast<const bf16x8*>(aRd + (((b) * 2 + (h)) * G_HT * 2 + m * 2048 + k * 1024))
; #define LDB(dst, b, h) for (int n = 0; n < 2; ++n) for (int k = 0; k < 2; ++k) \
;     dst[n][k] = *reinterpret_cast<const bf16x8*>(bRd + (((b) * 2 + (h)) * G_HT * 2 + n * 2048 + k * 1024))
; #define MMA(ai, bj, At, Bx) do { __builtin_amdgcn_s_setprio(1); \
;     for (int m = 0; m < 4; ++m) for (int n = 0; n < 2; ++n) for (int k = 0; k < 2; ++k) \
;       acc[ai][bj][m][n] = __builtin_amdgcn_mfma_f32_16x16x32_bf16(Bx[n][k], At[m][k], acc[ai][bj][m][n], 0, 0, 0);     \
;     __builtin_amdgcn_s_setprio(0); } while (0)
; #define WAIT_V(n) asm volatile("s_waitcnt vmcnt(" #n ")" ::: "memory")
; #define WAIT_L(n) asm volatile("s_waitcnt lgkmcnt(" #n ")" ::: "memory")
; #define BAR __builtin_amdgcn_s_barrier()
; #define SCHED __builtin_amdgcn_sched_barrier(0)
; template <int EPI>
; __device__ __forceinline__ void gemm_tile(const bf16* __restrict__ A, int lda, const bf16* __restrict__ Bt, int K,
;                                           int brow, int bcol, const EpiArgs& ea, char* shmc, bool has_next, int nbrow, int nbcol, bool first_tile) {
;     ...
;     WAIT_V(6); BAR; MMA(1, 1, At, B1); BAR;
;     LDB(B0, 1, 0); SCHED; LDA(At, 1, 0); STA(0, 1, 1, t + 2);
;     WAIT_L(8); BAR; WAIT_L(0); MMA(0, 0, At, B0); BAR; SCHED;
;     LDB(B1, 1, 1); STB(1, 0, 0, t + 3);
;     BAR; WAIT_L(0); MMA(0, 1, At, B1); BAR;
;     LDA(At, 1, 1); STA(1, 0, 0, t + 3);
;     BAR; WAIT_L(0); MMA(1, 0, At, B0); BAR; SCHED;
	s_setprio 1
	v_mfma_f32_16x16x32_bf16 v[28:31], v[208:211], v[176:179], v[28:31]
	v_mfma_f32_16x16x32_bf16 v[24:27], v[216:219], v[176:179], v[24:27]
	v_mfma_f32_16x16x32_bf16 v[20:23], v[208:211], v[184:187], v[20:23]
	v_mfma_f32_16x16x32_bf16 v[16:19], v[216:219], v[184:187], v[16:19]
	v_mfma_f32_16x16x32_bf16 v[12:15], v[208:211], v[192:195], v[12:15]
	v_mfma_f32_16x16x32_bf16 v[8:11], v[216:219], v[192:195], v[8:11]
	v_mfma_f32_16x16x32_bf16 v[4:7], v[208:211], v[200:203], v[4:7]
	v_mfma_f32_16x16x32_bf16 v[0:3], v[216:219], v[200:203], v[0:3]
	v_mfma_f32_16x16x32_bf16 v[28:31], v[212:215], v[180:183], v[28:31]
	v_mfma_f32_16x16x32_bf16 v[24:27], v[220:223], v[180:183], v[24:27]
	v_mfma_f32_16x16x32_bf16 v[20:23], v[212:215], v[188:191], v[20:23]
	v_mfma_f32_16x16x32_bf16 v[16:19], v[220:223], v[188:191], v[16:19]
	v_mfma_f32_16x16x32_bf16 v[12:15], v[212:215], v[196:199], v[12:15]
	v_mfma_f32_16x16x32_bf16 v[8:11], v[220:223], v[196:199], v[8:11]
	v_mfma_f32_16x16x32_bf16 v[4:7], v[212:215], v[204:207], v[4:7]
	v_mfma_f32_16x16x32_bf16 v[0:3], v[220:223], v[204:207], v[0:3]
	s_setprio 0
	s_barrier
	ds_read_b128 v[160:163], v146
	ds_read_b128 v[164:167], v147
	ds_read_b128 v[168:171], v148
	ds_read_b128 v[172:175], v149
	s_mov_b32 m0, s83
	ds_read_b128 v[176:179], v158 offset:32768
	ds_read_b128 v[180:183], v158 offset:33792
	ds_read_b128 v[184:187], v158 offset:34816
	ds_read_b128 v[188:191], v158 offset:35840
	ds_read_b128 v[192:195], v158 offset:36864
	ds_read_b128 v[196:199], v158 offset:37888
	ds_read_b128 v[200:203], v158 offset:38912
	ds_read_b128 v[204:207], v158 offset:39936
	v_lshl_add_u64 v[208:209], v[134:135], 0, s[30:31]
	global_load_lds_dwordx4 v[208:209], off
	s_add_i32 m0, s29, 0x6000
	v_lshl_add_u64 v[208:209], v[208:209], 0, s[8:9]
	global_load_lds_dwordx4 v[208:209], off
	s_waitcnt lgkmcnt(8)
	s_barrier
	s_waitcnt lgkmcnt(0)
	s_setprio 1
	v_mfma_f32_16x16x32_bf16 v[124:127], v[160:163], v[176:179], v[124:127]
	v_mfma_f32_16x16x32_bf16 v[120:123], v[168:171], v[176:179], v[120:123]
	v_mfma_f32_16x16x32_bf16 v[116:119], v[160:163], v[184:187], v[116:119]
	v_mfma_f32_16x16x32_bf16 v[112:115], v[168:171], v[184:187], v[112:115]
	v_mfma_f32_16x16x32_bf16 v[108:111], v[160:163], v[192:195], v[108:111]
	v_mfma_f32_16x16x32_bf16 v[104:107], v[168:171], v[192:195], v[104:107]
	v_mfma_f32_16x16x32_bf16 v[100:103], v[160:163], v[200:203], v[100:103]
	v_mfma_f32_16x16x32_bf16 v[96:99], v[168:171], v[200:203], v[96:99]
	v_mfma_f32_16x16x32_bf16 v[124:127], v[164:167], v[180:183], v[124:127]
	v_mfma_f32_16x16x32_bf16 v[120:123], v[172:175], v[180:183], v[120:123]
	v_mfma_f32_16x16x32_bf16 v[116:119], v[164:167], v[188:191], v[116:119]
	v_mfma_f32_16x16x32_bf16 v[112:115], v[172:175], v[188:191], v[112:115]
	v_mfma_f32_16x16x32_bf16 v[108:111], v[164:167], v[196:199], v[108:111]
	v_mfma_f32_16x16x32_bf16 v[104:107], v[172:175], v[196:199], v[104:107]
	v_mfma_f32_16x16x32_bf16 v[100:103], v[164:167], v[204:207], v[100:103]
	v_mfma_f32_16x16x32_bf16 v[96:99], v[172:175], v[204:207], v[96:99]
	s_setprio 0
	s_barrier
	s_add_u32 s84, s30, 0xfffa0080
	s_addc_u32 s85, s31, -1
	s_mov_b32 m0, s67
	ds_read_b128 v[208:211], v150
	ds_read_b128 v[212:215], v151
	ds_read_b128 v[216:219], v152
	ds_read_b128 v[220:223], v153
	v_lshl_add_u64 v[224:225], v[136:137], 0, s[84:85]
	global_load_lds_dwordx4 v[224:225], off
	s_mov_b32 m0, s68
	v_lshl_add_u64 v[224:225], v[224:225], 0, s[6:7]
	global_load_lds_dwordx4 v[224:225], off
	s_barrier
	s_waitcnt lgkmcnt(0)
	s_setprio 1
	v_mfma_f32_16x16x32_bf16 v[92:95], v[208:211], v[176:179], v[92:95]
	v_mfma_f32_16x16x32_bf16 v[88:91], v[216:219], v[176:179], v[88:91]
	v_mfma_f32_16x16x32_bf16 v[84:87], v[208:211], v[184:187], v[84:87]
	v_mfma_f32_16x16x32_bf16 v[80:83], v[216:219], v[184:187], v[80:83]
	v_mfma_f32_16x16x32_bf16 v[76:79], v[208:211], v[192:195], v[76:79]
	v_mfma_f32_16x16x32_bf16 v[72:75], v[216:219], v[192:195], v[72:75]
	v_mfma_f32_16x16x32_bf16 v[68:71], v[208:211], v[200:203], v[68:71]
	v_mfma_f32_16x16x32_bf16 v[64:67], v[216:219], v[200:203], v[64:67]
	v_mfma_f32_16x16x32_bf16 v[92:95], v[212:215], v[180:183], v[92:95]
	v_mfma_f32_16x16x32_bf16 v[88:91], v[220:223], v[180:183], v[88:91]
	v_mfma_f32_16x16x32_bf16 v[84:87], v[212:215], v[188:191], v[84:87]
	v_mfma_f32_16x16x32_bf16 v[80:83], v[220:223], v[188:191], v[80:83]
	v_mfma_f32_16x16x32_bf16 v[76:79], v[212:215], v[196:199], v[76:79]
	v_mfma_f32_16x16x32_bf16 v[72:75], v[220:223], v[196:199], v[72:75]
	v_mfma_f32_16x16x32_bf16 v[68:71], v[212:215], v[204:207], v[68:71]
	v_mfma_f32_16x16x32_bf16 v[64:67], v[220:223], v[204:207], v[64:67]
	s_setprio 0
	s_mov_b32 m0, s69
	s_barrier
	ds_read_b128 v[176:179], v158 offset:49152
	ds_read_b128 v[180:183], v158 offset:50176
	ds_read_b128 v[184:187], v158 offset:51200
	ds_read_b128 v[188:191], v158 offset:52224
	ds_read_b128 v[192:195], v158 offset:53248
	ds_read_b128 v[196:199], v158 offset:54272
	ds_read_b128 v[200:203], v158 offset:55296
	ds_read_b128 v[204:207], v158 offset:56320
	v_lshl_add_u64 v[224:225], v[134:135], 0, s[84:85]
	global_load_lds_dwordx4 v[224:225], off
	s_mov_b32 m0, s70
	v_lshl_add_u64 v[224:225], v[224:225], 0, s[8:9]
	global_load_lds_dwordx4 v[224:225], off
	s_barrier
; #define STA(b, h, half, kt) STAGE(((b) * 2 + (h)) * G_HT * 2, pA, ((size_t)(half) * G_HALF * lda + (size_t)(kt) * G_BK) * 2, lda)
; #define STB(b, h, half, kt) STAGE((4 + (b) * 2 + (h)) * G_HT * 2, pB, ((size_t)(half) * G_HALF * K + (size_t)(kt) * G_BK) * 2, K)
; #define LDA(dst, b, h) for (int m = 0; m < 4; ++m) for (int k = 0; k < 2; ++k) \
;     dst[m][k] = *reinterpret_cast<const bf16x8*>(aRd + (((b) * 2 + (h)) * G_HT * 2 + m * 2048 + k * 1024))
; #define LDB(dst, b, h) for (int n = 0; n < 2; ++n) for (int k = 0; k < 2; ++k) \
;     dst[n][k] = *reinterpret_cast<const bf16x8*>(bRd + (((b) * 2 + (h)) * G_HT * 2 + n * 2048 + k * 1024))
; #define MMA(ai, bj, At, Bx) do { __builtin_amdgcn_s_setprio(1); \
;     for (int m = 0; m < 4; ++m) for (int n = 0; n < 2; ++n) for (int k = 0; k < 2; ++k) \
;       acc[ai][bj][m][n] = __builtin_amdgcn_mfma_f32_16x16x32_bf16(Bx[n][k], At[m][k], acc[ai][bj][m][n], 0, 0, 0);     \
;     __builtin_amdgcn_s_setprio(0); } while (0)
; #define WAIT_V(n) asm volatile("s_waitcnt vmcnt(" #n ")" ::: "memory")
; #define WAIT_L(n) asm volatile("s_waitcnt lgkmcnt(" #n ")" ::: "memory")
; #define BAR __builtin_amdgcn_s_barrier()
; #define SCHED __builtin_amdgcn_sched_barrier(0)
; template <int EPI>
; __device__ __forceinline__ void gemm_tile(const bf16* __restrict__ A, int lda, const bf16* __restrict__ Bt, int K,
;                                           int brow, int bcol, const EpiArgs& ea, char* shmc, bool has_next, int nbrow, int nbcol, bool first_tile) {
;     ...
;     BAR; WAIT_L(0); MMA(1, 0, At, B0); BAR; SCHED;
;     STB(1, 1, 1, t + 3);
;     WAIT_V(6); BAR; MMA(1, 1, At, B1); BAR;
;   }
;   { LDB(B0, 0, 0); LDA(At, 0, 0); STA(1, 1, 1, nt - 1);
;     BAR; WAIT_L(0); MMA(0, 0, At, B0); BAR;
;     LDB(B1, 0, 1); BAR; WAIT_L(0); MMA(0, 1, At, B1); BAR;
;     LDA(At, 0, 1); WAIT_V(4); BAR; WAIT_L(0); MMA(1, 0, At, B0); MMA(1, 1, At, B1); BAR; }
	s_waitcnt lgkmcnt(0)
	s_setprio 1
	v_mfma_f32_16x16x32_bf16 v[60:63], v[160:163], v[176:179], v[60:63]
	v_mfma_f32_16x16x32_bf16 v[56:59], v[168:171], v[176:179], v[56:59]
	v_mfma_f32_16x16x32_bf16 v[52:55], v[160:163], v[184:187], v[52:55]
	v_mfma_f32_16x16x32_bf16 v[48:51], v[168:171], v[184:187], v[48:51]
	v_mfma_f32_16x16x32_bf16 v[44:47], v[160:163], v[192:195], v[44:47]
	v_mfma_f32_16x16x32_bf16 v[40:43], v[168:171], v[192:195], v[40:43]
	v_mfma_f32_16x16x32_bf16 v[36:39], v[160:163], v[200:203], v[36:39]
	v_mfma_f32_16x16x32_bf16 v[32:35], v[168:171], v[200:203], v[32:35]
	v_mfma_f32_16x16x32_bf16 v[60:63], v[164:167], v[180:183], v[60:63]
	v_mfma_f32_16x16x32_bf16 v[56:59], v[172:175], v[180:183], v[56:59]
	v_mfma_f32_16x16x32_bf16 v[52:55], v[164:167], v[188:191], v[52:55]
	v_mfma_f32_16x16x32_bf16 v[48:51], v[172:175], v[188:191], v[48:51]
	v_mfma_f32_16x16x32_bf16 v[44:47], v[164:167], v[196:199], v[44:47]
	v_mfma_f32_16x16x32_bf16 v[40:43], v[172:175], v[196:199], v[40:43]
	v_mfma_f32_16x16x32_bf16 v[36:39], v[164:167], v[204:207], v[36:39]
	v_mfma_f32_16x16x32_bf16 v[32:35], v[172:175], v[204:207], v[32:35]
	s_setprio 0
	s_barrier
	s_add_u32 s84, s30, 0xfffc0080
	s_addc_u32 s85, s31, -1
	s_mov_b32 m0, s72
	v_lshl_add_u64 v[160:161], v[136:137], 0, s[84:85]
	global_load_lds_dwordx4 v[160:161], off
	s_mov_b32 m0, s73
	v_lshl_add_u64 v[160:161], v[160:161], 0, s[6:7]
	global_load_lds_dwordx4 v[160:161], off
	s_waitcnt vmcnt(6)
	s_barrier
	s_setprio 1
	v_mfma_f32_16x16x32_bf16 v[28:31], v[208:211], v[176:179], v[28:31]
	v_mfma_f32_16x16x32_bf16 v[24:27], v[216:219], v[176:179], v[24:27]
	v_mfma_f32_16x16x32_bf16 v[20:23], v[208:211], v[184:187], v[20:23]
	v_mfma_f32_16x16x32_bf16 v[16:19], v[216:219], v[184:187], v[16:19]
	v_mfma_f32_16x16x32_bf16 v[12:15], v[208:211], v[192:195], v[12:15]
	v_mfma_f32_16x16x32_bf16 v[8:11], v[216:219], v[192:195], v[8:11]
	v_mfma_f32_16x16x32_bf16 v[4:7], v[208:211], v[200:203], v[4:7]
	v_mfma_f32_16x16x32_bf16 v[0:3], v[216:219], v[200:203], v[0:3]
	v_mfma_f32_16x16x32_bf16 v[28:31], v[212:215], v[180:183], v[28:31]
	v_mfma_f32_16x16x32_bf16 v[24:27], v[220:223], v[180:183], v[24:27]
	v_mfma_f32_16x16x32_bf16 v[20:23], v[212:215], v[188:191], v[20:23]
	v_mfma_f32_16x16x32_bf16 v[16:19], v[220:223], v[188:191], v[16:19]
	v_mfma_f32_16x16x32_bf16 v[12:15], v[212:215], v[196:199], v[12:15]
	v_mfma_f32_16x16x32_bf16 v[8:11], v[220:223], v[196:199], v[8:11]
	v_mfma_f32_16x16x32_bf16 v[4:7], v[212:215], v[204:207], v[4:7]
	v_mfma_f32_16x16x32_bf16 v[0:3], v[220:223], v[204:207], v[0:3]
	s_setprio 0
	s_add_i32 s80, s80, 2
	s_add_u32 s30, s30, 0x100
	s_addc_u32 s31, s31, 0
	s_cmp_lt_u32 s80, 4
	s_barrier
	s_cbranch_scc1 .LBB0_310
	s_mov_b64 s[30:31], 0x60380
	s_mov_b32 m0, s81
	ds_read_b128 v[160:163], v138
	ds_read_b128 v[164:167], v139
	ds_read_b128 v[168:171], v140
	ds_read_b128 v[172:175], v141
	ds_read_b128 v[176:179], v158
	ds_read_b128 v[180:183], v158 offset:1024
	ds_read_b128 v[184:187], v158 offset:2048
	ds_read_b128 v[188:191], v158 offset:3072
	ds_read_b128 v[192:195], v158 offset:4096
	ds_read_b128 v[196:199], v158 offset:5120
	ds_read_b128 v[200:203], v158 offset:6144
	ds_read_b128 v[204:207], v158 offset:7168
	s_nop 0
	v_lshl_add_u64 v[134:135], v[134:135], 0, s[30:31]
	global_load_lds_dwordx4 v[134:135], off
	v_lshl_add_u64 v[134:135], v[134:135], 0, s[8:9]
	s_mov_b32 m0, s71
	s_nop 0
	global_load_lds_dwordx4 v[134:135], off
	s_barrier
	s_waitcnt lgkmcnt(0)
	s_setprio 1
	s_waitcnt lgkmcnt(0)
	v_mfma_f32_16x16x32_bf16 v[124:127], v[160:163], v[176:179], v[124:127]
	v_mfma_f32_16x16x32_bf16 v[120:123], v[168:171], v[176:179], v[120:123]
	v_mfma_f32_16x16x32_bf16 v[108:111], v[160:163], v[192:195], v[108:111]
	v_mfma_f32_16x16x32_bf16 v[104:107], v[168:171], v[192:195], v[104:107]
	v_mfma_f32_16x16x32_bf16 v[124:127], v[164:167], v[180:183], v[124:127]
	v_mfma_f32_16x16x32_bf16 v[120:123], v[172:175], v[180:183], v[120:123]
	v_mfma_f32_16x16x32_bf16 v[116:119], v[160:163], v[184:187], v[116:119]
	v_mfma_f32_16x16x32_bf16 v[112:115], v[168:171], v[184:187], v[112:115]
	v_mfma_f32_16x16x32_bf16 v[108:111], v[164:167], v[196:199], v[108:111]
	v_mfma_f32_16x16x32_bf16 v[104:107], v[172:175], v[196:199], v[104:107]
	v_mfma_f32_16x16x32_bf16 v[100:103], v[160:163], v[200:203], v[100:103]
	v_mfma_f32_16x16x32_bf16 v[96:99], v[168:171], v[200:203], v[96:99]
	v_mfma_f32_16x16x32_bf16 v[134:137], v[164:167], v[188:191], v[116:119]
	v_mfma_f32_16x16x32_bf16 v[208:211], v[172:175], v[188:191], v[112:115]
	v_mfma_f32_16x16x32_bf16 v[212:215], v[164:167], v[204:207], v[100:103]
	v_mfma_f32_16x16x32_bf16 v[216:219], v[172:175], v[204:207], v[96:99]
	s_setprio 0
	s_barrier
	s_nop 1
	ds_read_b128 v[96:99], v142
	ds_read_b128 v[100:103], v143
	ds_read_b128 v[112:115], v144
	ds_read_b128 v[116:119], v145
	s_barrier
	s_waitcnt lgkmcnt(0)
	s_setprio 1
	s_waitcnt lgkmcnt(0)
	v_mfma_f32_16x16x32_bf16 v[92:95], v[96:99], v[176:179], v[92:95]
	v_mfma_f32_16x16x32_bf16 v[88:91], v[112:115], v[176:179], v[88:91]
	v_mfma_f32_16x16x32_bf16 v[76:79], v[96:99], v[192:195], v[76:79]
	v_mfma_f32_16x16x32_bf16 v[72:75], v[112:115], v[192:195], v[72:75]
	v_mfma_f32_16x16x32_bf16 v[68:71], v[96:99], v[200:203], v[68:71]
	v_mfma_f32_16x16x32_bf16 v[64:67], v[112:115], v[200:203], v[64:67]
	v_mfma_f32_16x16x32_bf16 v[92:95], v[100:103], v[180:183], v[92:95]
	v_mfma_f32_16x16x32_bf16 v[88:91], v[116:119], v[180:183], v[88:91]
	v_mfma_f32_16x16x32_bf16 v[84:87], v[96:99], v[184:187], v[84:87]
	v_mfma_f32_16x16x32_bf16 v[80:83], v[112:115], v[184:187], v[80:83]
	v_mfma_f32_16x16x32_bf16 v[76:79], v[100:103], v[196:199], v[76:79]
	v_mfma_f32_16x16x32_bf16 v[72:75], v[116:119], v[196:199], v[72:75]
	v_mfma_f32_16x16x32_bf16 v[68:71], v[100:103], v[204:207], v[68:71]
	v_mfma_f32_16x16x32_bf16 v[64:67], v[116:119], v[204:207], v[64:67]
	v_mfma_f32_16x16x32_bf16 v[176:179], v[100:103], v[188:191], v[84:87]
	v_mfma_f32_16x16x32_bf16 v[180:183], v[116:119], v[188:191], v[80:83]
	s_setprio 0
	s_barrier
; #define LDA(dst, b, h) for (int m = 0; m < 4; ++m) for (int k = 0; k < 2; ++k) \
;     dst[m][k] = *reinterpret_cast<const bf16x8*>(aRd + (((b) * 2 + (h)) * G_HT * 2 + m * 2048 + k * 1024))
; #define LDB(dst, b, h) for (int n = 0; n < 2; ++n) for (int k = 0; k < 2; ++k) \
;     dst[n][k] = *reinterpret_cast<const bf16x8*>(bRd + (((b) * 2 + (h)) * G_HT * 2 + n * 2048 + k * 1024))
; #define MMA(ai, bj, At, Bx) do { __builtin_amdgcn_s_setprio(1); \
;     for (int m = 0; m < 4; ++m) for (int n = 0; n < 2; ++n) for (int k = 0; k < 2; ++k) \
;       acc[ai][bj][m][n] = __builtin_amdgcn_mfma_f32_16x16x32_bf16(Bx[n][k], At[m][k], acc[ai][bj][m][n], 0, 0, 0);     \
;     __builtin_amdgcn_s_setprio(0); } while (0)
; #define WAIT_V(n) asm volatile("s_waitcnt vmcnt(" #n ")" ::: "memory")
; #define WAIT_L(n) asm volatile("s_waitcnt lgkmcnt(" #n ")" ::: "memory")
; #define BAR __builtin_amdgcn_s_barrier()
; template <int EPI>
; __device__ __forceinline__ void gemm_tile(const bf16* __restrict__ A, int lda, const bf16* __restrict__ Bt, int K,
;                                           int brow, int bcol, const EpiArgs& ea, char* shmc, bool has_next, int nbrow, int nbcol, bool first_tile) {
;     ...
;     LDA(At, 0, 1); WAIT_V(4); BAR; WAIT_L(0); MMA(1, 0, At, B0); MMA(1, 1, At, B1); BAR; }
;   { LDB(B0, 1, 0); LDA(At, 1, 0); WAIT_V(2); BAR; WAIT_L(0); MMA(0, 0, At, B0); BAR;
;     LDB(B1, 1, 1); WAIT_V(0); BAR; WAIT_L(0); MMA(0, 1, At, B1); BAR;
;     LDA(At, 1, 1); BAR; WAIT_L(0); MMA(1, 0, At, B0); MMA(1, 1, At, B1); BAR; }
	s_nop 0
	ds_read_b128 v[80:83], v158 offset:16384
	ds_read_b128 v[84:87], v158 offset:17408
	ds_read_b128 v[184:187], v158 offset:18432
	ds_read_b128 v[188:191], v158 offset:19456
	ds_read_b128 v[192:195], v158 offset:20480
	ds_read_b128 v[196:199], v158 offset:21504
	ds_read_b128 v[200:203], v158 offset:22528
	ds_read_b128 v[204:207], v158 offset:23552
	s_waitcnt vmcnt(4)
	s_barrier
	s_waitcnt lgkmcnt(0)
	s_setprio 1
	s_waitcnt lgkmcnt(0)
	v_mfma_f32_16x16x32_bf16 v[36:39], v[160:163], v[200:203], v[36:39]
	v_mfma_f32_16x16x32_bf16 v[32:35], v[168:171], v[200:203], v[32:35]
	v_mfma_f32_16x16x32_bf16 v[60:63], v[160:163], v[80:83], v[60:63]
	v_mfma_f32_16x16x32_bf16 v[56:59], v[168:171], v[80:83], v[56:59]
	v_mfma_f32_16x16x32_bf16 v[52:55], v[160:163], v[184:187], v[52:55]
	v_mfma_f32_16x16x32_bf16 v[48:51], v[168:171], v[184:187], v[48:51]
	v_mfma_f32_16x16x32_bf16 v[44:47], v[160:163], v[192:195], v[44:47]
	v_mfma_f32_16x16x32_bf16 v[40:43], v[168:171], v[192:195], v[40:43]
	v_mfma_f32_16x16x32_bf16 v[36:39], v[164:167], v[204:207], v[36:39]
	v_mfma_f32_16x16x32_bf16 v[32:35], v[172:175], v[204:207], v[32:35]
	v_mfma_f32_16x16x32_bf16 v[220:223], v[164:167], v[84:87], v[60:63]
	v_mfma_f32_16x16x32_bf16 v[224:227], v[172:175], v[84:87], v[56:59]
	v_mfma_f32_16x16x32_bf16 v[228:231], v[164:167], v[188:191], v[52:55]
	v_mfma_f32_16x16x32_bf16 v[232:235], v[172:175], v[188:191], v[48:51]
	v_mfma_f32_16x16x32_bf16 v[236:239], v[164:167], v[196:199], v[44:47]
	v_mfma_f32_16x16x32_bf16 v[240:243], v[172:175], v[196:199], v[40:43]
	s_setprio 0
	s_setprio 1
	v_mfma_f32_16x16x32_bf16 v[20:23], v[96:99], v[184:187], v[20:23]
	v_mfma_f32_16x16x32_bf16 v[16:19], v[112:115], v[184:187], v[16:19]
	v_mfma_f32_16x16x32_bf16 v[4:7], v[96:99], v[200:203], v[4:7]
	v_mfma_f32_16x16x32_bf16 v[28:31], v[96:99], v[80:83], v[28:31]
	v_mfma_f32_16x16x32_bf16 v[24:27], v[112:115], v[80:83], v[24:27]
	v_mfma_f32_16x16x32_bf16 v[20:23], v[100:103], v[188:191], v[20:23]
	v_mfma_f32_16x16x32_bf16 v[16:19], v[116:119], v[188:191], v[16:19]
	v_mfma_f32_16x16x32_bf16 v[12:15], v[96:99], v[192:195], v[12:15]
	v_mfma_f32_16x16x32_bf16 v[8:11], v[112:115], v[192:195], v[8:11]
	v_mfma_f32_16x16x32_bf16 v[4:7], v[100:103], v[204:207], v[4:7]
	v_mfma_f32_16x16x32_bf16 v[0:3], v[112:115], v[200:203], v[0:3]
	v_mfma_f32_16x16x32_bf16 v[160:163], v[100:103], v[84:87], v[28:31]
	v_mfma_f32_16x16x32_bf16 v[164:167], v[116:119], v[84:87], v[24:27]
	v_mfma_f32_16x16x32_bf16 v[168:171], v[100:103], v[196:199], v[12:15]
	v_mfma_f32_16x16x32_bf16 v[172:175], v[116:119], v[196:199], v[8:11]
	v_mfma_f32_16x16x32_bf16 v[184:187], v[116:119], v[204:207], v[0:3]
	s_setprio 0
	s_barrier
	s_nop 0
	ds_read_b128 v[0:3], v146
	ds_read_b128 v[8:11], v147
	ds_read_b128 v[12:15], v148
	ds_read_b128 v[188:191], v149
	ds_read_b128 v[24:27], v158 offset:32768
	ds_read_b128 v[28:31], v158 offset:33792
	ds_read_b128 v[40:43], v158 offset:34816
	ds_read_b128 v[44:47], v158 offset:35840
	ds_read_b128 v[56:59], v158 offset:36864
	ds_read_b128 v[60:63], v158 offset:37888
	ds_read_b128 v[192:195], v158 offset:38912
	ds_read_b128 v[196:199], v158 offset:39936
	s_waitcnt vmcnt(2)
	s_barrier
	s_waitcnt lgkmcnt(0)
	s_setprio 1
	s_waitcnt lgkmcnt(0)
	v_mfma_f32_16x16x32_bf16 v[48:51], v[0:3], v[24:27], v[124:127]
	v_mfma_f32_16x16x32_bf16 v[112:115], v[8:11], v[28:31], v[48:51]
	v_mfma_f32_16x16x32_bf16 v[48:51], v[12:15], v[24:27], v[120:123]
	v_mfma_f32_16x16x32_bf16 v[116:119], v[188:191], v[28:31], v[48:51]
	v_mfma_f32_16x16x32_bf16 v[48:51], v[0:3], v[40:43], v[134:137]
	v_mfma_f32_16x16x32_bf16 v[96:99], v[8:11], v[44:47], v[48:51]
	v_mfma_f32_16x16x32_bf16 v[48:51], v[12:15], v[40:43], v[208:211]
	v_mfma_f32_16x16x32_bf16 v[100:103], v[188:191], v[44:47], v[48:51]
	v_mfma_f32_16x16x32_bf16 v[48:51], v[0:3], v[56:59], v[108:111]
	v_mfma_f32_16x16x32_bf16 v[80:83], v[8:11], v[60:63], v[48:51]
	v_mfma_f32_16x16x32_bf16 v[48:51], v[12:15], v[56:59], v[104:107]
	v_mfma_f32_16x16x32_bf16 v[84:87], v[188:191], v[60:63], v[48:51]
	v_mfma_f32_16x16x32_bf16 v[48:51], v[0:3], v[192:195], v[212:215]
	v_mfma_f32_16x16x32_bf16 v[52:55], v[12:15], v[192:195], v[216:219]
	v_mfma_f32_16x16x32_bf16 v[48:51], v[8:11], v[196:199], v[48:51]
	v_mfma_f32_16x16x32_bf16 v[52:55], v[188:191], v[196:199], v[52:55]
	s_setprio 0
	s_barrier
; #define LDA(dst, b, h) for (int m = 0; m < 4; ++m) for (int k = 0; k < 2; ++k) \
;     dst[m][k] = *reinterpret_cast<const bf16x8*>(aRd + (((b) * 2 + (h)) * G_HT * 2 + m * 2048 + k * 1024))
; #define LDB(dst, b, h) for (int n = 0; n < 2; ++n) for (int k = 0; k < 2; ++k) \
;     dst[n][k] = *reinterpret_cast<const bf16x8*>(bRd + (((b) * 2 + (h)) * G_HT * 2 + n * 2048 + k * 1024))
; #define MMA(ai, bj, At, Bx) do { __builtin_amdgcn_s_setprio(1); \
;     for (int m = 0; m < 4; ++m) for (int n = 0; n < 2; ++n) for (int k = 0; k < 2; ++k) \
;       acc[ai][bj][m][n] = __builtin_amdgcn_mfma_f32_16x16x32_bf16(Bx[n][k], At[m][k], acc[ai][bj][m][n], 0, 0, 0);     \
;     __builtin_amdgcn_s_setprio(0); } while (0)
; #define WAIT_V(n) asm volatile("s_waitcnt vmcnt(" #n ")" ::: "memory")
; #define WAIT_L(n) asm volatile("s_waitcnt lgkmcnt(" #n ")" ::: "memory")
; #define BAR __builtin_amdgcn_s_barrier()
; template <int EPI>
; __device__ __forceinline__ void gemm_tile(const bf16* __restrict__ A, int lda, const bf16* __restrict__ Bt, int K,
;                                           int brow, int bcol, const EpiArgs& ea, char* shmc, bool has_next, int nbrow, int nbcol, bool first_tile) {
;     ...
;   { LDB(B0, 1, 0); LDA(At, 1, 0); WAIT_V(2); BAR; WAIT_L(0); MMA(0, 0, At, B0); BAR;
;     LDB(B1, 1, 1); WAIT_V(0); BAR; WAIT_L(0); MMA(0, 1, At, B1); BAR;
;     LDA(At, 1, 1); BAR; WAIT_L(0); MMA(1, 0, At, B0); MMA(1, 1, At, B1); BAR; }
;   if (wr == 0) BAR;
;   if (has_next) gemm_prefetch(A, lda, Bt, K, nbrow, nbcol, shmc);
	ds_read_b128 v[134:137], v150
	ds_read_b128 v[200:203], v151
	ds_read_b128 v[204:207], v152
	ds_read_b128 v[208:211], v153
	s_waitcnt vmcnt(0)
	s_barrier
	s_waitcnt lgkmcnt(0)
	s_setprio 1
	s_waitcnt lgkmcnt(0)
	v_mfma_f32_16x16x32_bf16 v[92:95], v[134:137], v[24:27], v[92:95]
	v_mfma_f32_16x16x32_bf16 v[24:27], v[204:207], v[24:27], v[88:91]
	v_mfma_f32_16x16x32_bf16 v[124:127], v[208:211], v[28:31], v[24:27]
	v_mfma_f32_16x16x32_bf16 v[24:27], v[134:137], v[40:43], v[176:179]
	v_mfma_f32_16x16x32_bf16 v[104:107], v[200:203], v[44:47], v[24:27]
	v_mfma_f32_16x16x32_bf16 v[24:27], v[204:207], v[40:43], v[180:183]
	v_mfma_f32_16x16x32_bf16 v[108:111], v[208:211], v[44:47], v[24:27]
	v_mfma_f32_16x16x32_bf16 v[24:27], v[134:137], v[56:59], v[76:79]
	v_mfma_f32_16x16x32_bf16 v[88:91], v[200:203], v[60:63], v[24:27]
	v_mfma_f32_16x16x32_bf16 v[24:27], v[204:207], v[56:59], v[72:75]
	v_mfma_f32_16x16x32_bf16 v[120:123], v[200:203], v[28:31], v[92:95]
	v_mfma_f32_16x16x32_bf16 v[92:95], v[208:211], v[60:63], v[24:27]
	v_mfma_f32_16x16x32_bf16 v[24:27], v[134:137], v[192:195], v[68:71]
	v_mfma_f32_16x16x32_bf16 v[56:59], v[200:203], v[196:199], v[24:27]
	v_mfma_f32_16x16x32_bf16 v[24:27], v[204:207], v[192:195], v[64:67]
	v_mfma_f32_16x16x32_bf16 v[60:63], v[208:211], v[196:199], v[24:27]
	s_setprio 0
	s_barrier
	ds_read_b128 v[68:71], v158 offset:49152
	ds_read_b128 v[176:179], v158 offset:50176
	ds_read_b128 v[180:183], v158 offset:51200
	ds_read_b128 v[192:195], v158 offset:52224
	ds_read_b128 v[196:199], v158 offset:53248
	ds_read_b128 v[212:215], v158 offset:54272
	ds_read_b128 v[216:219], v158 offset:55296
	ds_read_b128 v[244:247], v158 offset:56320
	s_barrier
	s_waitcnt lgkmcnt(0)
	s_setprio 1
	s_waitcnt lgkmcnt(0)
	v_mfma_f32_16x16x32_bf16 v[24:27], v[0:3], v[68:71], v[220:223]
	v_mfma_f32_16x16x32_bf16 v[72:75], v[8:11], v[176:179], v[24:27]
	v_mfma_f32_16x16x32_bf16 v[24:27], v[12:15], v[68:71], v[224:227]
	v_mfma_f32_16x16x32_bf16 v[76:79], v[188:191], v[176:179], v[24:27]
	v_mfma_f32_16x16x32_bf16 v[24:27], v[0:3], v[180:183], v[228:231]
	v_mfma_f32_16x16x32_bf16 v[40:43], v[8:11], v[192:195], v[24:27]
	v_mfma_f32_16x16x32_bf16 v[24:27], v[12:15], v[180:183], v[232:235]
	v_mfma_f32_16x16x32_bf16 v[44:47], v[188:191], v[192:195], v[24:27]
	v_mfma_f32_16x16x32_bf16 v[24:27], v[0:3], v[196:199], v[236:239]
	v_mfma_f32_16x16x32_bf16 v[0:3], v[0:3], v[216:219], v[36:39]
	v_mfma_f32_16x16x32_bf16 v[24:27], v[8:11], v[212:215], v[24:27]
	v_mfma_f32_16x16x32_bf16 v[28:31], v[12:15], v[196:199], v[240:243]
	v_mfma_f32_16x16x32_bf16 v[8:11], v[8:11], v[244:247], v[0:3]
	v_mfma_f32_16x16x32_bf16 v[0:3], v[12:15], v[216:219], v[32:35]
	v_mfma_f32_16x16x32_bf16 v[28:31], v[188:191], v[212:215], v[28:31]
	v_mfma_f32_16x16x32_bf16 v[12:15], v[188:191], v[244:247], v[0:3]
	s_setprio 0
	s_setprio 1
	v_mfma_f32_16x16x32_bf16 v[0:3], v[134:137], v[68:71], v[160:163]
	v_mfma_f32_16x16x32_bf16 v[64:67], v[200:203], v[176:179], v[0:3]
	v_mfma_f32_16x16x32_bf16 v[0:3], v[204:207], v[68:71], v[164:167]
	v_mfma_f32_16x16x32_bf16 v[68:71], v[208:211], v[176:179], v[0:3]
	v_mfma_f32_16x16x32_bf16 v[0:3], v[134:137], v[180:183], v[20:23]
	v_mfma_f32_16x16x32_bf16 v[32:35], v[200:203], v[192:195], v[0:3]
	v_mfma_f32_16x16x32_bf16 v[0:3], v[204:207], v[180:183], v[16:19]
	v_mfma_f32_16x16x32_bf16 v[36:39], v[208:211], v[192:195], v[0:3]
	v_mfma_f32_16x16x32_bf16 v[0:3], v[134:137], v[196:199], v[168:171]
	v_mfma_f32_16x16x32_bf16 v[16:19], v[200:203], v[212:215], v[0:3]
	v_mfma_f32_16x16x32_bf16 v[0:3], v[204:207], v[196:199], v[172:175]
	v_mfma_f32_16x16x32_bf16 v[20:23], v[208:211], v[212:215], v[0:3]
	v_mfma_f32_16x16x32_bf16 v[0:3], v[134:137], v[216:219], v[4:7]
	v_mfma_f32_16x16x32_bf16 v[4:7], v[204:207], v[216:219], v[184:187]
	v_mfma_f32_16x16x32_bf16 v[0:3], v[200:203], v[244:247], v[0:3]
	v_mfma_f32_16x16x32_bf16 v[4:7], v[208:211], v[244:247], v[4:7]
	s_setprio 0
	s_barrier
	s_and_saveexec_b64 s[30:31], s[4:5]
	s_cbranch_execz .LBB0_313
	s_barrier

; #define STA(b, h, half, kt) STAGE(((b) * 2 + (h)) * G_HT * 2, pA, ((size_t)(half) * G_HALF * lda + (size_t)(kt) * G_BK) * 2, lda)
; #define STB(b, h, half, kt) STAGE((4 + (b) * 2 + (h)) * G_HT * 2, pB, ((size_t)(half) * G_HALF * K + (size_t)(kt) * G_BK) * 2, K)
; #define LDA(dst, b, h) for (int m = 0; m < 4; ++m) for (int k = 0; k < 2; ++k) \
;     dst[m][k] = *reinterpret_cast<const bf16x8*>(aRd + (((b) * 2 + (h)) * G_HT * 2 + m * 2048 + k * 1024))
; #define LDB(dst, b, h) for (int n = 0; n < 2; ++n) for (int k = 0; k < 2; ++k) \
;     dst[n][k] = *reinterpret_cast<const bf16x8*>(bRd + (((b) * 2 + (h)) * G_HT * 2 + n * 2048 + k * 1024))
; #define MMA(ai, bj, At, Bx) do { __builtin_amdgcn_s_setprio(1); \
;     for (int m = 0; m < 4; ++m) for (int n = 0; n < 2; ++n) for (int k = 0; k < 2; ++k) \
;       acc[ai][bj][m][n] = __builtin_amdgcn_mfma_f32_16x16x32_bf16(Bx[n][k], At[m][k], acc[ai][bj][m][n], 0, 0, 0);     \
;     __builtin_amdgcn_s_setprio(0); } while (0)
; #define WAIT_V(n) asm volatile("s_waitcnt vmcnt(" #n ")" ::: "memory")
; #define WAIT_L(n) asm volatile("s_waitcnt lgkmcnt(" #n ")" ::: "memory")
; #define BAR __builtin_amdgcn_s_barrier()
; #define SCHED __builtin_amdgcn_sched_barrier(0)
; template <int EPI>
; __device__ __forceinline__ void gemm_tile(const bf16* __restrict__ A, int lda, const bf16* __restrict__ Bt, int K,
;                                           int brow, int bcol, const EpiArgs& ea, char* shmc, bool has_next, int nbrow, int nbcol, bool first_tile) {
;     ...
;   for (int t = 0; t < nt - 2; t += 2) {
;     LDB(B0, 0, 0); SCHED; LDA(At, 0, 0); STA(1, 1, 1, t + 1);
;     WAIT_L(8); BAR; WAIT_L(0); MMA(0, 0, At, B0); BAR; SCHED;
;     LDB(B1, 0, 1); STB(0, 0, 0, t + 2);
;     BAR; WAIT_L(0); MMA(0, 1, At, B1); BAR;
;     LDA(At, 0, 1); STA(0, 0, 0, t + 2);
;     BAR; WAIT_L(0); MMA(1, 0, At, B0); BAR; SCHED;
;     STB(0, 1, 1, t + 2);
;     WAIT_V(6); BAR; MMA(1, 1, At, B1); BAR;
.LBB0_654:
	ds_read_b128 v[140:143], v145
	ds_read_b128 v[166:169], v146
	ds_read_b128 v[170:173], v147
	ds_read_b128 v[174:177], v148
	s_add_u32 s42, s14, 0xffffff00
	s_addc_u32 s43, s15, -1
	s_mov_b32 m0, s29
	ds_read_b128 v[178:181], v164
	ds_read_b128 v[182:185], v164 offset:1024
	ds_read_b128 v[186:189], v164 offset:2048
	ds_read_b128 v[190:193], v164 offset:3072
	ds_read_b128 v[194:197], v164 offset:4096
	ds_read_b128 v[198:201], v164 offset:5120
	ds_read_b128 v[202:205], v164 offset:6144
	ds_read_b128 v[206:209], v164 offset:7168
	v_lshl_add_u64 v[210:211], v[136:137], 0, s[42:43]
	global_load_lds_dwordx4 v[210:211], off
	s_mov_b32 m0, s21
	v_lshl_add_u64 v[210:211], v[210:211], 0, s[10:11]
	global_load_lds_dwordx4 v[210:211], off
	s_waitcnt lgkmcnt(8)
	s_barrier
	s_waitcnt lgkmcnt(0)
	s_setprio 1
	v_mfma_f32_16x16x32_bf16 v[124:127], v[140:143], v[178:181], v[124:127]
	v_mfma_f32_16x16x32_bf16 v[120:123], v[170:173], v[178:181], v[120:123]
	v_mfma_f32_16x16x32_bf16 v[116:119], v[140:143], v[186:189], v[116:119]
	v_mfma_f32_16x16x32_bf16 v[112:115], v[170:173], v[186:189], v[112:115]
	v_mfma_f32_16x16x32_bf16 v[108:111], v[140:143], v[194:197], v[108:111]
	v_mfma_f32_16x16x32_bf16 v[104:107], v[170:173], v[194:197], v[104:107]
	v_mfma_f32_16x16x32_bf16 v[100:103], v[140:143], v[202:205], v[100:103]
	v_mfma_f32_16x16x32_bf16 v[96:99], v[170:173], v[202:205], v[96:99]
	v_mfma_f32_16x16x32_bf16 v[124:127], v[166:169], v[182:185], v[124:127]
	v_mfma_f32_16x16x32_bf16 v[120:123], v[174:177], v[182:185], v[120:123]
	v_mfma_f32_16x16x32_bf16 v[116:119], v[166:169], v[190:193], v[116:119]
	v_mfma_f32_16x16x32_bf16 v[112:115], v[174:177], v[190:193], v[112:115]
	v_mfma_f32_16x16x32_bf16 v[108:111], v[166:169], v[198:201], v[108:111]
	v_mfma_f32_16x16x32_bf16 v[104:107], v[174:177], v[198:201], v[104:107]
	v_mfma_f32_16x16x32_bf16 v[100:103], v[166:169], v[206:209], v[100:103]
	v_mfma_f32_16x16x32_bf16 v[96:99], v[174:177], v[206:209], v[96:99]
	s_setprio 0
	s_barrier
	s_add_u32 s42, s14, 0xffefff80
	s_addc_u32 s43, s15, -1
	s_mov_b32 m0, s24
	ds_read_b128 v[210:213], v149
	ds_read_b128 v[214:217], v150
	ds_read_b128 v[218:221], v151
	ds_read_b128 v[222:225], v152
	v_lshl_add_u64 v[226:227], v[138:139], 0, s[42:43]
	global_load_lds_dwordx4 v[226:227], off
	s_mov_b32 m0, s25
	v_lshl_add_u64 v[226:227], v[226:227], 0, s[10:11]
	global_load_lds_dwordx4 v[226:227], off
	s_barrier
	s_waitcnt lgkmcnt(0)
	s_setprio 1
	v_mfma_f32_16x16x32_bf16 v[92:95], v[210:213], v[178:181], v[92:95]
	v_mfma_f32_16x16x32_bf16 v[88:91], v[218:221], v[178:181], v[88:91]
	v_mfma_f32_16x16x32_bf16 v[84:87], v[210:213], v[186:189], v[84:87]
	v_mfma_f32_16x16x32_bf16 v[80:83], v[218:221], v[186:189], v[80:83]
	v_mfma_f32_16x16x32_bf16 v[76:79], v[210:213], v[194:197], v[76:79]
	v_mfma_f32_16x16x32_bf16 v[72:75], v[218:221], v[194:197], v[72:75]
	v_mfma_f32_16x16x32_bf16 v[68:71], v[210:213], v[202:205], v[68:71]
	v_mfma_f32_16x16x32_bf16 v[64:67], v[218:221], v[202:205], v[64:67]
	v_mfma_f32_16x16x32_bf16 v[92:95], v[214:217], v[182:185], v[92:95]
	v_mfma_f32_16x16x32_bf16 v[88:91], v[222:225], v[182:185], v[88:91]
	v_mfma_f32_16x16x32_bf16 v[84:87], v[214:217], v[190:193], v[84:87]
	v_mfma_f32_16x16x32_bf16 v[80:83], v[222:225], v[190:193], v[80:83]
	v_mfma_f32_16x16x32_bf16 v[76:79], v[214:217], v[198:201], v[76:79]
	v_mfma_f32_16x16x32_bf16 v[72:75], v[222:225], v[198:201], v[72:75]
	v_mfma_f32_16x16x32_bf16 v[68:71], v[214:217], v[206:209], v[68:71]
	v_mfma_f32_16x16x32_bf16 v[64:67], v[222:225], v[206:209], v[64:67]
	s_setprio 0
	s_mov_b32 m0, s1
	s_barrier
	ds_read_b128 v[178:181], v164 offset:16384
	ds_read_b128 v[182:185], v164 offset:17408
	ds_read_b128 v[186:189], v164 offset:18432
	ds_read_b128 v[190:193], v164 offset:19456
	ds_read_b128 v[194:197], v164 offset:20480
	ds_read_b128 v[198:201], v164 offset:21504
	ds_read_b128 v[202:205], v164 offset:22528
	ds_read_b128 v[206:209], v164 offset:23552
	v_lshl_add_u64 v[226:227], v[136:137], 0, s[42:43]
	global_load_lds_dwordx4 v[226:227], off
	s_mov_b32 m0, s30
	v_lshl_add_u64 v[226:227], v[226:227], 0, s[10:11]
	global_load_lds_dwordx4 v[226:227], off
	s_barrier
	s_waitcnt lgkmcnt(0)
	s_setprio 1
	v_mfma_f32_16x16x32_bf16 v[60:63], v[140:143], v[178:181], v[60:63]
	v_mfma_f32_16x16x32_bf16 v[56:59], v[170:173], v[178:181], v[56:59]
	v_mfma_f32_16x16x32_bf16 v[52:55], v[140:143], v[186:189], v[52:55]
	v_mfma_f32_16x16x32_bf16 v[48:51], v[170:173], v[186:189], v[48:51]
	v_mfma_f32_16x16x32_bf16 v[44:47], v[140:143], v[194:197], v[44:47]
	v_mfma_f32_16x16x32_bf16 v[40:43], v[170:173], v[194:197], v[40:43]
	v_mfma_f32_16x16x32_bf16 v[36:39], v[140:143], v[202:205], v[36:39]
	v_mfma_f32_16x16x32_bf16 v[32:35], v[170:173], v[202:205], v[32:35]
	v_mfma_f32_16x16x32_bf16 v[60:63], v[166:169], v[182:185], v[60:63]
	v_mfma_f32_16x16x32_bf16 v[56:59], v[174:177], v[182:185], v[56:59]
	v_mfma_f32_16x16x32_bf16 v[52:55], v[166:169], v[190:193], v[52:55]
	v_mfma_f32_16x16x32_bf16 v[48:51], v[174:177], v[190:193], v[48:51]
	v_mfma_f32_16x16x32_bf16 v[44:47], v[166:169], v[198:201], v[44:47]
	v_mfma_f32_16x16x32_bf16 v[40:43], v[174:177], v[198:201], v[40:43]
	v_mfma_f32_16x16x32_bf16 v[36:39], v[166:169], v[206:209], v[36:39]
	v_mfma_f32_16x16x32_bf16 v[32:35], v[174:177], v[206:209], v[32:35]
	s_setprio 0
	s_barrier
	s_add_u32 s42, s14, 0xffffff80
	s_addc_u32 s43, s15, -1
	s_mov_b32 m0, s26
	v_lshl_add_u64 v[140:141], v[138:139], 0, s[42:43]
	global_load_lds_dwordx4 v[140:141], off
	s_mov_b32 m0, s27
	v_lshl_add_u64 v[140:141], v[140:141], 0, s[10:11]
	global_load_lds_dwordx4 v[140:141], off
	s_waitcnt vmcnt(6)
	s_barrier
; #define STA(b, h, half, kt) STAGE(((b) * 2 + (h)) * G_HT * 2, pA, ((size_t)(half) * G_HALF * lda + (size_t)(kt) * G_BK) * 2, lda)
; #define STB(b, h, half, kt) STAGE((4 + (b) * 2 + (h)) * G_HT * 2, pB, ((size_t)(half) * G_HALF * K + (size_t)(kt) * G_BK) * 2, K)
; #define LDA(dst, b, h) for (int m = 0; m < 4; ++m) for (int k = 0; k < 2; ++k) \
;     dst[m][k] = *reinterpret_cast<const bf16x8*>(aRd + (((b) * 2 + (h)) * G_HT * 2 + m * 2048 + k * 1024))
; #define LDB(dst, b, h) for (int n = 0; n < 2; ++n) for (int k = 0; k < 2; ++k) \
;     dst[n][k] = *reinterpret_cast<const bf16x8*>(bRd + (((b) * 2 + (h)) * G_HT * 2 + n * 2048 + k * 1024))
; #define MMA(ai, bj, At, Bx) do { __builtin_amdgcn_s_setprio(1); \
;     for (int m = 0; m < 4; ++m) for (int n = 0; n < 2; ++n) for (int k = 0; k < 2; ++k) \
;       acc[ai][bj][m][n] = __builtin_amdgcn_mfma_f32_16x16x32_bf16(Bx[n][k], At[m][k], acc[ai][bj][m][n], 0, 0, 0);     \
;     __builtin_amdgcn_s_setprio(0); } while (0)
; #define WAIT_V(n) asm volatile("s_waitcnt vmcnt(" #n ")" ::: "memory")
; #define WAIT_L(n) asm volatile("s_waitcnt lgkmcnt(" #n ")" ::: "memory")
; #define BAR __builtin_amdgcn_s_barrier()
; #define SCHED __builtin_amdgcn_sched_barrier(0)
; template <int EPI>
; __device__ __forceinline__ void gemm_tile(const bf16* __restrict__ A, int lda, const bf16* __restrict__ Bt, int K,
;                                           int brow, int bcol, const EpiArgs& ea, char* shmc, bool has_next, int nbrow, int nbcol, bool first_tile) {
;     ...
;     WAIT_V(6); BAR; MMA(1, 1, At, B1); BAR;
;     LDB(B0, 1, 0); SCHED; LDA(At, 1, 0); STA(0, 1, 1, t + 2);
;     WAIT_L(8); BAR; WAIT_L(0); MMA(0, 0, At, B0); BAR; SCHED;
;     LDB(B1, 1, 1); STB(1, 0, 0, t + 3);
;     BAR; WAIT_L(0); MMA(0, 1, At, B1); BAR;
;     LDA(At, 1, 1); STA(1, 0, 0, t + 3);
;     BAR; WAIT_L(0); MMA(1, 0, At, B0); BAR; SCHED;
	s_setprio 1
	v_mfma_f32_16x16x32_bf16 v[28:31], v[210:213], v[178:181], v[28:31]
	v_mfma_f32_16x16x32_bf16 v[24:27], v[218:221], v[178:181], v[24:27]
	v_mfma_f32_16x16x32_bf16 v[20:23], v[210:213], v[186:189], v[20:23]
	v_mfma_f32_16x16x32_bf16 v[16:19], v[218:221], v[186:189], v[16:19]
	v_mfma_f32_16x16x32_bf16 v[12:15], v[210:213], v[194:197], v[12:15]
	v_mfma_f32_16x16x32_bf16 v[8:11], v[218:221], v[194:197], v[8:11]
	v_mfma_f32_16x16x32_bf16 v[4:7], v[210:213], v[202:205], v[4:7]
	v_mfma_f32_16x16x32_bf16 v[0:3], v[218:221], v[202:205], v[0:3]
	v_mfma_f32_16x16x32_bf16 v[28:31], v[214:217], v[182:185], v[28:31]
	v_mfma_f32_16x16x32_bf16 v[24:27], v[222:225], v[182:185], v[24:27]
	v_mfma_f32_16x16x32_bf16 v[20:23], v[214:217], v[190:193], v[20:23]
	v_mfma_f32_16x16x32_bf16 v[16:19], v[222:225], v[190:193], v[16:19]
	v_mfma_f32_16x16x32_bf16 v[12:15], v[214:217], v[198:201], v[12:15]
	v_mfma_f32_16x16x32_bf16 v[8:11], v[222:225], v[198:201], v[8:11]
	v_mfma_f32_16x16x32_bf16 v[4:7], v[214:217], v[206:209], v[4:7]
	v_mfma_f32_16x16x32_bf16 v[0:3], v[222:225], v[206:209], v[0:3]
	s_setprio 0
	s_barrier
	ds_read_b128 v[140:143], v153
	ds_read_b128 v[166:169], v154
	ds_read_b128 v[170:173], v155
	ds_read_b128 v[174:177], v156
	s_mov_b32 m0, s31
	ds_read_b128 v[178:181], v164 offset:32768
	ds_read_b128 v[182:185], v164 offset:33792
	ds_read_b128 v[186:189], v164 offset:34816
	ds_read_b128 v[190:193], v164 offset:35840
	ds_read_b128 v[194:197], v164 offset:36864
	ds_read_b128 v[198:201], v164 offset:37888
	ds_read_b128 v[202:205], v164 offset:38912
	ds_read_b128 v[206:209], v164 offset:39936
	v_lshl_add_u64 v[210:211], v[136:137], 0, s[42:43]
	global_load_lds_dwordx4 v[210:211], off
	s_mov_b32 m0, s34
	v_lshl_add_u64 v[210:211], v[210:211], 0, s[10:11]
	global_load_lds_dwordx4 v[210:211], off
	s_waitcnt lgkmcnt(8)
	s_barrier
	s_waitcnt lgkmcnt(0)
	s_setprio 1
	v_mfma_f32_16x16x32_bf16 v[124:127], v[140:143], v[178:181], v[124:127]
	v_mfma_f32_16x16x32_bf16 v[120:123], v[170:173], v[178:181], v[120:123]
	v_mfma_f32_16x16x32_bf16 v[116:119], v[140:143], v[186:189], v[116:119]
	v_mfma_f32_16x16x32_bf16 v[112:115], v[170:173], v[186:189], v[112:115]
	v_mfma_f32_16x16x32_bf16 v[108:111], v[140:143], v[194:197], v[108:111]
	v_mfma_f32_16x16x32_bf16 v[104:107], v[170:173], v[194:197], v[104:107]
	v_mfma_f32_16x16x32_bf16 v[100:103], v[140:143], v[202:205], v[100:103]
	v_mfma_f32_16x16x32_bf16 v[96:99], v[170:173], v[202:205], v[96:99]
	v_mfma_f32_16x16x32_bf16 v[124:127], v[166:169], v[182:185], v[124:127]
	v_mfma_f32_16x16x32_bf16 v[120:123], v[174:177], v[182:185], v[120:123]
	v_mfma_f32_16x16x32_bf16 v[116:119], v[166:169], v[190:193], v[116:119]
	v_mfma_f32_16x16x32_bf16 v[112:115], v[174:177], v[190:193], v[112:115]
	v_mfma_f32_16x16x32_bf16 v[108:111], v[166:169], v[198:201], v[108:111]
	v_mfma_f32_16x16x32_bf16 v[104:107], v[174:177], v[198:201], v[104:107]
	v_mfma_f32_16x16x32_bf16 v[100:103], v[166:169], v[206:209], v[100:103]
	v_mfma_f32_16x16x32_bf16 v[96:99], v[174:177], v[206:209], v[96:99]
	s_setprio 0
	s_barrier
	s_add_u32 s42, s14, 0xfff00000
	s_addc_u32 s43, s15, -1
	s_mov_b32 m0, s13
	ds_read_b128 v[210:213], v158
	ds_read_b128 v[214:217], v159
	ds_read_b128 v[218:221], v160
	ds_read_b128 v[222:225], v161
	v_lshl_add_u64 v[226:227], v[138:139], 0, s[42:43]
	global_load_lds_dwordx4 v[226:227], off
	s_mov_b32 m0, s18
	v_lshl_add_u64 v[226:227], v[226:227], 0, s[10:11]
	global_load_lds_dwordx4 v[226:227], off
	s_barrier
	s_waitcnt lgkmcnt(0)
	s_setprio 1
	v_mfma_f32_16x16x32_bf16 v[92:95], v[210:213], v[178:181], v[92:95]
	v_mfma_f32_16x16x32_bf16 v[88:91], v[218:221], v[178:181], v[88:91]
	v_mfma_f32_16x16x32_bf16 v[84:87], v[210:213], v[186:189], v[84:87]
	v_mfma_f32_16x16x32_bf16 v[80:83], v[218:221], v[186:189], v[80:83]
	v_mfma_f32_16x16x32_bf16 v[76:79], v[210:213], v[194:197], v[76:79]
	v_mfma_f32_16x16x32_bf16 v[72:75], v[218:221], v[194:197], v[72:75]
	v_mfma_f32_16x16x32_bf16 v[68:71], v[210:213], v[202:205], v[68:71]
	v_mfma_f32_16x16x32_bf16 v[64:67], v[218:221], v[202:205], v[64:67]
	v_mfma_f32_16x16x32_bf16 v[92:95], v[214:217], v[182:185], v[92:95]
	v_mfma_f32_16x16x32_bf16 v[88:91], v[222:225], v[182:185], v[88:91]
	v_mfma_f32_16x16x32_bf16 v[84:87], v[214:217], v[190:193], v[84:87]
	v_mfma_f32_16x16x32_bf16 v[80:83], v[222:225], v[190:193], v[80:83]
	v_mfma_f32_16x16x32_bf16 v[76:79], v[214:217], v[198:201], v[76:79]
	v_mfma_f32_16x16x32_bf16 v[72:75], v[222:225], v[198:201], v[72:75]
	v_mfma_f32_16x16x32_bf16 v[68:71], v[214:217], v[206:209], v[68:71]
	v_mfma_f32_16x16x32_bf16 v[64:67], v[222:225], v[206:209], v[64:67]
	s_setprio 0
	s_mov_b32 m0, s19
	s_barrier
	ds_read_b128 v[178:181], v164 offset:49152
	ds_read_b128 v[182:185], v164 offset:50176
	ds_read_b128 v[186:189], v164 offset:51200
	ds_read_b128 v[190:193], v164 offset:52224
	ds_read_b128 v[194:197], v164 offset:53248
	ds_read_b128 v[198:201], v164 offset:54272
	ds_read_b128 v[202:205], v164 offset:55296
	ds_read_b128 v[206:209], v164 offset:56320
	v_lshl_add_u64 v[226:227], v[136:137], 0, s[42:43]
	global_load_lds_dwordx4 v[226:227], off
	s_mov_b32 m0, s20
	v_lshl_add_u64 v[226:227], v[226:227], 0, s[10:11]
	global_load_lds_dwordx4 v[226:227], off
	s_barrier
; #define STA(b, h, half, kt) STAGE(((b) * 2 + (h)) * G_HT * 2, pA, ((size_t)(half) * G_HALF * lda + (size_t)(kt) * G_BK) * 2, lda)
; #define STB(b, h, half, kt) STAGE((4 + (b) * 2 + (h)) * G_HT * 2, pB, ((size_t)(half) * G_HALF * K + (size_t)(kt) * G_BK) * 2, K)
; #define LDA(dst, b, h) for (int m = 0; m < 4; ++m) for (int k = 0; k < 2; ++k) \
;     dst[m][k] = *reinterpret_cast<const bf16x8*>(aRd + (((b) * 2 + (h)) * G_HT * 2 + m * 2048 + k * 1024))
; #define LDB(dst, b, h) for (int n = 0; n < 2; ++n) for (int k = 0; k < 2; ++k) \
;     dst[n][k] = *reinterpret_cast<const bf16x8*>(bRd + (((b) * 2 + (h)) * G_HT * 2 + n * 2048 + k * 1024))
; #define MMA(ai, bj, At, Bx) do { __builtin_amdgcn_s_setprio(1); \
;     for (int m = 0; m < 4; ++m) for (int n = 0; n < 2; ++n) for (int k = 0; k < 2; ++k) \
;       acc[ai][bj][m][n] = __builtin_amdgcn_mfma_f32_16x16x32_bf16(Bx[n][k], At[m][k], acc[ai][bj][m][n], 0, 0, 0);     \
;     __builtin_amdgcn_s_setprio(0); } while (0)
; #define WAIT_V(n) asm volatile("s_waitcnt vmcnt(" #n ")" ::: "memory")
; #define WAIT_L(n) asm volatile("s_waitcnt lgkmcnt(" #n ")" ::: "memory")
; #define BAR __builtin_amdgcn_s_barrier()
; #define SCHED __builtin_amdgcn_sched_barrier(0)
; template <int EPI>
; __device__ __forceinline__ void gemm_tile(const bf16* __restrict__ A, int lda, const bf16* __restrict__ Bt, int K,
;                                           int brow, int bcol, const EpiArgs& ea, char* shmc, bool has_next, int nbrow, int nbcol, bool first_tile) {
;     ...
;     BAR; WAIT_L(0); MMA(1, 0, At, B0); BAR; SCHED;
;     STB(1, 1, 1, t + 3);
;     WAIT_V(6); BAR; MMA(1, 1, At, B1); BAR;
;   }
;   { LDB(B0, 0, 0); LDA(At, 0, 0); STA(1, 1, 1, nt - 1);
;     BAR; WAIT_L(0); MMA(0, 0, At, B0); BAR;
;     LDB(B1, 0, 1); BAR; WAIT_L(0); MMA(0, 1, At, B1); BAR;
	s_waitcnt lgkmcnt(0)
	s_setprio 1
	v_mfma_f32_16x16x32_bf16 v[60:63], v[140:143], v[178:181], v[60:63]
	v_mfma_f32_16x16x32_bf16 v[56:59], v[170:173], v[178:181], v[56:59]
	v_mfma_f32_16x16x32_bf16 v[52:55], v[140:143], v[186:189], v[52:55]
	v_mfma_f32_16x16x32_bf16 v[48:51], v[170:173], v[186:189], v[48:51]
	v_mfma_f32_16x16x32_bf16 v[44:47], v[140:143], v[194:197], v[44:47]
	v_mfma_f32_16x16x32_bf16 v[40:43], v[170:173], v[194:197], v[40:43]
	v_mfma_f32_16x16x32_bf16 v[36:39], v[140:143], v[202:205], v[36:39]
	v_mfma_f32_16x16x32_bf16 v[32:35], v[170:173], v[202:205], v[32:35]
	v_mfma_f32_16x16x32_bf16 v[60:63], v[166:169], v[182:185], v[60:63]
	v_mfma_f32_16x16x32_bf16 v[56:59], v[174:177], v[182:185], v[56:59]
	v_mfma_f32_16x16x32_bf16 v[52:55], v[166:169], v[190:193], v[52:55]
	v_mfma_f32_16x16x32_bf16 v[48:51], v[174:177], v[190:193], v[48:51]
	v_mfma_f32_16x16x32_bf16 v[44:47], v[166:169], v[198:201], v[44:47]
	v_mfma_f32_16x16x32_bf16 v[40:43], v[174:177], v[198:201], v[40:43]
	v_mfma_f32_16x16x32_bf16 v[36:39], v[166:169], v[206:209], v[36:39]
	v_mfma_f32_16x16x32_bf16 v[32:35], v[174:177], v[206:209], v[32:35]
	s_setprio 0
	s_barrier
	s_mov_b32 m0, s22
	v_lshl_add_u64 v[140:141], v[138:139], 0, s[14:15]
	global_load_lds_dwordx4 v[140:141], off
	s_mov_b32 m0, s23
	v_lshl_add_u64 v[140:141], v[140:141], 0, s[10:11]
	global_load_lds_dwordx4 v[140:141], off
	s_waitcnt vmcnt(6)
	s_barrier
	s_setprio 1
	v_mfma_f32_16x16x32_bf16 v[28:31], v[210:213], v[178:181], v[28:31]
	v_mfma_f32_16x16x32_bf16 v[24:27], v[218:221], v[178:181], v[24:27]
	v_mfma_f32_16x16x32_bf16 v[20:23], v[210:213], v[186:189], v[20:23]
	v_mfma_f32_16x16x32_bf16 v[16:19], v[218:221], v[186:189], v[16:19]
	v_mfma_f32_16x16x32_bf16 v[12:15], v[210:213], v[194:197], v[12:15]
	v_mfma_f32_16x16x32_bf16 v[8:11], v[218:221], v[194:197], v[8:11]
	v_mfma_f32_16x16x32_bf16 v[4:7], v[210:213], v[202:205], v[4:7]
	v_mfma_f32_16x16x32_bf16 v[0:3], v[218:221], v[202:205], v[0:3]
	v_mfma_f32_16x16x32_bf16 v[28:31], v[214:217], v[182:185], v[28:31]
	v_mfma_f32_16x16x32_bf16 v[24:27], v[222:225], v[182:185], v[24:27]
	v_mfma_f32_16x16x32_bf16 v[20:23], v[214:217], v[190:193], v[20:23]
	v_mfma_f32_16x16x32_bf16 v[16:19], v[222:225], v[190:193], v[16:19]
	v_mfma_f32_16x16x32_bf16 v[12:15], v[214:217], v[198:201], v[12:15]
	v_mfma_f32_16x16x32_bf16 v[8:11], v[222:225], v[198:201], v[8:11]
	v_mfma_f32_16x16x32_bf16 v[4:7], v[214:217], v[206:209], v[4:7]
	v_mfma_f32_16x16x32_bf16 v[0:3], v[222:225], v[206:209], v[0:3]
	s_setprio 0
	s_add_i32 s28, s28, 2
	s_add_u32 s14, s14, 0x100
	s_addc_u32 s15, s15, 0
	s_cmp_lt_u32 s28, 60
	s_barrier
	s_cbranch_scc1 .LBB0_654
	s_mov_b64 s[14:15], 0x101f80
	s_mov_b32 m0, s29
	ds_read_b128 v[138:141], v145
	ds_read_b128 v[166:169], v146
	ds_read_b128 v[170:173], v147
	ds_read_b128 v[174:177], v148
	ds_read_b128 v[178:181], v164
	ds_read_b128 v[182:185], v164 offset:1024
	ds_read_b128 v[186:189], v164 offset:2048
	ds_read_b128 v[190:193], v164 offset:3072
	ds_read_b128 v[194:197], v164 offset:4096
	ds_read_b128 v[198:201], v164 offset:5120
	ds_read_b128 v[202:205], v164 offset:6144
	ds_read_b128 v[206:209], v164 offset:7168
	s_nop 0
	v_lshl_add_u64 v[136:137], v[136:137], 0, s[14:15]
	global_load_lds_dwordx4 v[136:137], off
	v_lshl_add_u64 v[136:137], v[136:137], 0, s[10:11]
	s_mov_b32 m0, s21
	s_nop 0
	global_load_lds_dwordx4 v[136:137], off
	s_barrier
	s_waitcnt lgkmcnt(0)
	s_setprio 1
	s_waitcnt lgkmcnt(0)
	v_mfma_f32_16x16x32_bf16 v[124:127], v[138:141], v[178:181], v[124:127]
	v_mfma_f32_16x16x32_bf16 v[116:119], v[138:141], v[186:189], v[116:119]
	v_mfma_f32_16x16x32_bf16 v[112:115], v[170:173], v[186:189], v[112:115]
	v_mfma_f32_16x16x32_bf16 v[100:103], v[138:141], v[202:205], v[100:103]
	v_mfma_f32_16x16x32_bf16 v[96:99], v[170:173], v[202:205], v[96:99]
	v_mfma_f32_16x16x32_bf16 v[124:127], v[166:169], v[182:185], v[124:127]
	v_mfma_f32_16x16x32_bf16 v[120:123], v[170:173], v[178:181], v[120:123]
	v_mfma_f32_16x16x32_bf16 v[116:119], v[166:169], v[190:193], v[116:119]
	v_mfma_f32_16x16x32_bf16 v[112:115], v[174:177], v[190:193], v[112:115]
	v_mfma_f32_16x16x32_bf16 v[108:111], v[138:141], v[194:197], v[108:111]
	v_mfma_f32_16x16x32_bf16 v[104:107], v[170:173], v[194:197], v[104:107]
	v_mfma_f32_16x16x32_bf16 v[100:103], v[166:169], v[206:209], v[100:103]
	v_mfma_f32_16x16x32_bf16 v[96:99], v[174:177], v[206:209], v[96:99]
	v_mfma_f32_16x16x32_bf16 v[210:213], v[174:177], v[182:185], v[120:123]
	v_mfma_f32_16x16x32_bf16 v[214:217], v[166:169], v[198:201], v[108:111]
	v_mfma_f32_16x16x32_bf16 v[218:221], v[174:177], v[198:201], v[104:107]
	s_setprio 0
	s_barrier
	s_nop 0
	ds_read_b128 v[104:107], v149
	ds_read_b128 v[108:111], v150
	ds_read_b128 v[120:123], v151
	ds_read_b128 v[222:225], v152
	s_barrier
	s_waitcnt lgkmcnt(0)
	s_setprio 1
	s_waitcnt lgkmcnt(0)
	v_mfma_f32_16x16x32_bf16 v[84:87], v[104:107], v[186:189], v[84:87]
	v_mfma_f32_16x16x32_bf16 v[80:83], v[120:123], v[186:189], v[80:83]
	v_mfma_f32_16x16x32_bf16 v[68:71], v[104:107], v[202:205], v[68:71]
	v_mfma_f32_16x16x32_bf16 v[92:95], v[104:107], v[178:181], v[92:95]
	v_mfma_f32_16x16x32_bf16 v[88:91], v[120:123], v[178:181], v[88:91]
	v_mfma_f32_16x16x32_bf16 v[84:87], v[108:111], v[190:193], v[84:87]
	v_mfma_f32_16x16x32_bf16 v[80:83], v[222:225], v[190:193], v[80:83]
	v_mfma_f32_16x16x32_bf16 v[76:79], v[104:107], v[194:197], v[76:79]
	v_mfma_f32_16x16x32_bf16 v[72:75], v[120:123], v[194:197], v[72:75]
	v_mfma_f32_16x16x32_bf16 v[68:71], v[108:111], v[206:209], v[68:71]
	v_mfma_f32_16x16x32_bf16 v[64:67], v[120:123], v[202:205], v[64:67]
	v_mfma_f32_16x16x32_bf16 v[226:229], v[108:111], v[182:185], v[92:95]
	v_mfma_f32_16x16x32_bf16 v[178:181], v[222:225], v[182:185], v[88:91]
	v_mfma_f32_16x16x32_bf16 v[182:185], v[108:111], v[198:201], v[76:79]
	v_mfma_f32_16x16x32_bf16 v[186:189], v[222:225], v[198:201], v[72:75]
	v_mfma_f32_16x16x32_bf16 v[190:193], v[222:225], v[206:209], v[64:67]
	s_setprio 0
	s_barrier
; #define LDA(dst, b, h) for (int m = 0; m < 4; ++m) for (int k = 0; k < 2; ++k) \
;     dst[m][k] = *reinterpret_cast<const bf16x8*>(aRd + (((b) * 2 + (h)) * G_HT * 2 + m * 2048 + k * 1024))
; #define LDB(dst, b, h) for (int n = 0; n < 2; ++n) for (int k = 0; k < 2; ++k) \
;     dst[n][k] = *reinterpret_cast<const bf16x8*>(bRd + (((b) * 2 + (h)) * G_HT * 2 + n * 2048 + k * 1024))
; #define MMA(ai, bj, At, Bx) do { __builtin_amdgcn_s_setprio(1); \
;     for (int m = 0; m < 4; ++m) for (int n = 0; n < 2; ++n) for (int k = 0; k < 2; ++k) \
;       acc[ai][bj][m][n] = __builtin_amdgcn_mfma_f32_16x16x32_bf16(Bx[n][k], At[m][k], acc[ai][bj][m][n], 0, 0, 0);     \
;     __builtin_amdgcn_s_setprio(0); } while (0)
; #define WAIT_V(n) asm volatile("s_waitcnt vmcnt(" #n ")" ::: "memory")
; #define WAIT_L(n) asm volatile("s_waitcnt lgkmcnt(" #n ")" ::: "memory")
; #define BAR __builtin_amdgcn_s_barrier()
; template <int EPI>
; __device__ __forceinline__ void gemm_tile(const bf16* __restrict__ A, int lda, const bf16* __restrict__ Bt, int K,
;                                           int brow, int bcol, const EpiArgs& ea, char* shmc, bool has_next, int nbrow, int nbcol, bool first_tile) {
;     ...
;     LDA(At, 0, 1); WAIT_V(4); BAR; WAIT_L(0); MMA(1, 0, At, B0); MMA(1, 1, At, B1); BAR; }
;   { LDB(B0, 1, 0); LDA(At, 1, 0); WAIT_V(2); BAR; WAIT_L(0); MMA(0, 0, At, B0); BAR;
	s_nop 0
	ds_read_b128 v[64:67], v164 offset:16384
	ds_read_b128 v[72:75], v164 offset:17408
	ds_read_b128 v[76:79], v164 offset:18432
	ds_read_b128 v[88:91], v164 offset:19456
	ds_read_b128 v[92:95], v164 offset:20480
	ds_read_b128 v[194:197], v164 offset:21504
	ds_read_b128 v[198:201], v164 offset:22528
	ds_read_b128 v[202:205], v164 offset:23552
	s_waitcnt vmcnt(4)
	s_barrier
	s_waitcnt lgkmcnt(0)
	s_setprio 1
	s_waitcnt lgkmcnt(0)
	v_mfma_f32_16x16x32_bf16 v[60:63], v[138:141], v[64:67], v[60:63]
	v_mfma_f32_16x16x32_bf16 v[52:55], v[138:141], v[76:79], v[52:55]
	v_mfma_f32_16x16x32_bf16 v[48:51], v[170:173], v[76:79], v[48:51]
	v_mfma_f32_16x16x32_bf16 v[36:39], v[138:141], v[198:201], v[36:39]
	v_mfma_f32_16x16x32_bf16 v[32:35], v[170:173], v[198:201], v[32:35]
	v_mfma_f32_16x16x32_bf16 v[60:63], v[166:169], v[72:75], v[60:63]
	v_mfma_f32_16x16x32_bf16 v[56:59], v[170:173], v[64:67], v[56:59]
	v_mfma_f32_16x16x32_bf16 v[52:55], v[166:169], v[88:91], v[52:55]
	v_mfma_f32_16x16x32_bf16 v[48:51], v[174:177], v[88:91], v[48:51]
	v_mfma_f32_16x16x32_bf16 v[44:47], v[138:141], v[92:95], v[44:47]
	v_mfma_f32_16x16x32_bf16 v[40:43], v[170:173], v[92:95], v[40:43]
	v_mfma_f32_16x16x32_bf16 v[36:39], v[166:169], v[202:205], v[36:39]
	v_mfma_f32_16x16x32_bf16 v[32:35], v[174:177], v[202:205], v[32:35]
	v_mfma_f32_16x16x32_bf16 v[206:209], v[174:177], v[72:75], v[56:59]
	v_mfma_f32_16x16x32_bf16 v[230:233], v[166:169], v[194:197], v[44:47]
	v_mfma_f32_16x16x32_bf16 v[234:237], v[174:177], v[194:197], v[40:43]
	s_setprio 0
	s_setprio 1
	v_mfma_f32_16x16x32_bf16 v[20:23], v[104:107], v[76:79], v[20:23]
	v_mfma_f32_16x16x32_bf16 v[16:19], v[120:123], v[76:79], v[16:19]
	v_mfma_f32_16x16x32_bf16 v[4:7], v[104:107], v[198:201], v[4:7]
	v_mfma_f32_16x16x32_bf16 v[28:31], v[104:107], v[64:67], v[28:31]
	v_mfma_f32_16x16x32_bf16 v[24:27], v[120:123], v[64:67], v[24:27]
	v_mfma_f32_16x16x32_bf16 v[20:23], v[108:111], v[88:91], v[20:23]
	v_mfma_f32_16x16x32_bf16 v[16:19], v[222:225], v[88:91], v[16:19]
	v_mfma_f32_16x16x32_bf16 v[12:15], v[104:107], v[92:95], v[12:15]
	v_mfma_f32_16x16x32_bf16 v[8:11], v[120:123], v[92:95], v[8:11]
	v_mfma_f32_16x16x32_bf16 v[4:7], v[108:111], v[202:205], v[4:7]
	v_mfma_f32_16x16x32_bf16 v[0:3], v[120:123], v[198:201], v[0:3]
	v_mfma_f32_16x16x32_bf16 v[136:139], v[108:111], v[72:75], v[28:31]
	v_mfma_f32_16x16x32_bf16 v[140:143], v[222:225], v[72:75], v[24:27]
	v_mfma_f32_16x16x32_bf16 v[166:169], v[108:111], v[194:197], v[12:15]
	v_mfma_f32_16x16x32_bf16 v[170:173], v[222:225], v[194:197], v[8:11]
	v_mfma_f32_16x16x32_bf16 v[174:177], v[222:225], v[202:205], v[0:3]
	s_setprio 0
	s_barrier
	s_nop 0
	ds_read_b128 v[0:3], v153
	ds_read_b128 v[8:11], v154
	ds_read_b128 v[12:15], v155
	ds_read_b128 v[194:197], v156
	ds_read_b128 v[24:27], v164 offset:32768
	ds_read_b128 v[28:31], v164 offset:33792
	ds_read_b128 v[40:43], v164 offset:34816
	ds_read_b128 v[44:47], v164 offset:35840
	ds_read_b128 v[56:59], v164 offset:36864
	ds_read_b128 v[64:67], v164 offset:37888
	ds_read_b128 v[198:201], v164 offset:38912
	ds_read_b128 v[202:205], v164 offset:39936
	s_waitcnt vmcnt(2)
	s_barrier
	s_waitcnt lgkmcnt(0)
	s_setprio 1
	s_waitcnt lgkmcnt(0)
	v_mfma_f32_16x16x32_bf16 v[72:75], v[0:3], v[24:27], v[124:127]
	v_mfma_f32_16x16x32_bf16 v[120:123], v[8:11], v[28:31], v[72:75]
	v_mfma_f32_16x16x32_bf16 v[72:75], v[12:15], v[24:27], v[210:213]
	v_mfma_f32_16x16x32_bf16 v[124:127], v[194:197], v[28:31], v[72:75]
	v_mfma_f32_16x16x32_bf16 v[72:75], v[0:3], v[40:43], v[116:119]
	v_mfma_f32_16x16x32_bf16 v[104:107], v[8:11], v[44:47], v[72:75]
	v_mfma_f32_16x16x32_bf16 v[72:75], v[12:15], v[40:43], v[112:115]
	v_mfma_f32_16x16x32_bf16 v[108:111], v[194:197], v[44:47], v[72:75]
	v_mfma_f32_16x16x32_bf16 v[72:75], v[0:3], v[56:59], v[214:217]
	v_mfma_f32_16x16x32_bf16 v[88:91], v[8:11], v[64:67], v[72:75]
	v_mfma_f32_16x16x32_bf16 v[72:75], v[12:15], v[56:59], v[218:221]
	v_mfma_f32_16x16x32_bf16 v[92:95], v[194:197], v[64:67], v[72:75]
	v_mfma_f32_16x16x32_bf16 v[72:75], v[0:3], v[198:201], v[100:103]
	v_mfma_f32_16x16x32_bf16 v[76:79], v[12:15], v[198:201], v[96:99]
	v_mfma_f32_16x16x32_bf16 v[72:75], v[8:11], v[202:205], v[72:75]
	v_mfma_f32_16x16x32_bf16 v[76:79], v[194:197], v[202:205], v[76:79]
	s_setprio 0
	s_barrier
; #define LDA(dst, b, h) for (int m = 0; m < 4; ++m) for (int k = 0; k < 2; ++k) \
;     dst[m][k] = *reinterpret_cast<const bf16x8*>(aRd + (((b) * 2 + (h)) * G_HT * 2 + m * 2048 + k * 1024))
; #define LDB(dst, b, h) for (int n = 0; n < 2; ++n) for (int k = 0; k < 2; ++k) \
;     dst[n][k] = *reinterpret_cast<const bf16x8*>(bRd + (((b) * 2 + (h)) * G_HT * 2 + n * 2048 + k * 1024))
; #define MMA(ai, bj, At, Bx) do { __builtin_amdgcn_s_setprio(1); \
;     for (int m = 0; m < 4; ++m) for (int n = 0; n < 2; ++n) for (int k = 0; k < 2; ++k) \
;       acc[ai][bj][m][n] = __builtin_amdgcn_mfma_f32_16x16x32_bf16(Bx[n][k], At[m][k], acc[ai][bj][m][n], 0, 0, 0);     \
;     __builtin_amdgcn_s_setprio(0); } while (0)
; #define WAIT_V(n) asm volatile("s_waitcnt vmcnt(" #n ")" ::: "memory")
; #define WAIT_L(n) asm volatile("s_waitcnt lgkmcnt(" #n ")" ::: "memory")
; #define BAR __builtin_amdgcn_s_barrier()
; template <int EPI>
; __device__ __forceinline__ void gemm_tile(const bf16* __restrict__ A, int lda, const bf16* __restrict__ Bt, int K,
;                                           int brow, int bcol, const EpiArgs& ea, char* shmc, bool has_next, int nbrow, int nbcol, bool first_tile) {
;     ...
;     LDB(B1, 1, 1); WAIT_V(0); BAR; WAIT_L(0); MMA(0, 1, At, B1); BAR;
;     LDA(At, 1, 1); BAR; WAIT_L(0); MMA(1, 0, At, B0); MMA(1, 1, At, B1); BAR; }
;   if (wr == 0) BAR;
	ds_read_b128 v[210:213], v158
	ds_read_b128 v[214:217], v159
	ds_read_b128 v[218:221], v160
	ds_read_b128 v[222:225], v161
	s_waitcnt vmcnt(0)
	s_barrier
	s_waitcnt lgkmcnt(0)
	s_setprio 1
	s_waitcnt lgkmcnt(0)
	v_mfma_f32_16x16x32_bf16 v[96:99], v[210:213], v[24:27], v[226:229]
	v_mfma_f32_16x16x32_bf16 v[24:27], v[218:221], v[24:27], v[178:181]
	v_mfma_f32_16x16x32_bf16 v[116:119], v[222:225], v[28:31], v[24:27]
	v_mfma_f32_16x16x32_bf16 v[24:27], v[210:213], v[40:43], v[84:87]
	v_mfma_f32_16x16x32_bf16 v[112:115], v[214:217], v[28:31], v[96:99]
	v_mfma_f32_16x16x32_bf16 v[96:99], v[214:217], v[44:47], v[24:27]
	v_mfma_f32_16x16x32_bf16 v[24:27], v[218:221], v[40:43], v[80:83]
	v_mfma_f32_16x16x32_bf16 v[100:103], v[222:225], v[44:47], v[24:27]
	v_mfma_f32_16x16x32_bf16 v[24:27], v[210:213], v[56:59], v[182:185]
	v_mfma_f32_16x16x32_bf16 v[80:83], v[214:217], v[64:67], v[24:27]
	v_mfma_f32_16x16x32_bf16 v[24:27], v[218:221], v[56:59], v[186:189]
	v_mfma_f32_16x16x32_bf16 v[84:87], v[222:225], v[64:67], v[24:27]
	v_mfma_f32_16x16x32_bf16 v[24:27], v[210:213], v[198:201], v[68:71]
	v_mfma_f32_16x16x32_bf16 v[64:67], v[214:217], v[202:205], v[24:27]
	v_mfma_f32_16x16x32_bf16 v[24:27], v[218:221], v[198:201], v[190:193]
	v_mfma_f32_16x16x32_bf16 v[68:71], v[222:225], v[202:205], v[24:27]
	s_setprio 0
	s_barrier
	ds_read_b128 v[178:181], v164 offset:49152
	ds_read_b128 v[182:185], v164 offset:50176
	ds_read_b128 v[186:189], v164 offset:51200
	ds_read_b128 v[190:193], v164 offset:52224
	ds_read_b128 v[198:201], v164 offset:53248
	ds_read_b128 v[202:205], v164 offset:54272
	ds_read_b128 v[226:229], v164 offset:55296
	ds_read_b128 v[238:241], v164 offset:56320
	s_barrier
	s_waitcnt lgkmcnt(0)
	s_setprio 1
	s_waitcnt lgkmcnt(0)
	v_mfma_f32_16x16x32_bf16 v[24:27], v[0:3], v[178:181], v[60:63]
	v_mfma_f32_16x16x32_bf16 v[56:59], v[8:11], v[182:185], v[24:27]
	v_mfma_f32_16x16x32_bf16 v[24:27], v[12:15], v[178:181], v[206:209]
	v_mfma_f32_16x16x32_bf16 v[60:63], v[194:197], v[182:185], v[24:27]
	v_mfma_f32_16x16x32_bf16 v[24:27], v[0:3], v[186:189], v[52:55]
	v_mfma_f32_16x16x32_bf16 v[40:43], v[8:11], v[190:193], v[24:27]
	v_mfma_f32_16x16x32_bf16 v[24:27], v[12:15], v[186:189], v[48:51]
	v_mfma_f32_16x16x32_bf16 v[44:47], v[194:197], v[190:193], v[24:27]
	v_mfma_f32_16x16x32_bf16 v[24:27], v[0:3], v[198:201], v[230:233]
	v_mfma_f32_16x16x32_bf16 v[0:3], v[0:3], v[226:229], v[36:39]
	v_mfma_f32_16x16x32_bf16 v[24:27], v[8:11], v[202:205], v[24:27]
	v_mfma_f32_16x16x32_bf16 v[28:31], v[12:15], v[198:201], v[234:237]
	v_mfma_f32_16x16x32_bf16 v[8:11], v[8:11], v[238:241], v[0:3]
	v_mfma_f32_16x16x32_bf16 v[0:3], v[12:15], v[226:229], v[32:35]
	v_mfma_f32_16x16x32_bf16 v[28:31], v[194:197], v[202:205], v[28:31]
	v_mfma_f32_16x16x32_bf16 v[12:15], v[194:197], v[238:241], v[0:3]
	s_setprio 0
	s_setprio 1
	v_mfma_f32_16x16x32_bf16 v[0:3], v[210:213], v[178:181], v[136:139]
	v_mfma_f32_16x16x32_bf16 v[48:51], v[214:217], v[182:185], v[0:3]
	v_mfma_f32_16x16x32_bf16 v[0:3], v[218:221], v[178:181], v[140:143]
	v_mfma_f32_16x16x32_bf16 v[52:55], v[222:225], v[182:185], v[0:3]
	v_mfma_f32_16x16x32_bf16 v[0:3], v[210:213], v[186:189], v[20:23]
	v_mfma_f32_16x16x32_bf16 v[32:35], v[214:217], v[190:193], v[0:3]
	v_mfma_f32_16x16x32_bf16 v[0:3], v[218:221], v[186:189], v[16:19]
	v_mfma_f32_16x16x32_bf16 v[36:39], v[222:225], v[190:193], v[0:3]
	v_mfma_f32_16x16x32_bf16 v[0:3], v[210:213], v[198:201], v[166:169]
	v_mfma_f32_16x16x32_bf16 v[16:19], v[214:217], v[202:205], v[0:3]
	v_mfma_f32_16x16x32_bf16 v[0:3], v[218:221], v[198:201], v[170:173]
	v_mfma_f32_16x16x32_bf16 v[20:23], v[222:225], v[202:205], v[0:3]
	v_mfma_f32_16x16x32_bf16 v[0:3], v[210:213], v[226:229], v[4:7]
	v_mfma_f32_16x16x32_bf16 v[4:7], v[218:221], v[226:229], v[174:177]
	v_mfma_f32_16x16x32_bf16 v[0:3], v[214:217], v[238:241], v[0:3]
	v_mfma_f32_16x16x32_bf16 v[4:7], v[222:225], v[238:241], v[4:7]
	s_setprio 0
	s_barrier
	s_and_saveexec_b64 s[14:15], s[4:5]
	s_cbranch_execz .LBB0_657
	s_barrier

; #define STA(b, h, half, kt) STAGE(((b) * 2 + (h)) * G_HT * 2, pA, ((size_t)(half) * G_HALF * lda + (size_t)(kt) * G_BK) * 2, lda)
; #define STB(b, h, half, kt) STAGE((4 + (b) * 2 + (h)) * G_HT * 2, pB, ((size_t)(half) * G_HALF * K + (size_t)(kt) * G_BK) * 2, K)
; #define LDA(dst, b, h) for (int m = 0; m < 4; ++m) for (int k = 0; k < 2; ++k) \
;     dst[m][k] = *reinterpret_cast<const bf16x8*>(aRd + (((b) * 2 + (h)) * G_HT * 2 + m * 2048 + k * 1024))
; #define LDB(dst, b, h) for (int n = 0; n < 2; ++n) for (int k = 0; k < 2; ++k) \
;     dst[n][k] = *reinterpret_cast<const bf16x8*>(bRd + (((b) * 2 + (h)) * G_HT * 2 + n * 2048 + k * 1024))
; #define MMA(ai, bj, At, Bx) do { __builtin_amdgcn_s_setprio(1); \
;     for (int m = 0; m < 4; ++m) for (int n = 0; n < 2; ++n) for (int k = 0; k < 2; ++k) \
;       acc[ai][bj][m][n] = __builtin_amdgcn_mfma_f32_16x16x32_bf16(Bx[n][k], At[m][k], acc[ai][bj][m][n], 0, 0, 0);     \
;     __builtin_amdgcn_s_setprio(0); } while (0)
; #define WAIT_V(n) asm volatile("s_waitcnt vmcnt(" #n ")" ::: "memory")
; #define WAIT_L(n) asm volatile("s_waitcnt lgkmcnt(" #n ")" ::: "memory")
; #define BAR __builtin_amdgcn_s_barrier()
; #define SCHED __builtin_amdgcn_sched_barrier(0)
; template <int EPI>
; __device__ __forceinline__ void gemm_tile(const bf16* __restrict__ A, int lda, const bf16* __restrict__ Bt, int K,
;                                           int brow, int bcol, const EpiArgs& ea, char* shmc, bool has_next, int nbrow, int nbcol, bool first_tile) {
;     ...
;   for (int t = 0; t < nt - 2; t += 2) {
;     LDB(B0, 0, 0); SCHED; LDA(At, 0, 0); STA(1, 1, 1, t + 1);
;     WAIT_L(8); BAR; WAIT_L(0); MMA(0, 0, At, B0); BAR; SCHED;
;     LDB(B1, 0, 1); STB(0, 0, 0, t + 2);
;     BAR; WAIT_L(0); MMA(0, 1, At, B1); BAR;
;     LDA(At, 0, 1); STA(0, 0, 0, t + 2);
;     BAR; WAIT_L(0); MMA(1, 0, At, B0); BAR; SCHED;
;     STB(0, 1, 1, t + 2);
;     WAIT_V(6); BAR; MMA(1, 1, At, B1); BAR;
.LBB0_727:
	ds_read_b128 v[136:139], v141
	ds_read_b128 v[162:165], v142
	ds_read_b128 v[166:169], v143
	ds_read_b128 v[170:173], v144
	s_add_u32 s52, s20, 0xffffff00
	s_addc_u32 s53, s21, -1
	s_mov_b32 m0, s50
	ds_read_b128 v[174:177], v160
	ds_read_b128 v[178:181], v160 offset:1024
	ds_read_b128 v[182:185], v160 offset:2048
	ds_read_b128 v[186:189], v160 offset:3072
	ds_read_b128 v[190:193], v160 offset:4096
	ds_read_b128 v[194:197], v160 offset:5120
	ds_read_b128 v[198:201], v160 offset:6144
	ds_read_b128 v[202:205], v160 offset:7168
	v_lshl_add_u64 v[206:207], v[132:133], 0, s[52:53]
	global_load_lds_dwordx4 v[206:207], off
	s_mov_b32 m0, s34
	v_lshl_add_u64 v[206:207], v[206:207], 0, s[10:11]
	global_load_lds_dwordx4 v[206:207], off
	s_waitcnt lgkmcnt(8)
	s_barrier
	s_waitcnt lgkmcnt(0)
	s_setprio 1
	v_mfma_f32_16x16x32_bf16 v[124:127], v[136:139], v[174:177], v[124:127]
	v_mfma_f32_16x16x32_bf16 v[120:123], v[166:169], v[174:177], v[120:123]
	v_mfma_f32_16x16x32_bf16 v[116:119], v[136:139], v[182:185], v[116:119]
	v_mfma_f32_16x16x32_bf16 v[112:115], v[166:169], v[182:185], v[112:115]
	v_mfma_f32_16x16x32_bf16 v[108:111], v[136:139], v[190:193], v[108:111]
	v_mfma_f32_16x16x32_bf16 v[104:107], v[166:169], v[190:193], v[104:107]
	v_mfma_f32_16x16x32_bf16 v[100:103], v[136:139], v[198:201], v[100:103]
	v_mfma_f32_16x16x32_bf16 v[96:99], v[166:169], v[198:201], v[96:99]
	v_mfma_f32_16x16x32_bf16 v[124:127], v[162:165], v[178:181], v[124:127]
	v_mfma_f32_16x16x32_bf16 v[120:123], v[170:173], v[178:181], v[120:123]
	v_mfma_f32_16x16x32_bf16 v[116:119], v[162:165], v[186:189], v[116:119]
	v_mfma_f32_16x16x32_bf16 v[112:115], v[170:173], v[186:189], v[112:115]
	v_mfma_f32_16x16x32_bf16 v[108:111], v[162:165], v[194:197], v[108:111]
	v_mfma_f32_16x16x32_bf16 v[104:107], v[170:173], v[194:197], v[104:107]
	v_mfma_f32_16x16x32_bf16 v[100:103], v[162:165], v[202:205], v[100:103]
	v_mfma_f32_16x16x32_bf16 v[96:99], v[170:173], v[202:205], v[96:99]
	s_setprio 0
	s_barrier
	s_add_u32 s52, s20, 0xffefff80
	s_addc_u32 s53, s21, -1
	s_mov_b32 m0, s41
	ds_read_b128 v[206:209], v145
	ds_read_b128 v[210:213], v146
	ds_read_b128 v[214:217], v147
	ds_read_b128 v[218:221], v148
	v_lshl_add_u64 v[222:223], v[134:135], 0, s[52:53]
	global_load_lds_dwordx4 v[222:223], off
	s_mov_b32 m0, s42
	v_lshl_add_u64 v[222:223], v[222:223], 0, s[10:11]
	global_load_lds_dwordx4 v[222:223], off
	s_barrier
	s_waitcnt lgkmcnt(0)
	s_setprio 1
	v_mfma_f32_16x16x32_bf16 v[92:95], v[206:209], v[174:177], v[92:95]
	v_mfma_f32_16x16x32_bf16 v[88:91], v[214:217], v[174:177], v[88:91]
	v_mfma_f32_16x16x32_bf16 v[84:87], v[206:209], v[182:185], v[84:87]
	v_mfma_f32_16x16x32_bf16 v[80:83], v[214:217], v[182:185], v[80:83]
	v_mfma_f32_16x16x32_bf16 v[76:79], v[206:209], v[190:193], v[76:79]
	v_mfma_f32_16x16x32_bf16 v[72:75], v[214:217], v[190:193], v[72:75]
	v_mfma_f32_16x16x32_bf16 v[68:71], v[206:209], v[198:201], v[68:71]
	v_mfma_f32_16x16x32_bf16 v[64:67], v[214:217], v[198:201], v[64:67]
	v_mfma_f32_16x16x32_bf16 v[92:95], v[210:213], v[178:181], v[92:95]
	v_mfma_f32_16x16x32_bf16 v[88:91], v[218:221], v[178:181], v[88:91]
	v_mfma_f32_16x16x32_bf16 v[84:87], v[210:213], v[186:189], v[84:87]
	v_mfma_f32_16x16x32_bf16 v[80:83], v[218:221], v[186:189], v[80:83]
	v_mfma_f32_16x16x32_bf16 v[76:79], v[210:213], v[194:197], v[76:79]
	v_mfma_f32_16x16x32_bf16 v[72:75], v[218:221], v[194:197], v[72:75]
	v_mfma_f32_16x16x32_bf16 v[68:71], v[210:213], v[202:205], v[68:71]
	v_mfma_f32_16x16x32_bf16 v[64:67], v[218:221], v[202:205], v[64:67]
	s_setprio 0
	s_mov_b32 m0, s1
	s_barrier
	ds_read_b128 v[174:177], v160 offset:16384
	ds_read_b128 v[178:181], v160 offset:17408
	ds_read_b128 v[182:185], v160 offset:18432
	ds_read_b128 v[186:189], v160 offset:19456
	ds_read_b128 v[190:193], v160 offset:20480
	ds_read_b128 v[194:197], v160 offset:21504
	ds_read_b128 v[198:201], v160 offset:22528
	ds_read_b128 v[202:205], v160 offset:23552
	v_lshl_add_u64 v[222:223], v[132:133], 0, s[52:53]
	global_load_lds_dwordx4 v[222:223], off
	s_add_i32 m0, s1, 0x2000
	v_lshl_add_u64 v[222:223], v[222:223], 0, s[10:11]
	global_load_lds_dwordx4 v[222:223], off
	s_barrier
	s_waitcnt lgkmcnt(0)
	s_setprio 1
	v_mfma_f32_16x16x32_bf16 v[60:63], v[136:139], v[174:177], v[60:63]
	v_mfma_f32_16x16x32_bf16 v[56:59], v[166:169], v[174:177], v[56:59]
	v_mfma_f32_16x16x32_bf16 v[52:55], v[136:139], v[182:185], v[52:55]
	v_mfma_f32_16x16x32_bf16 v[48:51], v[166:169], v[182:185], v[48:51]
	v_mfma_f32_16x16x32_bf16 v[44:47], v[136:139], v[190:193], v[44:47]
	v_mfma_f32_16x16x32_bf16 v[40:43], v[166:169], v[190:193], v[40:43]
	v_mfma_f32_16x16x32_bf16 v[36:39], v[136:139], v[198:201], v[36:39]
	v_mfma_f32_16x16x32_bf16 v[32:35], v[166:169], v[198:201], v[32:35]
	v_mfma_f32_16x16x32_bf16 v[60:63], v[162:165], v[178:181], v[60:63]
	v_mfma_f32_16x16x32_bf16 v[56:59], v[170:173], v[178:181], v[56:59]
	v_mfma_f32_16x16x32_bf16 v[52:55], v[162:165], v[186:189], v[52:55]
	v_mfma_f32_16x16x32_bf16 v[48:51], v[170:173], v[186:189], v[48:51]
	v_mfma_f32_16x16x32_bf16 v[44:47], v[162:165], v[194:197], v[44:47]
	v_mfma_f32_16x16x32_bf16 v[40:43], v[170:173], v[194:197], v[40:43]
	v_mfma_f32_16x16x32_bf16 v[36:39], v[162:165], v[202:205], v[36:39]
	v_mfma_f32_16x16x32_bf16 v[32:35], v[170:173], v[202:205], v[32:35]
	s_setprio 0
	s_barrier
	s_add_u32 s52, s20, 0xffffff80
	s_addc_u32 s53, s21, -1
	s_mov_b32 m0, s43
	v_lshl_add_u64 v[136:137], v[134:135], 0, s[52:53]
	global_load_lds_dwordx4 v[136:137], off
	s_mov_b32 m0, s48
	v_lshl_add_u64 v[136:137], v[136:137], 0, s[10:11]
	global_load_lds_dwordx4 v[136:137], off
	s_waitcnt vmcnt(6)
	s_barrier
; #define STA(b, h, half, kt) STAGE(((b) * 2 + (h)) * G_HT * 2, pA, ((size_t)(half) * G_HALF * lda + (size_t)(kt) * G_BK) * 2, lda)
; #define STB(b, h, half, kt) STAGE((4 + (b) * 2 + (h)) * G_HT * 2, pB, ((size_t)(half) * G_HALF * K + (size_t)(kt) * G_BK) * 2, K)
; #define LDA(dst, b, h) for (int m = 0; m < 4; ++m) for (int k = 0; k < 2; ++k) \
;     dst[m][k] = *reinterpret_cast<const bf16x8*>(aRd + (((b) * 2 + (h)) * G_HT * 2 + m * 2048 + k * 1024))
; #define LDB(dst, b, h) for (int n = 0; n < 2; ++n) for (int k = 0; k < 2; ++k) \
;     dst[n][k] = *reinterpret_cast<const bf16x8*>(bRd + (((b) * 2 + (h)) * G_HT * 2 + n * 2048 + k * 1024))
; #define MMA(ai, bj, At, Bx) do { __builtin_amdgcn_s_setprio(1); \
;     for (int m = 0; m < 4; ++m) for (int n = 0; n < 2; ++n) for (int k = 0; k < 2; ++k) \
;       acc[ai][bj][m][n] = __builtin_amdgcn_mfma_f32_16x16x32_bf16(Bx[n][k], At[m][k], acc[ai][bj][m][n], 0, 0, 0);     \
;     __builtin_amdgcn_s_setprio(0); } while (0)
; #define WAIT_V(n) asm volatile("s_waitcnt vmcnt(" #n ")" ::: "memory")
; #define WAIT_L(n) asm volatile("s_waitcnt lgkmcnt(" #n ")" ::: "memory")
; #define BAR __builtin_amdgcn_s_barrier()
; #define SCHED __builtin_amdgcn_sched_barrier(0)
; template <int EPI>
; __device__ __forceinline__ void gemm_tile(const bf16* __restrict__ A, int lda, const bf16* __restrict__ Bt, int K,
;                                           int brow, int bcol, const EpiArgs& ea, char* shmc, bool has_next, int nbrow, int nbcol, bool first_tile) {
;     ...
;     WAIT_V(6); BAR; MMA(1, 1, At, B1); BAR;
;     LDB(B0, 1, 0); SCHED; LDA(At, 1, 0); STA(0, 1, 1, t + 2);
;     WAIT_L(8); BAR; WAIT_L(0); MMA(0, 0, At, B0); BAR; SCHED;
;     LDB(B1, 1, 1); STB(1, 0, 0, t + 3);
;     BAR; WAIT_L(0); MMA(0, 1, At, B1); BAR;
;     LDA(At, 1, 1); STA(1, 0, 0, t + 3);
;     BAR; WAIT_L(0); MMA(1, 0, At, B0); BAR; SCHED;
	s_setprio 1
	v_mfma_f32_16x16x32_bf16 v[28:31], v[206:209], v[174:177], v[28:31]
	v_mfma_f32_16x16x32_bf16 v[24:27], v[214:217], v[174:177], v[24:27]
	v_mfma_f32_16x16x32_bf16 v[20:23], v[206:209], v[182:185], v[20:23]
	v_mfma_f32_16x16x32_bf16 v[16:19], v[214:217], v[182:185], v[16:19]
	v_mfma_f32_16x16x32_bf16 v[12:15], v[206:209], v[190:193], v[12:15]
	v_mfma_f32_16x16x32_bf16 v[8:11], v[214:217], v[190:193], v[8:11]
	v_mfma_f32_16x16x32_bf16 v[4:7], v[206:209], v[198:201], v[4:7]
	v_mfma_f32_16x16x32_bf16 v[0:3], v[214:217], v[198:201], v[0:3]
	v_mfma_f32_16x16x32_bf16 v[28:31], v[210:213], v[178:181], v[28:31]
	v_mfma_f32_16x16x32_bf16 v[24:27], v[218:221], v[178:181], v[24:27]
	v_mfma_f32_16x16x32_bf16 v[20:23], v[210:213], v[186:189], v[20:23]
	v_mfma_f32_16x16x32_bf16 v[16:19], v[218:221], v[186:189], v[16:19]
	v_mfma_f32_16x16x32_bf16 v[12:15], v[210:213], v[194:197], v[12:15]
	v_mfma_f32_16x16x32_bf16 v[8:11], v[218:221], v[194:197], v[8:11]
	v_mfma_f32_16x16x32_bf16 v[4:7], v[210:213], v[202:205], v[4:7]
	v_mfma_f32_16x16x32_bf16 v[0:3], v[218:221], v[202:205], v[0:3]
	s_setprio 0
	s_barrier
	ds_read_b128 v[136:139], v149
	ds_read_b128 v[162:165], v150
	ds_read_b128 v[166:169], v151
	ds_read_b128 v[170:173], v152
	ds_read_b128 v[174:177], v160 offset:32768
	ds_read_b128 v[178:181], v160 offset:33792
	ds_read_b128 v[182:185], v160 offset:34816
	ds_read_b128 v[186:189], v160 offset:35840
	ds_read_b128 v[190:193], v160 offset:36864
	ds_read_b128 v[194:197], v160 offset:37888
	ds_read_b128 v[198:201], v160 offset:38912
	ds_read_b128 v[202:205], v160 offset:39936
	s_add_i32 m0, s1, 0x4000
	v_lshl_add_u64 v[206:207], v[132:133], 0, s[52:53]
	global_load_lds_dwordx4 v[206:207], off
	s_add_i32 m0, s1, 0x6000
	v_lshl_add_u64 v[206:207], v[206:207], 0, s[10:11]
	global_load_lds_dwordx4 v[206:207], off
	s_waitcnt lgkmcnt(8)
	s_barrier
	s_waitcnt lgkmcnt(0)
	s_setprio 1
	v_mfma_f32_16x16x32_bf16 v[124:127], v[136:139], v[174:177], v[124:127]
	v_mfma_f32_16x16x32_bf16 v[120:123], v[166:169], v[174:177], v[120:123]
	v_mfma_f32_16x16x32_bf16 v[116:119], v[136:139], v[182:185], v[116:119]
	v_mfma_f32_16x16x32_bf16 v[112:115], v[166:169], v[182:185], v[112:115]
	v_mfma_f32_16x16x32_bf16 v[108:111], v[136:139], v[190:193], v[108:111]
	v_mfma_f32_16x16x32_bf16 v[104:107], v[166:169], v[190:193], v[104:107]
	v_mfma_f32_16x16x32_bf16 v[100:103], v[136:139], v[198:201], v[100:103]
	v_mfma_f32_16x16x32_bf16 v[96:99], v[166:169], v[198:201], v[96:99]
	v_mfma_f32_16x16x32_bf16 v[124:127], v[162:165], v[178:181], v[124:127]
	v_mfma_f32_16x16x32_bf16 v[120:123], v[170:173], v[178:181], v[120:123]
	v_mfma_f32_16x16x32_bf16 v[116:119], v[162:165], v[186:189], v[116:119]
	v_mfma_f32_16x16x32_bf16 v[112:115], v[170:173], v[186:189], v[112:115]
	v_mfma_f32_16x16x32_bf16 v[108:111], v[162:165], v[194:197], v[108:111]
	v_mfma_f32_16x16x32_bf16 v[104:107], v[170:173], v[194:197], v[104:107]
	v_mfma_f32_16x16x32_bf16 v[100:103], v[162:165], v[202:205], v[100:103]
	v_mfma_f32_16x16x32_bf16 v[96:99], v[170:173], v[202:205], v[96:99]
	s_setprio 0
	s_barrier
	s_add_u32 s52, s20, 0xfff00000
	s_addc_u32 s53, s21, -1
	s_mov_b32 m0, s7
	ds_read_b128 v[206:209], v153
	ds_read_b128 v[210:213], v154
	ds_read_b128 v[214:217], v155
	ds_read_b128 v[218:221], v156
	v_lshl_add_u64 v[222:223], v[134:135], 0, s[52:53]
	global_load_lds_dwordx4 v[222:223], off
	s_mov_b32 m0, s29
	v_lshl_add_u64 v[222:223], v[222:223], 0, s[10:11]
	global_load_lds_dwordx4 v[222:223], off
	s_barrier
	s_waitcnt lgkmcnt(0)
	s_setprio 1
	v_mfma_f32_16x16x32_bf16 v[92:95], v[206:209], v[174:177], v[92:95]
	v_mfma_f32_16x16x32_bf16 v[88:91], v[214:217], v[174:177], v[88:91]
	v_mfma_f32_16x16x32_bf16 v[84:87], v[206:209], v[182:185], v[84:87]
	v_mfma_f32_16x16x32_bf16 v[80:83], v[214:217], v[182:185], v[80:83]
	v_mfma_f32_16x16x32_bf16 v[76:79], v[206:209], v[190:193], v[76:79]
	v_mfma_f32_16x16x32_bf16 v[72:75], v[214:217], v[190:193], v[72:75]
	v_mfma_f32_16x16x32_bf16 v[68:71], v[206:209], v[198:201], v[68:71]
	v_mfma_f32_16x16x32_bf16 v[64:67], v[214:217], v[198:201], v[64:67]
	v_mfma_f32_16x16x32_bf16 v[92:95], v[210:213], v[178:181], v[92:95]
	v_mfma_f32_16x16x32_bf16 v[88:91], v[218:221], v[178:181], v[88:91]
	v_mfma_f32_16x16x32_bf16 v[84:87], v[210:213], v[186:189], v[84:87]
	v_mfma_f32_16x16x32_bf16 v[80:83], v[218:221], v[186:189], v[80:83]
	v_mfma_f32_16x16x32_bf16 v[76:79], v[210:213], v[194:197], v[76:79]
	v_mfma_f32_16x16x32_bf16 v[72:75], v[218:221], v[194:197], v[72:75]
	v_mfma_f32_16x16x32_bf16 v[68:71], v[210:213], v[202:205], v[68:71]
	v_mfma_f32_16x16x32_bf16 v[64:67], v[218:221], v[202:205], v[64:67]
	s_setprio 0
	s_mov_b32 m0, s30
	s_barrier
	ds_read_b128 v[174:177], v160 offset:49152
	ds_read_b128 v[178:181], v160 offset:50176
	ds_read_b128 v[182:185], v160 offset:51200
	ds_read_b128 v[186:189], v160 offset:52224
	ds_read_b128 v[190:193], v160 offset:53248
	ds_read_b128 v[194:197], v160 offset:54272
	ds_read_b128 v[198:201], v160 offset:55296
	ds_read_b128 v[202:205], v160 offset:56320
	v_lshl_add_u64 v[222:223], v[132:133], 0, s[52:53]
	global_load_lds_dwordx4 v[222:223], off
	s_mov_b32 m0, s31
	v_lshl_add_u64 v[222:223], v[222:223], 0, s[10:11]
	global_load_lds_dwordx4 v[222:223], off
	s_barrier
; #define STA(b, h, half, kt) STAGE(((b) * 2 + (h)) * G_HT * 2, pA, ((size_t)(half) * G_HALF * lda + (size_t)(kt) * G_BK) * 2, lda)
; #define STB(b, h, half, kt) STAGE((4 + (b) * 2 + (h)) * G_HT * 2, pB, ((size_t)(half) * G_HALF * K + (size_t)(kt) * G_BK) * 2, K)
; #define LDA(dst, b, h) for (int m = 0; m < 4; ++m) for (int k = 0; k < 2; ++k) \
;     dst[m][k] = *reinterpret_cast<const bf16x8*>(aRd + (((b) * 2 + (h)) * G_HT * 2 + m * 2048 + k * 1024))
; #define LDB(dst, b, h) for (int n = 0; n < 2; ++n) for (int k = 0; k < 2; ++k) \
;     dst[n][k] = *reinterpret_cast<const bf16x8*>(bRd + (((b) * 2 + (h)) * G_HT * 2 + n * 2048 + k * 1024))
; #define MMA(ai, bj, At, Bx) do { __builtin_amdgcn_s_setprio(1); \
;     for (int m = 0; m < 4; ++m) for (int n = 0; n < 2; ++n) for (int k = 0; k < 2; ++k) \
;       acc[ai][bj][m][n] = __builtin_amdgcn_mfma_f32_16x16x32_bf16(Bx[n][k], At[m][k], acc[ai][bj][m][n], 0, 0, 0);     \
;     __builtin_amdgcn_s_setprio(0); } while (0)
; #define WAIT_V(n) asm volatile("s_waitcnt vmcnt(" #n ")" ::: "memory")
; #define WAIT_L(n) asm volatile("s_waitcnt lgkmcnt(" #n ")" ::: "memory")
; #define BAR __builtin_amdgcn_s_barrier()
; #define SCHED __builtin_amdgcn_sched_barrier(0)
; template <int EPI>
; __device__ __forceinline__ void gemm_tile(const bf16* __restrict__ A, int lda, const bf16* __restrict__ Bt, int K,
;                                           int brow, int bcol, const EpiArgs& ea, char* shmc, bool has_next, int nbrow, int nbcol, bool first_tile) {
;     ...
;     BAR; WAIT_L(0); MMA(1, 0, At, B0); BAR; SCHED;
;     STB(1, 1, 1, t + 3);
;     WAIT_V(6); BAR; MMA(1, 1, At, B1); BAR;
;   }
;   { LDB(B0, 0, 0); LDA(At, 0, 0); STA(1, 1, 1, nt - 1);
;     BAR; WAIT_L(0); MMA(0, 0, At, B0); BAR;
;     LDB(B1, 0, 1); BAR; WAIT_L(0); MMA(0, 1, At, B1); BAR;
	s_waitcnt lgkmcnt(0)
	s_setprio 1
	v_mfma_f32_16x16x32_bf16 v[60:63], v[136:139], v[174:177], v[60:63]
	v_mfma_f32_16x16x32_bf16 v[56:59], v[166:169], v[174:177], v[56:59]
	v_mfma_f32_16x16x32_bf16 v[52:55], v[136:139], v[182:185], v[52:55]
	v_mfma_f32_16x16x32_bf16 v[48:51], v[166:169], v[182:185], v[48:51]
	v_mfma_f32_16x16x32_bf16 v[44:47], v[136:139], v[190:193], v[44:47]
	v_mfma_f32_16x16x32_bf16 v[40:43], v[166:169], v[190:193], v[40:43]
	v_mfma_f32_16x16x32_bf16 v[36:39], v[136:139], v[198:201], v[36:39]
	v_mfma_f32_16x16x32_bf16 v[32:35], v[166:169], v[198:201], v[32:35]
	v_mfma_f32_16x16x32_bf16 v[60:63], v[162:165], v[178:181], v[60:63]
	v_mfma_f32_16x16x32_bf16 v[56:59], v[170:173], v[178:181], v[56:59]
	v_mfma_f32_16x16x32_bf16 v[52:55], v[162:165], v[186:189], v[52:55]
	v_mfma_f32_16x16x32_bf16 v[48:51], v[170:173], v[186:189], v[48:51]
	v_mfma_f32_16x16x32_bf16 v[44:47], v[162:165], v[194:197], v[44:47]
	v_mfma_f32_16x16x32_bf16 v[40:43], v[170:173], v[194:197], v[40:43]
	v_mfma_f32_16x16x32_bf16 v[36:39], v[162:165], v[202:205], v[36:39]
	v_mfma_f32_16x16x32_bf16 v[32:35], v[170:173], v[202:205], v[32:35]
	s_setprio 0
	s_barrier
	s_mov_b32 m0, s35
	v_lshl_add_u64 v[136:137], v[134:135], 0, s[20:21]
	global_load_lds_dwordx4 v[136:137], off
	s_mov_b32 m0, s40
	v_lshl_add_u64 v[136:137], v[136:137], 0, s[10:11]
	global_load_lds_dwordx4 v[136:137], off
	s_waitcnt vmcnt(6)
	s_barrier
	s_setprio 1
	v_mfma_f32_16x16x32_bf16 v[28:31], v[206:209], v[174:177], v[28:31]
	v_mfma_f32_16x16x32_bf16 v[24:27], v[214:217], v[174:177], v[24:27]
	v_mfma_f32_16x16x32_bf16 v[20:23], v[206:209], v[182:185], v[20:23]
	v_mfma_f32_16x16x32_bf16 v[16:19], v[214:217], v[182:185], v[16:19]
	v_mfma_f32_16x16x32_bf16 v[12:15], v[206:209], v[190:193], v[12:15]
	v_mfma_f32_16x16x32_bf16 v[8:11], v[214:217], v[190:193], v[8:11]
	v_mfma_f32_16x16x32_bf16 v[4:7], v[206:209], v[198:201], v[4:7]
	v_mfma_f32_16x16x32_bf16 v[0:3], v[214:217], v[198:201], v[0:3]
	v_mfma_f32_16x16x32_bf16 v[28:31], v[210:213], v[178:181], v[28:31]
	v_mfma_f32_16x16x32_bf16 v[24:27], v[218:221], v[178:181], v[24:27]
	v_mfma_f32_16x16x32_bf16 v[20:23], v[210:213], v[186:189], v[20:23]
	v_mfma_f32_16x16x32_bf16 v[16:19], v[218:221], v[186:189], v[16:19]
	v_mfma_f32_16x16x32_bf16 v[12:15], v[210:213], v[194:197], v[12:15]
	v_mfma_f32_16x16x32_bf16 v[8:11], v[218:221], v[194:197], v[8:11]
	v_mfma_f32_16x16x32_bf16 v[4:7], v[210:213], v[202:205], v[4:7]
	v_mfma_f32_16x16x32_bf16 v[0:3], v[218:221], v[202:205], v[0:3]
	s_setprio 0
	s_add_i32 s49, s49, 2
	s_add_u32 s20, s20, 0x100
	s_addc_u32 s21, s21, 0
	s_cmp_lt_u32 s49, 60
	s_barrier
	s_cbranch_scc1 .LBB0_727
	s_mov_b64 s[20:21], 0x101f80
	s_mov_b32 m0, s50
	ds_read_b128 v[134:137], v141
	ds_read_b128 v[162:165], v142
	ds_read_b128 v[166:169], v143
	ds_read_b128 v[170:173], v144
	ds_read_b128 v[174:177], v160
	ds_read_b128 v[178:181], v160 offset:1024
	ds_read_b128 v[182:185], v160 offset:2048
	ds_read_b128 v[186:189], v160 offset:3072
	ds_read_b128 v[190:193], v160 offset:4096
	ds_read_b128 v[194:197], v160 offset:5120
	ds_read_b128 v[198:201], v160 offset:6144
	ds_read_b128 v[202:205], v160 offset:7168
	s_nop 0
	v_lshl_add_u64 v[132:133], v[132:133], 0, s[20:21]
	global_load_lds_dwordx4 v[132:133], off
	v_lshl_add_u64 v[132:133], v[132:133], 0, s[10:11]
	s_mov_b32 m0, s34
	s_nop 0
	global_load_lds_dwordx4 v[132:133], off
	s_barrier
	s_waitcnt lgkmcnt(0)
	s_setprio 1
	s_waitcnt lgkmcnt(0)
	v_mfma_f32_16x16x32_bf16 v[124:127], v[134:137], v[174:177], v[124:127]
	v_mfma_f32_16x16x32_bf16 v[120:123], v[166:169], v[174:177], v[120:123]
	v_mfma_f32_16x16x32_bf16 v[108:111], v[134:137], v[190:193], v[108:111]
	v_mfma_f32_16x16x32_bf16 v[104:107], v[166:169], v[190:193], v[104:107]
	v_mfma_f32_16x16x32_bf16 v[124:127], v[162:165], v[178:181], v[124:127]
	v_mfma_f32_16x16x32_bf16 v[120:123], v[170:173], v[178:181], v[120:123]
	v_mfma_f32_16x16x32_bf16 v[116:119], v[134:137], v[182:185], v[116:119]
	v_mfma_f32_16x16x32_bf16 v[112:115], v[166:169], v[182:185], v[112:115]
	v_mfma_f32_16x16x32_bf16 v[108:111], v[162:165], v[194:197], v[108:111]
	v_mfma_f32_16x16x32_bf16 v[104:107], v[170:173], v[194:197], v[104:107]
	v_mfma_f32_16x16x32_bf16 v[100:103], v[134:137], v[198:201], v[100:103]
	v_mfma_f32_16x16x32_bf16 v[96:99], v[166:169], v[198:201], v[96:99]
	v_mfma_f32_16x16x32_bf16 v[206:209], v[162:165], v[186:189], v[116:119]
	v_mfma_f32_16x16x32_bf16 v[210:213], v[170:173], v[186:189], v[112:115]
	v_mfma_f32_16x16x32_bf16 v[214:217], v[162:165], v[202:205], v[100:103]
	v_mfma_f32_16x16x32_bf16 v[218:221], v[170:173], v[202:205], v[96:99]
	s_setprio 0
	s_barrier
	s_nop 1
	ds_read_b128 v[96:99], v145
	ds_read_b128 v[100:103], v146
	ds_read_b128 v[112:115], v147
	ds_read_b128 v[116:119], v148
	s_barrier
	s_waitcnt lgkmcnt(0)
	s_setprio 1
	s_waitcnt lgkmcnt(0)
	v_mfma_f32_16x16x32_bf16 v[92:95], v[96:99], v[174:177], v[92:95]
	v_mfma_f32_16x16x32_bf16 v[88:91], v[112:115], v[174:177], v[88:91]
	v_mfma_f32_16x16x32_bf16 v[76:79], v[96:99], v[190:193], v[76:79]
	v_mfma_f32_16x16x32_bf16 v[72:75], v[112:115], v[190:193], v[72:75]
	v_mfma_f32_16x16x32_bf16 v[92:95], v[100:103], v[178:181], v[92:95]
	v_mfma_f32_16x16x32_bf16 v[88:91], v[116:119], v[178:181], v[88:91]
	v_mfma_f32_16x16x32_bf16 v[84:87], v[96:99], v[182:185], v[84:87]
	v_mfma_f32_16x16x32_bf16 v[80:83], v[112:115], v[182:185], v[80:83]
	v_mfma_f32_16x16x32_bf16 v[76:79], v[100:103], v[194:197], v[76:79]
	v_mfma_f32_16x16x32_bf16 v[72:75], v[116:119], v[194:197], v[72:75]
	v_mfma_f32_16x16x32_bf16 v[68:71], v[96:99], v[198:201], v[68:71]
	v_mfma_f32_16x16x32_bf16 v[64:67], v[112:115], v[198:201], v[64:67]
	v_mfma_f32_16x16x32_bf16 v[174:177], v[100:103], v[186:189], v[84:87]
	v_mfma_f32_16x16x32_bf16 v[178:181], v[116:119], v[186:189], v[80:83]
	v_mfma_f32_16x16x32_bf16 v[182:185], v[100:103], v[202:205], v[68:71]
	v_mfma_f32_16x16x32_bf16 v[186:189], v[116:119], v[202:205], v[64:67]
	s_setprio 0
	s_barrier
; #define LDA(dst, b, h) for (int m = 0; m < 4; ++m) for (int k = 0; k < 2; ++k) \
;     dst[m][k] = *reinterpret_cast<const bf16x8*>(aRd + (((b) * 2 + (h)) * G_HT * 2 + m * 2048 + k * 1024))
; #define LDB(dst, b, h) for (int n = 0; n < 2; ++n) for (int k = 0; k < 2; ++k) \
;     dst[n][k] = *reinterpret_cast<const bf16x8*>(bRd + (((b) * 2 + (h)) * G_HT * 2 + n * 2048 + k * 1024))
; #define MMA(ai, bj, At, Bx) do { __builtin_amdgcn_s_setprio(1); \
;     for (int m = 0; m < 4; ++m) for (int n = 0; n < 2; ++n) for (int k = 0; k < 2; ++k) \
;       acc[ai][bj][m][n] = __builtin_amdgcn_mfma_f32_16x16x32_bf16(Bx[n][k], At[m][k], acc[ai][bj][m][n], 0, 0, 0);     \
;     __builtin_amdgcn_s_setprio(0); } while (0)
; #define WAIT_V(n) asm volatile("s_waitcnt vmcnt(" #n ")" ::: "memory")
; #define WAIT_L(n) asm volatile("s_waitcnt lgkmcnt(" #n ")" ::: "memory")
; #define BAR __builtin_amdgcn_s_barrier()
; template <int EPI>
; __device__ __forceinline__ void gemm_tile(const bf16* __restrict__ A, int lda, const bf16* __restrict__ Bt, int K,
;                                           int brow, int bcol, const EpiArgs& ea, char* shmc, bool has_next, int nbrow, int nbcol, bool first_tile) {
;     ...
;     LDA(At, 0, 1); WAIT_V(4); BAR; WAIT_L(0); MMA(1, 0, At, B0); MMA(1, 1, At, B1); BAR; }
;   { LDB(B0, 1, 0); LDA(At, 1, 0); WAIT_V(2); BAR; WAIT_L(0); MMA(0, 0, At, B0); BAR;
	s_nop 1
	ds_read_b128 v[64:67], v160 offset:16384
	ds_read_b128 v[68:71], v160 offset:17408
	ds_read_b128 v[80:83], v160 offset:18432
	ds_read_b128 v[84:87], v160 offset:19456
	ds_read_b128 v[190:193], v160 offset:20480
	ds_read_b128 v[194:197], v160 offset:21504
	ds_read_b128 v[198:201], v160 offset:22528
	ds_read_b128 v[202:205], v160 offset:23552
	s_waitcnt vmcnt(4)
	s_barrier
	s_waitcnt lgkmcnt(0)
	s_setprio 1
	s_waitcnt lgkmcnt(0)
	v_mfma_f32_16x16x32_bf16 v[60:63], v[134:137], v[64:67], v[60:63]
	v_mfma_f32_16x16x32_bf16 v[52:55], v[134:137], v[80:83], v[52:55]
	v_mfma_f32_16x16x32_bf16 v[48:51], v[166:169], v[80:83], v[48:51]
	v_mfma_f32_16x16x32_bf16 v[36:39], v[134:137], v[198:201], v[36:39]
	v_mfma_f32_16x16x32_bf16 v[32:35], v[166:169], v[198:201], v[32:35]
	v_mfma_f32_16x16x32_bf16 v[60:63], v[162:165], v[68:71], v[60:63]
	v_mfma_f32_16x16x32_bf16 v[56:59], v[166:169], v[64:67], v[56:59]
	v_mfma_f32_16x16x32_bf16 v[52:55], v[162:165], v[84:87], v[52:55]
	v_mfma_f32_16x16x32_bf16 v[48:51], v[170:173], v[84:87], v[48:51]
	v_mfma_f32_16x16x32_bf16 v[44:47], v[134:137], v[190:193], v[44:47]
	v_mfma_f32_16x16x32_bf16 v[40:43], v[166:169], v[190:193], v[40:43]
	v_mfma_f32_16x16x32_bf16 v[36:39], v[162:165], v[202:205], v[36:39]
	v_mfma_f32_16x16x32_bf16 v[32:35], v[170:173], v[202:205], v[32:35]
	v_mfma_f32_16x16x32_bf16 v[222:225], v[170:173], v[68:71], v[56:59]
	v_mfma_f32_16x16x32_bf16 v[226:229], v[162:165], v[194:197], v[44:47]
	v_mfma_f32_16x16x32_bf16 v[230:233], v[170:173], v[194:197], v[40:43]
	s_setprio 0
	s_setprio 1
	v_mfma_f32_16x16x32_bf16 v[20:23], v[96:99], v[80:83], v[20:23]
	v_mfma_f32_16x16x32_bf16 v[16:19], v[112:115], v[80:83], v[16:19]
	v_mfma_f32_16x16x32_bf16 v[12:15], v[96:99], v[190:193], v[12:15]
	v_mfma_f32_16x16x32_bf16 v[8:11], v[112:115], v[190:193], v[8:11]
	v_mfma_f32_16x16x32_bf16 v[28:31], v[96:99], v[64:67], v[28:31]
	v_mfma_f32_16x16x32_bf16 v[24:27], v[112:115], v[64:67], v[24:27]
	v_mfma_f32_16x16x32_bf16 v[20:23], v[100:103], v[84:87], v[20:23]
	v_mfma_f32_16x16x32_bf16 v[16:19], v[116:119], v[84:87], v[16:19]
	v_mfma_f32_16x16x32_bf16 v[12:15], v[100:103], v[194:197], v[12:15]
	v_mfma_f32_16x16x32_bf16 v[8:11], v[116:119], v[194:197], v[8:11]
	v_mfma_f32_16x16x32_bf16 v[4:7], v[96:99], v[198:201], v[4:7]
	v_mfma_f32_16x16x32_bf16 v[0:3], v[112:115], v[198:201], v[0:3]
	v_mfma_f32_16x16x32_bf16 v[132:135], v[100:103], v[68:71], v[28:31]
	v_mfma_f32_16x16x32_bf16 v[136:139], v[116:119], v[68:71], v[24:27]
	v_mfma_f32_16x16x32_bf16 v[162:165], v[100:103], v[202:205], v[4:7]
	v_mfma_f32_16x16x32_bf16 v[166:169], v[116:119], v[202:205], v[0:3]
	s_setprio 0
	s_barrier
	s_nop 1
	ds_read_b128 v[0:3], v149
	ds_read_b128 v[4:7], v150
	ds_read_b128 v[170:173], v151
	ds_read_b128 v[190:193], v152
	ds_read_b128 v[24:27], v160 offset:32768
	ds_read_b128 v[28:31], v160 offset:33792
	ds_read_b128 v[40:43], v160 offset:34816
	ds_read_b128 v[44:47], v160 offset:35840
	ds_read_b128 v[56:59], v160 offset:36864
	ds_read_b128 v[194:197], v160 offset:37888
	ds_read_b128 v[198:201], v160 offset:38912
	ds_read_b128 v[202:205], v160 offset:39936
	s_waitcnt vmcnt(2)
	s_barrier
	s_waitcnt lgkmcnt(0)
	s_setprio 1
	s_waitcnt lgkmcnt(0)
	v_mfma_f32_16x16x32_bf16 v[64:67], v[0:3], v[24:27], v[124:127]
	v_mfma_f32_16x16x32_bf16 v[112:115], v[4:7], v[28:31], v[64:67]
	v_mfma_f32_16x16x32_bf16 v[64:67], v[170:173], v[24:27], v[120:123]
	v_mfma_f32_16x16x32_bf16 v[116:119], v[190:193], v[28:31], v[64:67]
	v_mfma_f32_16x16x32_bf16 v[64:67], v[0:3], v[40:43], v[206:209]
	v_mfma_f32_16x16x32_bf16 v[96:99], v[4:7], v[44:47], v[64:67]
	v_mfma_f32_16x16x32_bf16 v[64:67], v[170:173], v[40:43], v[210:213]
	v_mfma_f32_16x16x32_bf16 v[100:103], v[190:193], v[44:47], v[64:67]
	v_mfma_f32_16x16x32_bf16 v[64:67], v[0:3], v[56:59], v[108:111]
	v_mfma_f32_16x16x32_bf16 v[80:83], v[4:7], v[194:197], v[64:67]
	v_mfma_f32_16x16x32_bf16 v[64:67], v[170:173], v[56:59], v[104:107]
	v_mfma_f32_16x16x32_bf16 v[84:87], v[190:193], v[194:197], v[64:67]
	v_mfma_f32_16x16x32_bf16 v[64:67], v[0:3], v[198:201], v[214:217]
	v_mfma_f32_16x16x32_bf16 v[68:71], v[170:173], v[198:201], v[218:221]
	v_mfma_f32_16x16x32_bf16 v[64:67], v[4:7], v[202:205], v[64:67]
	v_mfma_f32_16x16x32_bf16 v[68:71], v[190:193], v[202:205], v[68:71]
	s_setprio 0
	s_barrier
; #define LDA(dst, b, h) for (int m = 0; m < 4; ++m) for (int k = 0; k < 2; ++k) \
;     dst[m][k] = *reinterpret_cast<const bf16x8*>(aRd + (((b) * 2 + (h)) * G_HT * 2 + m * 2048 + k * 1024))
; #define LDB(dst, b, h) for (int n = 0; n < 2; ++n) for (int k = 0; k < 2; ++k) \
;     dst[n][k] = *reinterpret_cast<const bf16x8*>(bRd + (((b) * 2 + (h)) * G_HT * 2 + n * 2048 + k * 1024))
; #define MMA(ai, bj, At, Bx) do { __builtin_amdgcn_s_setprio(1); \
;     for (int m = 0; m < 4; ++m) for (int n = 0; n < 2; ++n) for (int k = 0; k < 2; ++k) \
;       acc[ai][bj][m][n] = __builtin_amdgcn_mfma_f32_16x16x32_bf16(Bx[n][k], At[m][k], acc[ai][bj][m][n], 0, 0, 0);     \
;     __builtin_amdgcn_s_setprio(0); } while (0)
; #define WAIT_V(n) asm volatile("s_waitcnt vmcnt(" #n ")" ::: "memory")
; #define WAIT_L(n) asm volatile("s_waitcnt lgkmcnt(" #n ")" ::: "memory")
; #define BAR __builtin_amdgcn_s_barrier()
; template <int EPI>
; __device__ __forceinline__ void gemm_tile(const bf16* __restrict__ A, int lda, const bf16* __restrict__ Bt, int K,
;                                           int brow, int bcol, const EpiArgs& ea, char* shmc, bool has_next, int nbrow, int nbcol, bool first_tile) {
;     ...
;     LDB(B1, 1, 1); WAIT_V(0); BAR; WAIT_L(0); MMA(0, 1, At, B1); BAR;
;     LDA(At, 1, 1); BAR; WAIT_L(0); MMA(1, 0, At, B0); MMA(1, 1, At, B1); BAR; }
;   if (wr == 0) BAR;
	ds_read_b128 v[206:209], v153
	ds_read_b128 v[210:213], v154
	ds_read_b128 v[214:217], v155
	ds_read_b128 v[218:221], v156
	s_waitcnt vmcnt(0)
	s_barrier
	s_waitcnt lgkmcnt(0)
	s_setprio 1
	s_waitcnt lgkmcnt(0)
	v_mfma_f32_16x16x32_bf16 v[92:95], v[206:209], v[24:27], v[92:95]
	v_mfma_f32_16x16x32_bf16 v[24:27], v[214:217], v[24:27], v[88:91]
	v_mfma_f32_16x16x32_bf16 v[124:127], v[218:221], v[28:31], v[24:27]
	v_mfma_f32_16x16x32_bf16 v[24:27], v[206:209], v[40:43], v[174:177]
	v_mfma_f32_16x16x32_bf16 v[104:107], v[210:213], v[44:47], v[24:27]
	v_mfma_f32_16x16x32_bf16 v[24:27], v[214:217], v[40:43], v[178:181]
	v_mfma_f32_16x16x32_bf16 v[108:111], v[218:221], v[44:47], v[24:27]
	v_mfma_f32_16x16x32_bf16 v[24:27], v[206:209], v[56:59], v[76:79]
	v_mfma_f32_16x16x32_bf16 v[88:91], v[210:213], v[194:197], v[24:27]
	v_mfma_f32_16x16x32_bf16 v[24:27], v[214:217], v[56:59], v[72:75]
	v_mfma_f32_16x16x32_bf16 v[120:123], v[210:213], v[28:31], v[92:95]
	v_mfma_f32_16x16x32_bf16 v[92:95], v[218:221], v[194:197], v[24:27]
	v_mfma_f32_16x16x32_bf16 v[24:27], v[206:209], v[198:201], v[182:185]
	v_mfma_f32_16x16x32_bf16 v[72:75], v[210:213], v[202:205], v[24:27]
	v_mfma_f32_16x16x32_bf16 v[24:27], v[214:217], v[198:201], v[186:189]
	v_mfma_f32_16x16x32_bf16 v[76:79], v[218:221], v[202:205], v[24:27]
	s_setprio 0
	s_barrier
	ds_read_b128 v[174:177], v160 offset:49152
	ds_read_b128 v[178:181], v160 offset:50176
	ds_read_b128 v[182:185], v160 offset:51200
	ds_read_b128 v[186:189], v160 offset:52224
	ds_read_b128 v[194:197], v160 offset:53248
	ds_read_b128 v[198:201], v160 offset:54272
	ds_read_b128 v[202:205], v160 offset:55296
	ds_read_b128 v[234:237], v160 offset:56320
	s_barrier
	s_waitcnt lgkmcnt(0)
	s_setprio 1
	s_waitcnt lgkmcnt(0)
	v_mfma_f32_16x16x32_bf16 v[24:27], v[0:3], v[174:177], v[60:63]
	v_mfma_f32_16x16x32_bf16 v[56:59], v[4:7], v[178:181], v[24:27]
	v_mfma_f32_16x16x32_bf16 v[24:27], v[170:173], v[174:177], v[222:225]
	v_mfma_f32_16x16x32_bf16 v[60:63], v[190:193], v[178:181], v[24:27]
	v_mfma_f32_16x16x32_bf16 v[24:27], v[0:3], v[182:185], v[52:55]
	v_mfma_f32_16x16x32_bf16 v[40:43], v[4:7], v[186:189], v[24:27]
	v_mfma_f32_16x16x32_bf16 v[24:27], v[170:173], v[182:185], v[48:51]
	v_mfma_f32_16x16x32_bf16 v[44:47], v[190:193], v[186:189], v[24:27]
	v_mfma_f32_16x16x32_bf16 v[24:27], v[0:3], v[194:197], v[226:229]
	v_mfma_f32_16x16x32_bf16 v[0:3], v[0:3], v[202:205], v[36:39]
	v_mfma_f32_16x16x32_bf16 v[24:27], v[4:7], v[198:201], v[24:27]
	v_mfma_f32_16x16x32_bf16 v[28:31], v[170:173], v[194:197], v[230:233]
	v_mfma_f32_16x16x32_bf16 v[0:3], v[4:7], v[234:237], v[0:3]
	v_mfma_f32_16x16x32_bf16 v[4:7], v[170:173], v[202:205], v[32:35]
	v_mfma_f32_16x16x32_bf16 v[28:31], v[190:193], v[198:201], v[28:31]
	v_mfma_f32_16x16x32_bf16 v[4:7], v[190:193], v[234:237], v[4:7]
	s_setprio 0
	s_setprio 1
	v_mfma_f32_16x16x32_bf16 v[32:35], v[206:209], v[174:177], v[132:135]
	v_mfma_f32_16x16x32_bf16 v[48:51], v[210:213], v[178:181], v[32:35]
	v_mfma_f32_16x16x32_bf16 v[32:35], v[214:217], v[174:177], v[136:139]
	v_mfma_f32_16x16x32_bf16 v[20:23], v[206:209], v[182:185], v[20:23]
	v_mfma_f32_16x16x32_bf16 v[16:19], v[214:217], v[182:185], v[16:19]
	v_mfma_f32_16x16x32_bf16 v[12:15], v[206:209], v[194:197], v[12:15]
	v_mfma_f32_16x16x32_bf16 v[8:11], v[214:217], v[194:197], v[8:11]
	v_mfma_f32_16x16x32_bf16 v[52:55], v[218:221], v[178:181], v[32:35]
	v_mfma_f32_16x16x32_bf16 v[32:35], v[210:213], v[186:189], v[20:23]
	v_mfma_f32_16x16x32_bf16 v[36:39], v[218:221], v[186:189], v[16:19]
	v_mfma_f32_16x16x32_bf16 v[16:19], v[210:213], v[198:201], v[12:15]
	v_mfma_f32_16x16x32_bf16 v[20:23], v[218:221], v[198:201], v[8:11]
	v_mfma_f32_16x16x32_bf16 v[8:11], v[206:209], v[202:205], v[162:165]
	v_mfma_f32_16x16x32_bf16 v[12:15], v[214:217], v[202:205], v[166:169]
	v_mfma_f32_16x16x32_bf16 v[8:11], v[210:213], v[234:237], v[8:11]
	v_mfma_f32_16x16x32_bf16 v[12:15], v[218:221], v[234:237], v[12:15]
	s_setprio 0
	s_barrier
	s_and_saveexec_b64 s[20:21], s[4:5]
	s_cbranch_execz .LBB0_730
	s_barrier

; #define STA(b, h, half, kt) STAGE(((b) * 2 + (h)) * G_HT * 2, pA, ((size_t)(half) * G_HALF * lda + (size_t)(kt) * G_BK) * 2, lda)
; #define STB(b, h, half, kt) STAGE((4 + (b) * 2 + (h)) * G_HT * 2, pB, ((size_t)(half) * G_HALF * K + (size_t)(kt) * G_BK) * 2, K)
; #define LDA(dst, b, h) for (int m = 0; m < 4; ++m) for (int k = 0; k < 2; ++k) \
;     dst[m][k] = *reinterpret_cast<const bf16x8*>(aRd + (((b) * 2 + (h)) * G_HT * 2 + m * 2048 + k * 1024))
; #define LDB(dst, b, h) for (int n = 0; n < 2; ++n) for (int k = 0; k < 2; ++k) \
;     dst[n][k] = *reinterpret_cast<const bf16x8*>(bRd + (((b) * 2 + (h)) * G_HT * 2 + n * 2048 + k * 1024))
; #define MMA(ai, bj, At, Bx) do { __builtin_amdgcn_s_setprio(1); \
;     for (int m = 0; m < 4; ++m) for (int n = 0; n < 2; ++n) for (int k = 0; k < 2; ++k) \
;       acc[ai][bj][m][n] = __builtin_amdgcn_mfma_f32_16x16x32_bf16(Bx[n][k], At[m][k], acc[ai][bj][m][n], 0, 0, 0);     \
;     __builtin_amdgcn_s_setprio(0); } while (0)
; #define WAIT_V(n) asm volatile("s_waitcnt vmcnt(" #n ")" ::: "memory")
; #define WAIT_L(n) asm volatile("s_waitcnt lgkmcnt(" #n ")" ::: "memory")
; #define BAR __builtin_amdgcn_s_barrier()
; #define SCHED __builtin_amdgcn_sched_barrier(0)
; template <int EPI>
; __device__ __forceinline__ void gemm_tile(const bf16* __restrict__ A, int lda, const bf16* __restrict__ Bt, int K,
;                                           int brow, int bcol, const EpiArgs& ea, char* shmc, bool has_next, int nbrow, int nbcol, bool first_tile) {
;     ...
;   for (int t = 0; t < nt - 2; t += 2) {
;     LDB(B0, 0, 0); SCHED; LDA(At, 0, 0); STA(1, 1, 1, t + 1);
;     WAIT_L(8); BAR; WAIT_L(0); MMA(0, 0, At, B0); BAR; SCHED;
;     LDB(B1, 0, 1); STB(0, 0, 0, t + 2);
;     BAR; WAIT_L(0); MMA(0, 1, At, B1); BAR;
;     LDA(At, 0, 1); STA(0, 0, 0, t + 2);
;     BAR; WAIT_L(0); MMA(1, 0, At, B0); BAR; SCHED;
;     STB(0, 1, 1, t + 2);
;     WAIT_V(6); BAR; MMA(1, 1, At, B1); BAR;
.LBB0_784:
	ds_read_b128 v[136:139], v141
	ds_read_b128 v[162:165], v142
	ds_read_b128 v[166:169], v143
	ds_read_b128 v[170:173], v144
	s_add_u32 s40, s18, 0xffffff00
	s_addc_u32 s41, s19, -1
	s_mov_b32 m0, s34
	ds_read_b128 v[174:177], v160
	ds_read_b128 v[178:181], v160 offset:1024
	ds_read_b128 v[182:185], v160 offset:2048
	ds_read_b128 v[186:189], v160 offset:3072
	ds_read_b128 v[190:193], v160 offset:4096
	ds_read_b128 v[194:197], v160 offset:5120
	ds_read_b128 v[198:201], v160 offset:6144
	ds_read_b128 v[202:205], v160 offset:7168
	v_lshl_add_u64 v[206:207], v[132:133], 0, s[40:41]
	global_load_lds_dwordx4 v[206:207], off
	s_mov_b32 m0, s24
	v_lshl_add_u64 v[206:207], v[206:207], 0, s[4:5]
	global_load_lds_dwordx4 v[206:207], off
	s_waitcnt lgkmcnt(8)
	s_barrier
	s_waitcnt lgkmcnt(0)
	s_setprio 1
	v_mfma_f32_16x16x32_bf16 v[124:127], v[136:139], v[174:177], v[124:127]
	v_mfma_f32_16x16x32_bf16 v[120:123], v[166:169], v[174:177], v[120:123]
	v_mfma_f32_16x16x32_bf16 v[116:119], v[136:139], v[182:185], v[116:119]
	v_mfma_f32_16x16x32_bf16 v[112:115], v[166:169], v[182:185], v[112:115]
	v_mfma_f32_16x16x32_bf16 v[108:111], v[136:139], v[190:193], v[108:111]
	v_mfma_f32_16x16x32_bf16 v[104:107], v[166:169], v[190:193], v[104:107]
	v_mfma_f32_16x16x32_bf16 v[100:103], v[136:139], v[198:201], v[100:103]
	v_mfma_f32_16x16x32_bf16 v[96:99], v[166:169], v[198:201], v[96:99]
	v_mfma_f32_16x16x32_bf16 v[124:127], v[162:165], v[178:181], v[124:127]
	v_mfma_f32_16x16x32_bf16 v[120:123], v[170:173], v[178:181], v[120:123]
	v_mfma_f32_16x16x32_bf16 v[116:119], v[162:165], v[186:189], v[116:119]
	v_mfma_f32_16x16x32_bf16 v[112:115], v[170:173], v[186:189], v[112:115]
	v_mfma_f32_16x16x32_bf16 v[108:111], v[162:165], v[194:197], v[108:111]
	v_mfma_f32_16x16x32_bf16 v[104:107], v[170:173], v[194:197], v[104:107]
	v_mfma_f32_16x16x32_bf16 v[100:103], v[162:165], v[202:205], v[100:103]
	v_mfma_f32_16x16x32_bf16 v[96:99], v[170:173], v[202:205], v[96:99]
	s_setprio 0
	s_barrier
	s_add_u32 s40, s18, 0xffbfff80
	s_addc_u32 s41, s19, -1
	s_mov_b32 m0, s27
	ds_read_b128 v[206:209], v145
	ds_read_b128 v[210:213], v146
	ds_read_b128 v[214:217], v147
	ds_read_b128 v[218:221], v148
	v_lshl_add_u64 v[222:223], v[134:135], 0, s[40:41]
	global_load_lds_dwordx4 v[222:223], off
	s_mov_b32 m0, s28
	v_lshl_add_u64 v[222:223], v[222:223], 0, s[4:5]
	global_load_lds_dwordx4 v[222:223], off
	s_barrier
	s_waitcnt lgkmcnt(0)
	s_setprio 1
	v_mfma_f32_16x16x32_bf16 v[92:95], v[206:209], v[174:177], v[92:95]
	v_mfma_f32_16x16x32_bf16 v[88:91], v[214:217], v[174:177], v[88:91]
	v_mfma_f32_16x16x32_bf16 v[84:87], v[206:209], v[182:185], v[84:87]
	v_mfma_f32_16x16x32_bf16 v[80:83], v[214:217], v[182:185], v[80:83]
	v_mfma_f32_16x16x32_bf16 v[76:79], v[206:209], v[190:193], v[76:79]
	v_mfma_f32_16x16x32_bf16 v[72:75], v[214:217], v[190:193], v[72:75]
	v_mfma_f32_16x16x32_bf16 v[68:71], v[206:209], v[198:201], v[68:71]
	v_mfma_f32_16x16x32_bf16 v[64:67], v[214:217], v[198:201], v[64:67]
	v_mfma_f32_16x16x32_bf16 v[92:95], v[210:213], v[178:181], v[92:95]
	v_mfma_f32_16x16x32_bf16 v[88:91], v[218:221], v[178:181], v[88:91]
	v_mfma_f32_16x16x32_bf16 v[84:87], v[210:213], v[186:189], v[84:87]
	v_mfma_f32_16x16x32_bf16 v[80:83], v[218:221], v[186:189], v[80:83]
	v_mfma_f32_16x16x32_bf16 v[76:79], v[210:213], v[194:197], v[76:79]
	v_mfma_f32_16x16x32_bf16 v[72:75], v[218:221], v[194:197], v[72:75]
	v_mfma_f32_16x16x32_bf16 v[68:71], v[210:213], v[202:205], v[68:71]
	v_mfma_f32_16x16x32_bf16 v[64:67], v[218:221], v[202:205], v[64:67]
	s_setprio 0
	s_mov_b32 m0, s15
	s_barrier
	ds_read_b128 v[174:177], v160 offset:16384
	ds_read_b128 v[178:181], v160 offset:17408
	ds_read_b128 v[182:185], v160 offset:18432
	ds_read_b128 v[186:189], v160 offset:19456
	ds_read_b128 v[190:193], v160 offset:20480
	ds_read_b128 v[194:197], v160 offset:21504
	ds_read_b128 v[198:201], v160 offset:22528
	ds_read_b128 v[202:205], v160 offset:23552
	v_lshl_add_u64 v[222:223], v[132:133], 0, s[40:41]
	global_load_lds_dwordx4 v[222:223], off
	s_mov_b32 m0, s35
	v_lshl_add_u64 v[222:223], v[222:223], 0, s[4:5]
	global_load_lds_dwordx4 v[222:223], off
	s_barrier
	s_waitcnt lgkmcnt(0)
	s_setprio 1
	v_mfma_f32_16x16x32_bf16 v[60:63], v[136:139], v[174:177], v[60:63]
	v_mfma_f32_16x16x32_bf16 v[56:59], v[166:169], v[174:177], v[56:59]
	v_mfma_f32_16x16x32_bf16 v[52:55], v[136:139], v[182:185], v[52:55]
	v_mfma_f32_16x16x32_bf16 v[48:51], v[166:169], v[182:185], v[48:51]
	v_mfma_f32_16x16x32_bf16 v[44:47], v[136:139], v[190:193], v[44:47]
	v_mfma_f32_16x16x32_bf16 v[40:43], v[166:169], v[190:193], v[40:43]
	v_mfma_f32_16x16x32_bf16 v[36:39], v[136:139], v[198:201], v[36:39]
	v_mfma_f32_16x16x32_bf16 v[32:35], v[166:169], v[198:201], v[32:35]
	v_mfma_f32_16x16x32_bf16 v[60:63], v[162:165], v[178:181], v[60:63]
	v_mfma_f32_16x16x32_bf16 v[56:59], v[170:173], v[178:181], v[56:59]
	v_mfma_f32_16x16x32_bf16 v[52:55], v[162:165], v[186:189], v[52:55]
	v_mfma_f32_16x16x32_bf16 v[48:51], v[170:173], v[186:189], v[48:51]
	v_mfma_f32_16x16x32_bf16 v[44:47], v[162:165], v[194:197], v[44:47]
	v_mfma_f32_16x16x32_bf16 v[40:43], v[170:173], v[194:197], v[40:43]
	v_mfma_f32_16x16x32_bf16 v[36:39], v[162:165], v[202:205], v[36:39]
	v_mfma_f32_16x16x32_bf16 v[32:35], v[170:173], v[202:205], v[32:35]
	s_setprio 0
	s_barrier
	s_add_u32 s40, s18, 0xffffff80
	s_addc_u32 s41, s19, -1
	s_mov_b32 m0, s29
	v_lshl_add_u64 v[136:137], v[134:135], 0, s[40:41]
	global_load_lds_dwordx4 v[136:137], off
	s_mov_b32 m0, s30
	v_lshl_add_u64 v[136:137], v[136:137], 0, s[4:5]
	global_load_lds_dwordx4 v[136:137], off
	s_waitcnt vmcnt(6)
	s_barrier
; #define STA(b, h, half, kt) STAGE(((b) * 2 + (h)) * G_HT * 2, pA, ((size_t)(half) * G_HALF * lda + (size_t)(kt) * G_BK) * 2, lda)
; #define STB(b, h, half, kt) STAGE((4 + (b) * 2 + (h)) * G_HT * 2, pB, ((size_t)(half) * G_HALF * K + (size_t)(kt) * G_BK) * 2, K)
; #define LDA(dst, b, h) for (int m = 0; m < 4; ++m) for (int k = 0; k < 2; ++k) \
;     dst[m][k] = *reinterpret_cast<const bf16x8*>(aRd + (((b) * 2 + (h)) * G_HT * 2 + m * 2048 + k * 1024))
; #define LDB(dst, b, h) for (int n = 0; n < 2; ++n) for (int k = 0; k < 2; ++k) \
;     dst[n][k] = *reinterpret_cast<const bf16x8*>(bRd + (((b) * 2 + (h)) * G_HT * 2 + n * 2048 + k * 1024))
; #define MMA(ai, bj, At, Bx) do { __builtin_amdgcn_s_setprio(1); \
;     for (int m = 0; m < 4; ++m) for (int n = 0; n < 2; ++n) for (int k = 0; k < 2; ++k) \
;       acc[ai][bj][m][n] = __builtin_amdgcn_mfma_f32_16x16x32_bf16(Bx[n][k], At[m][k], acc[ai][bj][m][n], 0, 0, 0);     \
;     __builtin_amdgcn_s_setprio(0); } while (0)
; #define WAIT_V(n) asm volatile("s_waitcnt vmcnt(" #n ")" ::: "memory")
; #define WAIT_L(n) asm volatile("s_waitcnt lgkmcnt(" #n ")" ::: "memory")
; #define BAR __builtin_amdgcn_s_barrier()
; #define SCHED __builtin_amdgcn_sched_barrier(0)
; template <int EPI>
; __device__ __forceinline__ void gemm_tile(const bf16* __restrict__ A, int lda, const bf16* __restrict__ Bt, int K,
;                                           int brow, int bcol, const EpiArgs& ea, char* shmc, bool has_next, int nbrow, int nbcol, bool first_tile) {
;     ...
;     WAIT_V(6); BAR; MMA(1, 1, At, B1); BAR;
;     LDB(B0, 1, 0); SCHED; LDA(At, 1, 0); STA(0, 1, 1, t + 2);
;     WAIT_L(8); BAR; WAIT_L(0); MMA(0, 0, At, B0); BAR; SCHED;
;     LDB(B1, 1, 1); STB(1, 0, 0, t + 3);
;     BAR; WAIT_L(0); MMA(0, 1, At, B1); BAR;
;     LDA(At, 1, 1); STA(1, 0, 0, t + 3);
;     BAR; WAIT_L(0); MMA(1, 0, At, B0); BAR; SCHED;
	s_setprio 1
	v_mfma_f32_16x16x32_bf16 v[28:31], v[206:209], v[174:177], v[28:31]
	v_mfma_f32_16x16x32_bf16 v[24:27], v[214:217], v[174:177], v[24:27]
	v_mfma_f32_16x16x32_bf16 v[20:23], v[206:209], v[182:185], v[20:23]
	v_mfma_f32_16x16x32_bf16 v[16:19], v[214:217], v[182:185], v[16:19]
	v_mfma_f32_16x16x32_bf16 v[12:15], v[206:209], v[190:193], v[12:15]
	v_mfma_f32_16x16x32_bf16 v[8:11], v[214:217], v[190:193], v[8:11]
	v_mfma_f32_16x16x32_bf16 v[4:7], v[206:209], v[198:201], v[4:7]
	v_mfma_f32_16x16x32_bf16 v[0:3], v[214:217], v[198:201], v[0:3]
	v_mfma_f32_16x16x32_bf16 v[28:31], v[210:213], v[178:181], v[28:31]
	v_mfma_f32_16x16x32_bf16 v[24:27], v[218:221], v[178:181], v[24:27]
	v_mfma_f32_16x16x32_bf16 v[20:23], v[210:213], v[186:189], v[20:23]
	v_mfma_f32_16x16x32_bf16 v[16:19], v[218:221], v[186:189], v[16:19]
	v_mfma_f32_16x16x32_bf16 v[12:15], v[210:213], v[194:197], v[12:15]
	v_mfma_f32_16x16x32_bf16 v[8:11], v[218:221], v[194:197], v[8:11]
	v_mfma_f32_16x16x32_bf16 v[4:7], v[210:213], v[202:205], v[4:7]
	v_mfma_f32_16x16x32_bf16 v[0:3], v[218:221], v[202:205], v[0:3]
	s_setprio 0
	s_barrier
	ds_read_b128 v[136:139], v149
	ds_read_b128 v[162:165], v150
	ds_read_b128 v[166:169], v151
	ds_read_b128 v[170:173], v152
	s_mov_b32 m0, s36
	ds_read_b128 v[174:177], v160 offset:32768
	ds_read_b128 v[178:181], v160 offset:33792
	ds_read_b128 v[182:185], v160 offset:34816
	ds_read_b128 v[186:189], v160 offset:35840
	ds_read_b128 v[190:193], v160 offset:36864
	ds_read_b128 v[194:197], v160 offset:37888
	ds_read_b128 v[198:201], v160 offset:38912
	ds_read_b128 v[202:205], v160 offset:39936
	v_lshl_add_u64 v[206:207], v[132:133], 0, s[40:41]
	global_load_lds_dwordx4 v[206:207], off
	s_mov_b32 m0, s37
	v_lshl_add_u64 v[206:207], v[206:207], 0, s[4:5]
	global_load_lds_dwordx4 v[206:207], off
	s_waitcnt lgkmcnt(8)
	s_barrier
	s_waitcnt lgkmcnt(0)
	s_setprio 1
	v_mfma_f32_16x16x32_bf16 v[124:127], v[136:139], v[174:177], v[124:127]
	v_mfma_f32_16x16x32_bf16 v[120:123], v[166:169], v[174:177], v[120:123]
	v_mfma_f32_16x16x32_bf16 v[116:119], v[136:139], v[182:185], v[116:119]
	v_mfma_f32_16x16x32_bf16 v[112:115], v[166:169], v[182:185], v[112:115]
	v_mfma_f32_16x16x32_bf16 v[108:111], v[136:139], v[190:193], v[108:111]
	v_mfma_f32_16x16x32_bf16 v[104:107], v[166:169], v[190:193], v[104:107]
	v_mfma_f32_16x16x32_bf16 v[100:103], v[136:139], v[198:201], v[100:103]
	v_mfma_f32_16x16x32_bf16 v[96:99], v[166:169], v[198:201], v[96:99]
	v_mfma_f32_16x16x32_bf16 v[124:127], v[162:165], v[178:181], v[124:127]
	v_mfma_f32_16x16x32_bf16 v[120:123], v[170:173], v[178:181], v[120:123]
	v_mfma_f32_16x16x32_bf16 v[116:119], v[162:165], v[186:189], v[116:119]
	v_mfma_f32_16x16x32_bf16 v[112:115], v[170:173], v[186:189], v[112:115]
	v_mfma_f32_16x16x32_bf16 v[108:111], v[162:165], v[194:197], v[108:111]
	v_mfma_f32_16x16x32_bf16 v[104:107], v[170:173], v[194:197], v[104:107]
	v_mfma_f32_16x16x32_bf16 v[100:103], v[162:165], v[202:205], v[100:103]
	v_mfma_f32_16x16x32_bf16 v[96:99], v[170:173], v[202:205], v[96:99]
	s_setprio 0
	s_barrier
	s_add_u32 s40, s18, 0xffc00000
	s_addc_u32 s41, s19, -1
	s_mov_b32 m0, s17
	ds_read_b128 v[206:209], v153
	ds_read_b128 v[210:213], v154
	ds_read_b128 v[214:217], v155
	ds_read_b128 v[218:221], v156
	v_lshl_add_u64 v[222:223], v[134:135], 0, s[40:41]
	global_load_lds_dwordx4 v[222:223], off
	s_mov_b32 m0, s21
	v_lshl_add_u64 v[222:223], v[222:223], 0, s[4:5]
	global_load_lds_dwordx4 v[222:223], off
	s_barrier
	s_waitcnt lgkmcnt(0)
	s_setprio 1
	v_mfma_f32_16x16x32_bf16 v[92:95], v[206:209], v[174:177], v[92:95]
	v_mfma_f32_16x16x32_bf16 v[88:91], v[214:217], v[174:177], v[88:91]
	v_mfma_f32_16x16x32_bf16 v[84:87], v[206:209], v[182:185], v[84:87]
	v_mfma_f32_16x16x32_bf16 v[80:83], v[214:217], v[182:185], v[80:83]
	v_mfma_f32_16x16x32_bf16 v[76:79], v[206:209], v[190:193], v[76:79]
	v_mfma_f32_16x16x32_bf16 v[72:75], v[214:217], v[190:193], v[72:75]
	v_mfma_f32_16x16x32_bf16 v[68:71], v[206:209], v[198:201], v[68:71]
	v_mfma_f32_16x16x32_bf16 v[64:67], v[214:217], v[198:201], v[64:67]
	v_mfma_f32_16x16x32_bf16 v[92:95], v[210:213], v[178:181], v[92:95]
	v_mfma_f32_16x16x32_bf16 v[88:91], v[218:221], v[178:181], v[88:91]
	v_mfma_f32_16x16x32_bf16 v[84:87], v[210:213], v[186:189], v[84:87]
	v_mfma_f32_16x16x32_bf16 v[80:83], v[218:221], v[186:189], v[80:83]
	v_mfma_f32_16x16x32_bf16 v[76:79], v[210:213], v[194:197], v[76:79]
	v_mfma_f32_16x16x32_bf16 v[72:75], v[218:221], v[194:197], v[72:75]
	v_mfma_f32_16x16x32_bf16 v[68:71], v[210:213], v[202:205], v[68:71]
	v_mfma_f32_16x16x32_bf16 v[64:67], v[218:221], v[202:205], v[64:67]
	s_setprio 0
	s_mov_b32 m0, s22
	s_barrier
	ds_read_b128 v[174:177], v160 offset:49152
	ds_read_b128 v[178:181], v160 offset:50176
	ds_read_b128 v[182:185], v160 offset:51200
	ds_read_b128 v[186:189], v160 offset:52224
	ds_read_b128 v[190:193], v160 offset:53248
	ds_read_b128 v[194:197], v160 offset:54272
	ds_read_b128 v[198:201], v160 offset:55296
	ds_read_b128 v[202:205], v160 offset:56320
	v_lshl_add_u64 v[222:223], v[132:133], 0, s[40:41]
	global_load_lds_dwordx4 v[222:223], off
	s_mov_b32 m0, s23
	v_lshl_add_u64 v[222:223], v[222:223], 0, s[4:5]
	global_load_lds_dwordx4 v[222:223], off
	s_barrier
; #define STA(b, h, half, kt) STAGE(((b) * 2 + (h)) * G_HT * 2, pA, ((size_t)(half) * G_HALF * lda + (size_t)(kt) * G_BK) * 2, lda)
; #define STB(b, h, half, kt) STAGE((4 + (b) * 2 + (h)) * G_HT * 2, pB, ((size_t)(half) * G_HALF * K + (size_t)(kt) * G_BK) * 2, K)
; #define LDA(dst, b, h) for (int m = 0; m < 4; ++m) for (int k = 0; k < 2; ++k) \
;     dst[m][k] = *reinterpret_cast<const bf16x8*>(aRd + (((b) * 2 + (h)) * G_HT * 2 + m * 2048 + k * 1024))
; #define LDB(dst, b, h) for (int n = 0; n < 2; ++n) for (int k = 0; k < 2; ++k) \
;     dst[n][k] = *reinterpret_cast<const bf16x8*>(bRd + (((b) * 2 + (h)) * G_HT * 2 + n * 2048 + k * 1024))
; #define MMA(ai, bj, At, Bx) do { __builtin_amdgcn_s_setprio(1); \
;     for (int m = 0; m < 4; ++m) for (int n = 0; n < 2; ++n) for (int k = 0; k < 2; ++k) \
;       acc[ai][bj][m][n] = __builtin_amdgcn_mfma_f32_16x16x32_bf16(Bx[n][k], At[m][k], acc[ai][bj][m][n], 0, 0, 0);     \
;     __builtin_amdgcn_s_setprio(0); } while (0)
; #define WAIT_V(n) asm volatile("s_waitcnt vmcnt(" #n ")" ::: "memory")
; #define WAIT_L(n) asm volatile("s_waitcnt lgkmcnt(" #n ")" ::: "memory")
; #define BAR __builtin_amdgcn_s_barrier()
; #define SCHED __builtin_amdgcn_sched_barrier(0)
; template <int EPI>
; __device__ __forceinline__ void gemm_tile(const bf16* __restrict__ A, int lda, const bf16* __restrict__ Bt, int K,
;                                           int brow, int bcol, const EpiArgs& ea, char* shmc, bool has_next, int nbrow, int nbcol, bool first_tile) {
;     ...
;     BAR; WAIT_L(0); MMA(1, 0, At, B0); BAR; SCHED;
;     STB(1, 1, 1, t + 3);
;     WAIT_V(6); BAR; MMA(1, 1, At, B1); BAR;
;   }
;   { LDB(B0, 0, 0); LDA(At, 0, 0); STA(1, 1, 1, nt - 1);
;     BAR; WAIT_L(0); MMA(0, 0, At, B0); BAR;
;     LDB(B1, 0, 1); BAR; WAIT_L(0); MMA(0, 1, At, B1); BAR;
	s_waitcnt lgkmcnt(0)
	s_setprio 1
	v_mfma_f32_16x16x32_bf16 v[60:63], v[136:139], v[174:177], v[60:63]
	v_mfma_f32_16x16x32_bf16 v[56:59], v[166:169], v[174:177], v[56:59]
	v_mfma_f32_16x16x32_bf16 v[52:55], v[136:139], v[182:185], v[52:55]
	v_mfma_f32_16x16x32_bf16 v[48:51], v[166:169], v[182:185], v[48:51]
	v_mfma_f32_16x16x32_bf16 v[44:47], v[136:139], v[190:193], v[44:47]
	v_mfma_f32_16x16x32_bf16 v[40:43], v[166:169], v[190:193], v[40:43]
	v_mfma_f32_16x16x32_bf16 v[36:39], v[136:139], v[198:201], v[36:39]
	v_mfma_f32_16x16x32_bf16 v[32:35], v[166:169], v[198:201], v[32:35]
	v_mfma_f32_16x16x32_bf16 v[60:63], v[162:165], v[178:181], v[60:63]
	v_mfma_f32_16x16x32_bf16 v[56:59], v[170:173], v[178:181], v[56:59]
	v_mfma_f32_16x16x32_bf16 v[52:55], v[162:165], v[186:189], v[52:55]
	v_mfma_f32_16x16x32_bf16 v[48:51], v[170:173], v[186:189], v[48:51]
	v_mfma_f32_16x16x32_bf16 v[44:47], v[162:165], v[194:197], v[44:47]
	v_mfma_f32_16x16x32_bf16 v[40:43], v[170:173], v[194:197], v[40:43]
	v_mfma_f32_16x16x32_bf16 v[36:39], v[162:165], v[202:205], v[36:39]
	v_mfma_f32_16x16x32_bf16 v[32:35], v[170:173], v[202:205], v[32:35]
	s_setprio 0
	s_barrier
	s_mov_b32 m0, s25
	v_lshl_add_u64 v[136:137], v[134:135], 0, s[18:19]
	global_load_lds_dwordx4 v[136:137], off
	s_mov_b32 m0, s26
	v_lshl_add_u64 v[136:137], v[136:137], 0, s[4:5]
	global_load_lds_dwordx4 v[136:137], off
	s_waitcnt vmcnt(6)
	s_barrier
	s_setprio 1
	v_mfma_f32_16x16x32_bf16 v[28:31], v[206:209], v[174:177], v[28:31]
	v_mfma_f32_16x16x32_bf16 v[24:27], v[214:217], v[174:177], v[24:27]
	v_mfma_f32_16x16x32_bf16 v[20:23], v[206:209], v[182:185], v[20:23]
	v_mfma_f32_16x16x32_bf16 v[16:19], v[214:217], v[182:185], v[16:19]
	v_mfma_f32_16x16x32_bf16 v[12:15], v[206:209], v[190:193], v[12:15]
	v_mfma_f32_16x16x32_bf16 v[8:11], v[214:217], v[190:193], v[8:11]
	v_mfma_f32_16x16x32_bf16 v[4:7], v[206:209], v[198:201], v[4:7]
	v_mfma_f32_16x16x32_bf16 v[0:3], v[214:217], v[198:201], v[0:3]
	v_mfma_f32_16x16x32_bf16 v[28:31], v[210:213], v[178:181], v[28:31]
	v_mfma_f32_16x16x32_bf16 v[24:27], v[218:221], v[178:181], v[24:27]
	v_mfma_f32_16x16x32_bf16 v[20:23], v[210:213], v[186:189], v[20:23]
	v_mfma_f32_16x16x32_bf16 v[16:19], v[218:221], v[186:189], v[16:19]
	v_mfma_f32_16x16x32_bf16 v[12:15], v[210:213], v[194:197], v[12:15]
	v_mfma_f32_16x16x32_bf16 v[8:11], v[218:221], v[194:197], v[8:11]
	v_mfma_f32_16x16x32_bf16 v[4:7], v[210:213], v[202:205], v[4:7]
	v_mfma_f32_16x16x32_bf16 v[0:3], v[218:221], v[202:205], v[0:3]
	s_setprio 0
	s_add_i32 s31, s31, 2
	s_add_u32 s18, s18, 0x100
	s_addc_u32 s19, s19, 0
	s_cmpk_lt_u32 s31, 0xfc
	s_barrier
	s_cbranch_scc1 .LBB0_784
	s_mov_b64 s[18:19], 0x407f80
	s_mov_b32 m0, s34
	ds_read_b128 v[134:137], v141
	ds_read_b128 v[162:165], v142
	ds_read_b128 v[166:169], v143
	ds_read_b128 v[170:173], v144
	ds_read_b128 v[174:177], v160
	ds_read_b128 v[178:181], v160 offset:1024
	ds_read_b128 v[182:185], v160 offset:2048
	ds_read_b128 v[186:189], v160 offset:3072
	ds_read_b128 v[190:193], v160 offset:4096
	ds_read_b128 v[194:197], v160 offset:5120
	ds_read_b128 v[198:201], v160 offset:6144
	ds_read_b128 v[202:205], v160 offset:7168
	s_nop 0
	v_lshl_add_u64 v[132:133], v[132:133], 0, s[18:19]
	global_load_lds_dwordx4 v[132:133], off
	v_lshl_add_u64 v[132:133], v[132:133], 0, s[4:5]
	s_mov_b32 m0, s24
	s_nop 0
	global_load_lds_dwordx4 v[132:133], off
	s_barrier
	s_waitcnt lgkmcnt(0)
	s_setprio 1
	s_waitcnt lgkmcnt(0)
	v_mfma_f32_16x16x32_bf16 v[124:127], v[134:137], v[174:177], v[124:127]
	v_mfma_f32_16x16x32_bf16 v[120:123], v[166:169], v[174:177], v[120:123]
	v_mfma_f32_16x16x32_bf16 v[116:119], v[134:137], v[182:185], v[116:119]
	v_mfma_f32_16x16x32_bf16 v[112:115], v[166:169], v[182:185], v[112:115]
	v_mfma_f32_16x16x32_bf16 v[100:103], v[134:137], v[198:201], v[100:103]
	v_mfma_f32_16x16x32_bf16 v[96:99], v[166:169], v[198:201], v[96:99]
	v_mfma_f32_16x16x32_bf16 v[124:127], v[162:165], v[178:181], v[124:127]
	v_mfma_f32_16x16x32_bf16 v[120:123], v[170:173], v[178:181], v[120:123]
	v_mfma_f32_16x16x32_bf16 v[116:119], v[162:165], v[186:189], v[116:119]
	v_mfma_f32_16x16x32_bf16 v[112:115], v[170:173], v[186:189], v[112:115]
	v_mfma_f32_16x16x32_bf16 v[108:111], v[134:137], v[190:193], v[108:111]
	v_mfma_f32_16x16x32_bf16 v[104:107], v[166:169], v[190:193], v[104:107]
	v_mfma_f32_16x16x32_bf16 v[100:103], v[162:165], v[202:205], v[100:103]
	v_mfma_f32_16x16x32_bf16 v[96:99], v[170:173], v[202:205], v[96:99]
	v_mfma_f32_16x16x32_bf16 v[206:209], v[162:165], v[194:197], v[108:111]
	v_mfma_f32_16x16x32_bf16 v[210:213], v[170:173], v[194:197], v[104:107]
	s_setprio 0
	s_barrier
	s_nop 1
	ds_read_b128 v[104:107], v145
	ds_read_b128 v[108:111], v146
	ds_read_b128 v[214:217], v147
	ds_read_b128 v[218:221], v148
	s_barrier
	s_waitcnt lgkmcnt(0)
	s_setprio 1
	s_waitcnt lgkmcnt(0)
	v_mfma_f32_16x16x32_bf16 v[84:87], v[104:107], v[182:185], v[84:87]
	v_mfma_f32_16x16x32_bf16 v[80:83], v[214:217], v[182:185], v[80:83]
	v_mfma_f32_16x16x32_bf16 v[68:71], v[104:107], v[198:201], v[68:71]
	v_mfma_f32_16x16x32_bf16 v[64:67], v[214:217], v[198:201], v[64:67]
	v_mfma_f32_16x16x32_bf16 v[92:95], v[104:107], v[174:177], v[92:95]
	v_mfma_f32_16x16x32_bf16 v[88:91], v[214:217], v[174:177], v[88:91]
	v_mfma_f32_16x16x32_bf16 v[84:87], v[108:111], v[186:189], v[84:87]
	v_mfma_f32_16x16x32_bf16 v[80:83], v[218:221], v[186:189], v[80:83]
	v_mfma_f32_16x16x32_bf16 v[76:79], v[104:107], v[190:193], v[76:79]
	v_mfma_f32_16x16x32_bf16 v[72:75], v[214:217], v[190:193], v[72:75]
	v_mfma_f32_16x16x32_bf16 v[68:71], v[108:111], v[202:205], v[68:71]
	v_mfma_f32_16x16x32_bf16 v[64:67], v[218:221], v[202:205], v[64:67]
	v_mfma_f32_16x16x32_bf16 v[222:225], v[108:111], v[178:181], v[92:95]
	v_mfma_f32_16x16x32_bf16 v[174:177], v[218:221], v[178:181], v[88:91]
	v_mfma_f32_16x16x32_bf16 v[178:181], v[108:111], v[194:197], v[76:79]
	v_mfma_f32_16x16x32_bf16 v[182:185], v[218:221], v[194:197], v[72:75]
	s_setprio 0
	s_barrier
; #define LDA(dst, b, h) for (int m = 0; m < 4; ++m) for (int k = 0; k < 2; ++k) \
;     dst[m][k] = *reinterpret_cast<const bf16x8*>(aRd + (((b) * 2 + (h)) * G_HT * 2 + m * 2048 + k * 1024))
; #define LDB(dst, b, h) for (int n = 0; n < 2; ++n) for (int k = 0; k < 2; ++k) \
;     dst[n][k] = *reinterpret_cast<const bf16x8*>(bRd + (((b) * 2 + (h)) * G_HT * 2 + n * 2048 + k * 1024))
; #define MMA(ai, bj, At, Bx) do { __builtin_amdgcn_s_setprio(1); \
;     for (int m = 0; m < 4; ++m) for (int n = 0; n < 2; ++n) for (int k = 0; k < 2; ++k) \
;       acc[ai][bj][m][n] = __builtin_amdgcn_mfma_f32_16x16x32_bf16(Bx[n][k], At[m][k], acc[ai][bj][m][n], 0, 0, 0);     \
;     __builtin_amdgcn_s_setprio(0); } while (0)
; #define WAIT_V(n) asm volatile("s_waitcnt vmcnt(" #n ")" ::: "memory")
; #define WAIT_L(n) asm volatile("s_waitcnt lgkmcnt(" #n ")" ::: "memory")
; #define BAR __builtin_amdgcn_s_barrier()
; template <int EPI>
; __device__ __forceinline__ void gemm_tile(const bf16* __restrict__ A, int lda, const bf16* __restrict__ Bt, int K,
;                                           int brow, int bcol, const EpiArgs& ea, char* shmc, bool has_next, int nbrow, int nbcol, bool first_tile) {
;     ...
;     LDA(At, 0, 1); WAIT_V(4); BAR; WAIT_L(0); MMA(1, 0, At, B0); MMA(1, 1, At, B1); BAR; }
;   { LDB(B0, 1, 0); LDA(At, 1, 0); WAIT_V(2); BAR; WAIT_L(0); MMA(0, 0, At, B0); BAR;
	s_nop 0
	ds_read_b128 v[72:75], v160 offset:16384
	ds_read_b128 v[76:79], v160 offset:17408
	ds_read_b128 v[88:91], v160 offset:18432
	ds_read_b128 v[92:95], v160 offset:19456
	ds_read_b128 v[186:189], v160 offset:20480
	ds_read_b128 v[190:193], v160 offset:21504
	ds_read_b128 v[194:197], v160 offset:22528
	ds_read_b128 v[198:201], v160 offset:23552
	s_waitcnt vmcnt(4)
	s_barrier
	s_waitcnt lgkmcnt(0)
	s_setprio 1
	s_waitcnt lgkmcnt(0)
	v_mfma_f32_16x16x32_bf16 v[60:63], v[134:137], v[72:75], v[60:63]
	v_mfma_f32_16x16x32_bf16 v[56:59], v[166:169], v[72:75], v[56:59]
	v_mfma_f32_16x16x32_bf16 v[52:55], v[134:137], v[88:91], v[52:55]
	v_mfma_f32_16x16x32_bf16 v[48:51], v[166:169], v[88:91], v[48:51]
	v_mfma_f32_16x16x32_bf16 v[36:39], v[134:137], v[194:197], v[36:39]
	v_mfma_f32_16x16x32_bf16 v[32:35], v[166:169], v[194:197], v[32:35]
	v_mfma_f32_16x16x32_bf16 v[60:63], v[162:165], v[76:79], v[60:63]
	v_mfma_f32_16x16x32_bf16 v[56:59], v[170:173], v[76:79], v[56:59]
	v_mfma_f32_16x16x32_bf16 v[52:55], v[162:165], v[92:95], v[52:55]
	v_mfma_f32_16x16x32_bf16 v[48:51], v[170:173], v[92:95], v[48:51]
	v_mfma_f32_16x16x32_bf16 v[44:47], v[134:137], v[186:189], v[44:47]
	v_mfma_f32_16x16x32_bf16 v[40:43], v[166:169], v[186:189], v[40:43]
	v_mfma_f32_16x16x32_bf16 v[36:39], v[162:165], v[198:201], v[36:39]
	v_mfma_f32_16x16x32_bf16 v[32:35], v[170:173], v[198:201], v[32:35]
	v_mfma_f32_16x16x32_bf16 v[202:205], v[162:165], v[190:193], v[44:47]
	v_mfma_f32_16x16x32_bf16 v[226:229], v[170:173], v[190:193], v[40:43]
	s_setprio 0
	s_setprio 1
	v_mfma_f32_16x16x32_bf16 v[20:23], v[104:107], v[88:91], v[20:23]
	v_mfma_f32_16x16x32_bf16 v[16:19], v[214:217], v[88:91], v[16:19]
	v_mfma_f32_16x16x32_bf16 v[4:7], v[104:107], v[194:197], v[4:7]
	v_mfma_f32_16x16x32_bf16 v[0:3], v[214:217], v[194:197], v[0:3]
	v_mfma_f32_16x16x32_bf16 v[28:31], v[104:107], v[72:75], v[28:31]
	v_mfma_f32_16x16x32_bf16 v[24:27], v[214:217], v[72:75], v[24:27]
	v_mfma_f32_16x16x32_bf16 v[20:23], v[108:111], v[92:95], v[20:23]
	v_mfma_f32_16x16x32_bf16 v[16:19], v[218:221], v[92:95], v[16:19]
	v_mfma_f32_16x16x32_bf16 v[12:15], v[104:107], v[186:189], v[12:15]
	v_mfma_f32_16x16x32_bf16 v[8:11], v[214:217], v[186:189], v[8:11]
	v_mfma_f32_16x16x32_bf16 v[4:7], v[108:111], v[198:201], v[4:7]
	v_mfma_f32_16x16x32_bf16 v[0:3], v[218:221], v[198:201], v[0:3]
	v_mfma_f32_16x16x32_bf16 v[132:135], v[108:111], v[76:79], v[28:31]
	v_mfma_f32_16x16x32_bf16 v[136:139], v[218:221], v[76:79], v[24:27]
	v_mfma_f32_16x16x32_bf16 v[162:165], v[108:111], v[190:193], v[12:15]
	v_mfma_f32_16x16x32_bf16 v[166:169], v[218:221], v[190:193], v[8:11]
	s_setprio 0
	s_barrier
	s_nop 0
	ds_read_b128 v[8:11], v149
	ds_read_b128 v[12:15], v150
	ds_read_b128 v[170:173], v151
	ds_read_b128 v[186:189], v152
	ds_read_b128 v[24:27], v160 offset:32768
	ds_read_b128 v[28:31], v160 offset:33792
	ds_read_b128 v[40:43], v160 offset:34816
	ds_read_b128 v[44:47], v160 offset:35840
	ds_read_b128 v[190:193], v160 offset:36864
	ds_read_b128 v[194:197], v160 offset:37888
	ds_read_b128 v[198:201], v160 offset:38912
	ds_read_b128 v[214:217], v160 offset:39936
	s_waitcnt vmcnt(2)
	s_barrier
	s_waitcnt lgkmcnt(0)
	s_setprio 1
	s_waitcnt lgkmcnt(0)
	v_mfma_f32_16x16x32_bf16 v[72:75], v[8:11], v[24:27], v[124:127]
	v_mfma_f32_16x16x32_bf16 v[124:127], v[12:15], v[28:31], v[72:75]
	v_mfma_f32_16x16x32_bf16 v[72:75], v[170:173], v[24:27], v[120:123]
	v_mfma_f32_16x16x32_bf16 v[120:123], v[186:189], v[28:31], v[72:75]
	v_mfma_f32_16x16x32_bf16 v[72:75], v[8:11], v[40:43], v[116:119]
	v_mfma_f32_16x16x32_bf16 v[108:111], v[12:15], v[44:47], v[72:75]
	v_mfma_f32_16x16x32_bf16 v[72:75], v[170:173], v[40:43], v[112:115]
	v_mfma_f32_16x16x32_bf16 v[104:107], v[186:189], v[44:47], v[72:75]
	v_mfma_f32_16x16x32_bf16 v[72:75], v[8:11], v[190:193], v[206:209]
	v_mfma_f32_16x16x32_bf16 v[92:95], v[12:15], v[194:197], v[72:75]
	v_mfma_f32_16x16x32_bf16 v[72:75], v[170:173], v[190:193], v[210:213]
	v_mfma_f32_16x16x32_bf16 v[88:91], v[186:189], v[194:197], v[72:75]
	v_mfma_f32_16x16x32_bf16 v[72:75], v[8:11], v[198:201], v[100:103]
	v_mfma_f32_16x16x32_bf16 v[76:79], v[12:15], v[214:217], v[72:75]
	v_mfma_f32_16x16x32_bf16 v[72:75], v[170:173], v[198:201], v[96:99]
	v_mfma_f32_16x16x32_bf16 v[72:75], v[186:189], v[214:217], v[72:75]
	s_setprio 0
	s_barrier
; #define LDA(dst, b, h) for (int m = 0; m < 4; ++m) for (int k = 0; k < 2; ++k) \
;     dst[m][k] = *reinterpret_cast<const bf16x8*>(aRd + (((b) * 2 + (h)) * G_HT * 2 + m * 2048 + k * 1024))
; #define LDB(dst, b, h) for (int n = 0; n < 2; ++n) for (int k = 0; k < 2; ++k) \
;     dst[n][k] = *reinterpret_cast<const bf16x8*>(bRd + (((b) * 2 + (h)) * G_HT * 2 + n * 2048 + k * 1024))
; #define MMA(ai, bj, At, Bx) do { __builtin_amdgcn_s_setprio(1); \
;     for (int m = 0; m < 4; ++m) for (int n = 0; n < 2; ++n) for (int k = 0; k < 2; ++k) \
;       acc[ai][bj][m][n] = __builtin_amdgcn_mfma_f32_16x16x32_bf16(Bx[n][k], At[m][k], acc[ai][bj][m][n], 0, 0, 0);     \
;     __builtin_amdgcn_s_setprio(0); } while (0)
; #define WAIT_V(n) asm volatile("s_waitcnt vmcnt(" #n ")" ::: "memory")
; #define WAIT_L(n) asm volatile("s_waitcnt lgkmcnt(" #n ")" ::: "memory")
; #define BAR __builtin_amdgcn_s_barrier()
; template <int EPI>
; __device__ __forceinline__ void gemm_tile(const bf16* __restrict__ A, int lda, const bf16* __restrict__ Bt, int K,
;                                           int brow, int bcol, const EpiArgs& ea, char* shmc, bool has_next, int nbrow, int nbcol, bool first_tile) {
;     ...
;     LDB(B1, 1, 1); WAIT_V(0); BAR; WAIT_L(0); MMA(0, 1, At, B1); BAR;
;     LDA(At, 1, 1); BAR; WAIT_L(0); MMA(1, 0, At, B0); MMA(1, 1, At, B1); BAR; }
;   if (wr == 0) BAR;
	ds_read_b128 v[206:209], v153
	ds_read_b128 v[210:213], v154
	ds_read_b128 v[218:221], v155
	ds_read_b128 v[230:233], v156
	s_waitcnt vmcnt(0)
	s_barrier
	s_waitcnt lgkmcnt(0)
	s_setprio 1
	s_waitcnt lgkmcnt(0)
	v_mfma_f32_16x16x32_bf16 v[96:99], v[206:209], v[24:27], v[222:225]
	v_mfma_f32_16x16x32_bf16 v[24:27], v[218:221], v[24:27], v[174:177]
	v_mfma_f32_16x16x32_bf16 v[112:115], v[230:233], v[28:31], v[24:27]
	v_mfma_f32_16x16x32_bf16 v[24:27], v[206:209], v[40:43], v[84:87]
	v_mfma_f32_16x16x32_bf16 v[100:103], v[210:213], v[44:47], v[24:27]
	v_mfma_f32_16x16x32_bf16 v[24:27], v[218:221], v[40:43], v[80:83]
	v_mfma_f32_16x16x32_bf16 v[116:119], v[210:213], v[28:31], v[96:99]
	v_mfma_f32_16x16x32_bf16 v[96:99], v[230:233], v[44:47], v[24:27]
	v_mfma_f32_16x16x32_bf16 v[24:27], v[206:209], v[190:193], v[178:181]
	v_mfma_f32_16x16x32_bf16 v[84:87], v[210:213], v[194:197], v[24:27]
	v_mfma_f32_16x16x32_bf16 v[24:27], v[218:221], v[190:193], v[182:185]
	v_mfma_f32_16x16x32_bf16 v[80:83], v[230:233], v[194:197], v[24:27]
	v_mfma_f32_16x16x32_bf16 v[24:27], v[206:209], v[198:201], v[68:71]
	v_mfma_f32_16x16x32_bf16 v[68:71], v[210:213], v[214:217], v[24:27]
	v_mfma_f32_16x16x32_bf16 v[24:27], v[218:221], v[198:201], v[64:67]
	v_mfma_f32_16x16x32_bf16 v[64:67], v[230:233], v[214:217], v[24:27]
	s_setprio 0
	s_barrier
	ds_read_b128 v[174:177], v160 offset:49152
	ds_read_b128 v[178:181], v160 offset:50176
	ds_read_b128 v[182:185], v160 offset:51200
	ds_read_b128 v[190:193], v160 offset:52224
	ds_read_b128 v[194:197], v160 offset:53248
	ds_read_b128 v[198:201], v160 offset:54272
	ds_read_b128 v[214:217], v160 offset:55296
	ds_read_b128 v[222:225], v160 offset:56320
	s_barrier
	s_waitcnt lgkmcnt(0)
	s_setprio 1
	s_waitcnt lgkmcnt(0)
	v_mfma_f32_16x16x32_bf16 v[24:27], v[8:11], v[174:177], v[60:63]
	v_mfma_f32_16x16x32_bf16 v[60:63], v[12:15], v[178:181], v[24:27]
	v_mfma_f32_16x16x32_bf16 v[24:27], v[170:173], v[174:177], v[56:59]
	v_mfma_f32_16x16x32_bf16 v[56:59], v[186:189], v[178:181], v[24:27]
	v_mfma_f32_16x16x32_bf16 v[24:27], v[8:11], v[182:185], v[52:55]
	v_mfma_f32_16x16x32_bf16 v[44:47], v[12:15], v[190:193], v[24:27]
	v_mfma_f32_16x16x32_bf16 v[24:27], v[170:173], v[182:185], v[48:51]
	v_mfma_f32_16x16x32_bf16 v[40:43], v[186:189], v[190:193], v[24:27]
	v_mfma_f32_16x16x32_bf16 v[24:27], v[8:11], v[194:197], v[202:205]
	v_mfma_f32_16x16x32_bf16 v[8:11], v[8:11], v[214:217], v[36:39]
	v_mfma_f32_16x16x32_bf16 v[28:31], v[12:15], v[198:201], v[24:27]
	v_mfma_f32_16x16x32_bf16 v[24:27], v[170:173], v[194:197], v[226:229]
	v_mfma_f32_16x16x32_bf16 v[12:15], v[12:15], v[222:225], v[8:11]
	v_mfma_f32_16x16x32_bf16 v[8:11], v[170:173], v[214:217], v[32:35]
	v_mfma_f32_16x16x32_bf16 v[24:27], v[186:189], v[198:201], v[24:27]
	v_mfma_f32_16x16x32_bf16 v[8:11], v[186:189], v[222:225], v[8:11]
	s_setprio 0
	s_setprio 1
	v_mfma_f32_16x16x32_bf16 v[32:35], v[206:209], v[174:177], v[132:135]
	v_mfma_f32_16x16x32_bf16 v[52:55], v[210:213], v[178:181], v[32:35]
	v_mfma_f32_16x16x32_bf16 v[32:35], v[218:221], v[174:177], v[136:139]
	v_mfma_f32_16x16x32_bf16 v[16:19], v[218:221], v[182:185], v[16:19]
	v_mfma_f32_16x16x32_bf16 v[48:51], v[230:233], v[178:181], v[32:35]
	v_mfma_f32_16x16x32_bf16 v[20:23], v[206:209], v[182:185], v[20:23]
	v_mfma_f32_16x16x32_bf16 v[32:35], v[230:233], v[190:193], v[16:19]
	v_mfma_f32_16x16x32_bf16 v[16:19], v[206:209], v[194:197], v[162:165]
	v_mfma_f32_16x16x32_bf16 v[36:39], v[210:213], v[190:193], v[20:23]
	v_mfma_f32_16x16x32_bf16 v[20:23], v[210:213], v[198:201], v[16:19]
	v_mfma_f32_16x16x32_bf16 v[16:19], v[218:221], v[194:197], v[166:169]
	v_mfma_f32_16x16x32_bf16 v[4:7], v[206:209], v[214:217], v[4:7]
	v_mfma_f32_16x16x32_bf16 v[0:3], v[218:221], v[214:217], v[0:3]
	v_mfma_f32_16x16x32_bf16 v[16:19], v[230:233], v[198:201], v[16:19]
	v_mfma_f32_16x16x32_bf16 v[4:7], v[210:213], v[222:225], v[4:7]
	v_mfma_f32_16x16x32_bf16 v[0:3], v[230:233], v[222:225], v[0:3]
	s_setprio 0
	s_barrier
	s_and_saveexec_b64 s[18:19], s[2:3]
	s_cbranch_execz .LBB0_787
	s_barrier
